# GEMM loops: 72 LDS-DMA loads take their +128B source step as offset:128 with M0 lowered by 128 instead of a 64-bit VALU add per load
# baseline (speedup 1.0000x reference)
.LBB0_432:
	s_add_i32 m0, s17, 0x17f80
	v_lshl_add_u64 v[20:21], v[2:3], 0, v[132:133]
	s_waitcnt vmcnt(4)
	s_barrier
	global_load_lds_dwordx4 v[4:5], off offset:128
	s_add_i32 m0, s17, 0x19f80
	s_add_i32 s29, s17, 0x8000
	v_lshl_add_u64 v[22:23], v[2:3], 0, v[130:131]
	global_load_lds_dwordx4 v[6:7], off offset:128
	s_add_i32 m0, s29, 0xffffff80
	s_add_i32 s35, s17, 0xa000
	global_load_lds_dwordx4 v[20:21], off offset:128
	s_add_i32 m0, s35, 0xffffff80
	s_lshl_b32 s0, s0, 5
	global_load_lds_dwordx4 v[22:23], off offset:128
	s_add_i32 m0, s17, 0x1bf80
	global_load_lds_dwordx4 v[8:9], off offset:128
	s_add_i32 m0, s17, 0x1df80
	s_and_b32 s0, s0, 0x60
	global_load_lds_dwordx4 v[10:11], off offset:128
	v_bfe_u32 v4, v12, 4, 2
	v_and_b32_e32 v5, 15, v12
	v_lshlrev_b32_e32 v6, 4, v4
	v_lshl_or_b32 v1, s1, 6, v5
	v_lshl_or_b32 v5, v5, 6, v6
	v_lshlrev_b32_e32 v6, 2, v12
	s_lshl_b32 s1, s1, 13
	v_and_b32_e32 v6, 32, v6
	v_bitop3_b32 v8, v5, s1, v6 bitop3:0xde
	s_lshl_b32 s1, s0, 7
	v_bitop3_b32 v144, v5, s1, v6 bitop3:0xde
	v_add_u32_e32 v5, v16, v17
	s_waitcnt vmcnt(6)
	v_add_lshl_u32 v6, v5, v18, 1
	v_mov_b32_e32 v7, v0
	v_add_u32_e32 v5, v13, v14
	v_lshl_or_b32 v4, v4, 2, s0
	v_lshl_add_u64 v[134:135], s[94:95], 0, v[6:7]
	v_add_lshl_u32 v6, v5, v15, 1
	s_add_i32 s36, s13, -2
	s_ashr_i32 s42, s37, 31
	s_mov_b32 s25, s95
	v_lshl_add_u64 v[136:137], s[94:95], 0, v[6:7]
	s_mov_b32 s43, 0
	v_add_u32_e32 v145, 0, v8
	v_lshlrev_b32_e32 v138, 1, v4
	s_barrier
	s_waitcnt vmcnt(0)

.LBB0_440:
	s_add_i32 s40, s4, 2
	s_add_i32 s41, 0, 0x10000
	s_cmp_eq_u32 s36, s4
	v_lshl_add_u64 v[146:147], v[142:143], 0, s[84:85]
	s_cselect_b64 vcc, -1, 0
	v_add_u32_e32 v139, s41, v144
	v_cndmask_b32_e32 v213, v147, v141, vcc
	v_cndmask_b32_e32 v212, v146, v140, vcc
	ds_read_b128 v[146:149], v139
	ds_read_b128 v[150:153], v139 offset:1024
	ds_read_b128 v[154:157], v139 offset:2048
	ds_read_b128 v[160:163], v139 offset:3072
	s_cselect_b32 s4, s0, s6
	s_cselect_b32 s5, s1, s7
	v_lshl_add_u64 v[196:197], v[142:143], 0, v[134:135]
	s_add_i32 m0, s17, 0xc000
	ds_read_b128 v[164:167], v145
	ds_read_b128 v[168:171], v145 offset:1024
	ds_read_b128 v[172:175], v145 offset:2048
	ds_read_b128 v[176:179], v145 offset:3072
	ds_read_b128 v[180:183], v145 offset:4096
	ds_read_b128 v[184:187], v145 offset:5120
	ds_read_b128 v[188:191], v145 offset:6144
	ds_read_b128 v[192:195], v145 offset:7168
	global_load_lds_dwordx4 v[196:197], off
	v_lshl_add_u64 v[196:197], v[142:143], 0, v[136:137]
	s_add_i32 m0, s17, 0xe000
	s_nop 0
	global_load_lds_dwordx4 v[196:197], off
	s_waitcnt lgkmcnt(8)
	s_barrier
	s_waitcnt lgkmcnt(0)
	s_waitcnt lgkmcnt(0)
	v_mfma_f32_16x16x32_bf16 v[126:129], v[146:149], v[164:167], v[126:129]
	v_mfma_f32_16x16x32_bf16 v[122:125], v[154:157], v[164:167], v[122:125]
	v_mfma_f32_16x16x32_bf16 v[118:121], v[146:149], v[172:175], v[118:121]
	v_mfma_f32_16x16x32_bf16 v[110:113], v[154:157], v[172:175], v[110:113]
	v_mfma_f32_16x16x32_bf16 v[102:105], v[146:149], v[180:183], v[102:105]
	v_mfma_f32_16x16x32_bf16 v[94:97], v[154:157], v[180:183], v[94:97]
	v_mfma_f32_16x16x32_bf16 v[86:89], v[146:149], v[188:191], v[86:89]
	v_mfma_f32_16x16x32_bf16 v[78:81], v[154:157], v[188:191], v[78:81]
	v_mfma_f32_16x16x32_bf16 v[126:129], v[150:153], v[168:171], v[126:129]
	v_mfma_f32_16x16x32_bf16 v[122:125], v[160:163], v[168:171], v[122:125]
	v_mfma_f32_16x16x32_bf16 v[118:121], v[150:153], v[176:179], v[118:121]
	v_mfma_f32_16x16x32_bf16 v[110:113], v[160:163], v[176:179], v[110:113]
	v_mfma_f32_16x16x32_bf16 v[102:105], v[150:153], v[184:187], v[102:105]
	v_mfma_f32_16x16x32_bf16 v[94:97], v[160:163], v[184:187], v[94:97]
	v_mfma_f32_16x16x32_bf16 v[86:89], v[150:153], v[192:195], v[86:89]
	v_mfma_f32_16x16x32_bf16 v[78:81], v[160:163], v[192:195], v[78:81]
	s_barrier
	s_add_i32 s89, 0, 0x14000
	s_add_i32 s41, s41, s3
	v_add_u32_e32 v139, s89, v144
	v_lshl_add_u64 v[214:215], s[4:5], 0, v[132:133]
	s_mov_b32 m0, s41
	ds_read_b128 v[196:199], v139
	ds_read_b128 v[200:203], v139 offset:1024
	ds_read_b128 v[204:207], v139 offset:2048
	ds_read_b128 v[208:211], v139 offset:3072
	global_load_lds_dwordx4 v[214:215], off
	v_lshl_add_u64 v[216:217], s[4:5], 0, v[130:131]
	s_add_i32 m0, s41, 0x2000
	s_nop 0
	global_load_lds_dwordx4 v[216:217], off
	s_barrier
	s_waitcnt lgkmcnt(0)
	s_waitcnt lgkmcnt(0)
	v_mfma_f32_16x16x32_bf16 v[114:117], v[196:199], v[164:167], v[114:117]
	v_mfma_f32_16x16x32_bf16 v[106:109], v[204:207], v[164:167], v[106:109]
	v_mfma_f32_16x16x32_bf16 v[98:101], v[196:199], v[172:175], v[98:101]
	v_mfma_f32_16x16x32_bf16 v[90:93], v[204:207], v[172:175], v[90:93]
	v_mfma_f32_16x16x32_bf16 v[82:85], v[196:199], v[180:183], v[82:85]
	v_mfma_f32_16x16x32_bf16 v[74:77], v[204:207], v[180:183], v[74:77]
	v_mfma_f32_16x16x32_bf16 v[70:73], v[196:199], v[188:191], v[70:73]
	v_mfma_f32_16x16x32_bf16 v[66:69], v[204:207], v[188:191], v[66:69]
	v_mfma_f32_16x16x32_bf16 v[114:117], v[200:203], v[168:171], v[114:117]
	v_mfma_f32_16x16x32_bf16 v[106:109], v[208:211], v[168:171], v[106:109]
	v_mfma_f32_16x16x32_bf16 v[98:101], v[200:203], v[176:179], v[98:101]
	v_mfma_f32_16x16x32_bf16 v[90:93], v[208:211], v[176:179], v[90:93]
	v_mfma_f32_16x16x32_bf16 v[82:85], v[200:203], v[184:187], v[82:85]
	v_mfma_f32_16x16x32_bf16 v[74:77], v[208:211], v[184:187], v[74:77]
	v_mfma_f32_16x16x32_bf16 v[70:73], v[200:203], v[192:195], v[70:73]
	v_mfma_f32_16x16x32_bf16 v[66:69], v[208:211], v[192:195], v[66:69]
	s_mov_b32 m0, s17
	v_lshl_add_u64 v[218:219], v[212:213], 0, v[132:133]
	s_barrier
	ds_read_b128 v[164:167], v145 offset:16384
	ds_read_b128 v[168:171], v145 offset:17408
	ds_read_b128 v[172:175], v145 offset:18432
	ds_read_b128 v[176:179], v145 offset:19456
	ds_read_b128 v[180:183], v145 offset:20480
	ds_read_b128 v[184:187], v145 offset:21504
	ds_read_b128 v[188:191], v145 offset:22528
	ds_read_b128 v[192:195], v145 offset:23552
	global_load_lds_dwordx4 v[218:219], off
	v_lshl_add_u64 v[224:225], v[212:213], 0, v[130:131]
	s_mov_b32 m0, s22
	s_nop 0
	global_load_lds_dwordx4 v[224:225], off
	s_barrier
	s_waitcnt lgkmcnt(0)
	s_waitcnt lgkmcnt(0)
	v_mfma_f32_16x16x32_bf16 v[62:65], v[146:149], v[164:167], v[62:65]
	v_mfma_f32_16x16x32_bf16 v[58:61], v[154:157], v[164:167], v[58:61]
	v_mfma_f32_16x16x32_bf16 v[54:57], v[146:149], v[172:175], v[54:57]
	v_mfma_f32_16x16x32_bf16 v[46:49], v[154:157], v[172:175], v[46:49]
	v_mfma_f32_16x16x32_bf16 v[38:41], v[146:149], v[180:183], v[38:41]
	v_mfma_f32_16x16x32_bf16 v[30:33], v[154:157], v[180:183], v[30:33]
	v_mfma_f32_16x16x32_bf16 v[22:25], v[146:149], v[188:191], v[22:25]
	v_mfma_f32_16x16x32_bf16 v[14:17], v[154:157], v[188:191], v[14:17]
	v_mfma_f32_16x16x32_bf16 v[62:65], v[150:153], v[168:171], v[62:65]
	v_mfma_f32_16x16x32_bf16 v[58:61], v[160:163], v[168:171], v[58:61]
	v_mfma_f32_16x16x32_bf16 v[54:57], v[150:153], v[176:179], v[54:57]
	v_mfma_f32_16x16x32_bf16 v[46:49], v[160:163], v[176:179], v[46:49]
	v_mfma_f32_16x16x32_bf16 v[38:41], v[150:153], v[184:187], v[38:41]
	v_mfma_f32_16x16x32_bf16 v[30:33], v[160:163], v[184:187], v[30:33]
	v_mfma_f32_16x16x32_bf16 v[22:25], v[150:153], v[192:195], v[22:25]
	v_mfma_f32_16x16x32_bf16 v[14:17], v[160:163], v[192:195], v[14:17]
	s_barrier
	s_add_u32 s4, s4, s94
	s_addc_u32 s5, s5, 0
	s_add_i32 s41, s89, s3
	v_lshl_add_u64 v[230:231], s[4:5], 0, v[132:133]
	s_mov_b32 m0, s41
	v_lshl_add_u64 v[232:233], s[4:5], 0, v[130:131]
	global_load_lds_dwordx4 v[230:231], off
	s_add_i32 m0, s41, 0x2000
	s_nop 0
	global_load_lds_dwordx4 v[232:233], off
	s_waitcnt vmcnt(6)
	s_barrier
	v_mfma_f32_16x16x32_bf16 v[50:53], v[196:199], v[164:167], v[50:53]
	v_mfma_f32_16x16x32_bf16 v[42:45], v[204:207], v[164:167], v[42:45]
	v_mfma_f32_16x16x32_bf16 v[34:37], v[196:199], v[172:175], v[34:37]
	v_mfma_f32_16x16x32_bf16 v[26:29], v[204:207], v[172:175], v[26:29]
	v_mfma_f32_16x16x32_bf16 v[18:21], v[196:199], v[180:183], v[18:21]
	v_mfma_f32_16x16x32_bf16 v[10:13], v[204:207], v[180:183], v[10:13]
	v_mfma_f32_16x16x32_bf16 v[6:9], v[196:199], v[188:191], v[6:9]
	v_mfma_f32_16x16x32_bf16 v[2:5], v[204:207], v[188:191], v[2:5]
	v_mfma_f32_16x16x32_bf16 v[50:53], v[200:203], v[168:171], v[50:53]
	v_mfma_f32_16x16x32_bf16 v[42:45], v[208:211], v[168:171], v[42:45]
	v_mfma_f32_16x16x32_bf16 v[34:37], v[200:203], v[176:179], v[34:37]
	v_mfma_f32_16x16x32_bf16 v[26:29], v[208:211], v[176:179], v[26:29]
	v_mfma_f32_16x16x32_bf16 v[18:21], v[200:203], v[184:187], v[18:21]
	v_mfma_f32_16x16x32_bf16 v[10:13], v[208:211], v[184:187], v[10:13]
	v_mfma_f32_16x16x32_bf16 v[6:9], v[200:203], v[192:195], v[6:9]
	v_mfma_f32_16x16x32_bf16 v[2:5], v[208:211], v[192:195], v[2:5]
	s_add_i32 s4, 0, 0x18000
	v_add_u32_e32 v139, s4, v144
	s_barrier
	ds_read_b128 v[146:149], v139
	ds_read_b128 v[150:153], v139 offset:1024
	ds_read_b128 v[154:157], v139 offset:2048
	ds_read_b128 v[160:163], v139 offset:3072
	v_lshl_add_u64 v[196:197], v[212:213], 0, s[94:95]
	s_mov_b32 m0, s23
	v_lshl_add_u64 v[198:199], v[196:197], 0, v[132:133]
	ds_read_b128 v[164:167], v145 offset:32768
	ds_read_b128 v[168:171], v145 offset:33792
	ds_read_b128 v[172:175], v145 offset:34816
	ds_read_b128 v[176:179], v145 offset:35840
	ds_read_b128 v[180:183], v145 offset:36864
	ds_read_b128 v[184:187], v145 offset:37888
	ds_read_b128 v[188:191], v145 offset:38912
	ds_read_b128 v[192:195], v145 offset:39936
	global_load_lds_dwordx4 v[198:199], off
	v_lshl_add_u64 v[196:197], v[196:197], 0, v[130:131]
	s_mov_b32 m0, s28
	s_nop 0
	global_load_lds_dwordx4 v[196:197], off
	s_waitcnt lgkmcnt(8)
	s_barrier
	s_waitcnt lgkmcnt(0)
	s_waitcnt lgkmcnt(0)
	v_mfma_f32_16x16x32_bf16 v[126:129], v[146:149], v[164:167], v[126:129]
	v_mfma_f32_16x16x32_bf16 v[122:125], v[154:157], v[164:167], v[122:125]
	v_mfma_f32_16x16x32_bf16 v[118:121], v[146:149], v[172:175], v[118:121]
	v_mfma_f32_16x16x32_bf16 v[110:113], v[154:157], v[172:175], v[110:113]
	v_mfma_f32_16x16x32_bf16 v[102:105], v[146:149], v[180:183], v[102:105]
	v_mfma_f32_16x16x32_bf16 v[94:97], v[154:157], v[180:183], v[94:97]
	v_mfma_f32_16x16x32_bf16 v[86:89], v[146:149], v[188:191], v[86:89]
	v_mfma_f32_16x16x32_bf16 v[78:81], v[154:157], v[188:191], v[78:81]
	v_mfma_f32_16x16x32_bf16 v[126:129], v[150:153], v[168:171], v[126:129]
	v_mfma_f32_16x16x32_bf16 v[122:125], v[160:163], v[168:171], v[122:125]
	v_mfma_f32_16x16x32_bf16 v[118:121], v[150:153], v[176:179], v[118:121]
	v_mfma_f32_16x16x32_bf16 v[110:113], v[160:163], v[176:179], v[110:113]
	v_mfma_f32_16x16x32_bf16 v[102:105], v[150:153], v[184:187], v[102:105]
	v_mfma_f32_16x16x32_bf16 v[94:97], v[160:163], v[184:187], v[94:97]
	v_mfma_f32_16x16x32_bf16 v[86:89], v[150:153], v[192:195], v[86:89]
	v_mfma_f32_16x16x32_bf16 v[78:81], v[160:163], v[192:195], v[78:81]
	s_barrier
	s_add_i32 s5, 0, 0x1c000
	s_add_i32 s4, s4, s3
	v_add_u32_e32 v139, s5, v144
	s_add_i32 m0, s4, 0xffffff80
	ds_read_b128 v[196:199], v139
	ds_read_b128 v[200:203], v139 offset:1024
	ds_read_b128 v[204:207], v139 offset:2048
	ds_read_b128 v[208:211], v139 offset:3072
	global_load_lds_dwordx4 v[214:215], off offset:128
	s_add_i32 m0, s4, 0x1f80
	s_nop 0
	global_load_lds_dwordx4 v[216:217], off offset:128
	s_barrier
	s_waitcnt lgkmcnt(0)
	s_waitcnt lgkmcnt(0)
	v_mfma_f32_16x16x32_bf16 v[114:117], v[196:199], v[164:167], v[114:117]
	v_mfma_f32_16x16x32_bf16 v[106:109], v[204:207], v[164:167], v[106:109]
	v_mfma_f32_16x16x32_bf16 v[98:101], v[196:199], v[172:175], v[98:101]
	v_mfma_f32_16x16x32_bf16 v[90:93], v[204:207], v[172:175], v[90:93]
	v_mfma_f32_16x16x32_bf16 v[82:85], v[196:199], v[180:183], v[82:85]
	v_mfma_f32_16x16x32_bf16 v[74:77], v[204:207], v[180:183], v[74:77]
	v_mfma_f32_16x16x32_bf16 v[70:73], v[196:199], v[188:191], v[70:73]
	v_mfma_f32_16x16x32_bf16 v[66:69], v[204:207], v[188:191], v[66:69]
	v_mfma_f32_16x16x32_bf16 v[114:117], v[200:203], v[168:171], v[114:117]
	v_mfma_f32_16x16x32_bf16 v[106:109], v[208:211], v[168:171], v[106:109]
	v_mfma_f32_16x16x32_bf16 v[98:101], v[200:203], v[176:179], v[98:101]
	v_mfma_f32_16x16x32_bf16 v[90:93], v[208:211], v[176:179], v[90:93]
	v_mfma_f32_16x16x32_bf16 v[82:85], v[200:203], v[184:187], v[82:85]
	v_mfma_f32_16x16x32_bf16 v[74:77], v[208:211], v[184:187], v[74:77]
	v_mfma_f32_16x16x32_bf16 v[70:73], v[200:203], v[192:195], v[70:73]
	v_mfma_f32_16x16x32_bf16 v[66:69], v[208:211], v[192:195], v[66:69]
	s_add_i32 m0, s29, 0xffffff80
	s_barrier
	ds_read_b128 v[164:167], v145 offset:49152
	ds_read_b128 v[168:171], v145 offset:50176
	ds_read_b128 v[172:175], v145 offset:51200
	ds_read_b128 v[176:179], v145 offset:52224
	ds_read_b128 v[180:183], v145 offset:53248
	ds_read_b128 v[184:187], v145 offset:54272
	ds_read_b128 v[188:191], v145 offset:55296
	ds_read_b128 v[192:195], v145 offset:56320
	global_load_lds_dwordx4 v[218:219], off offset:128
	s_add_i32 m0, s35, 0xffffff80
	s_nop 0
	global_load_lds_dwordx4 v[224:225], off offset:128
	s_barrier
	s_waitcnt lgkmcnt(0)
	s_waitcnt lgkmcnt(0)
	v_mfma_f32_16x16x32_bf16 v[62:65], v[146:149], v[164:167], v[62:65]
	v_mfma_f32_16x16x32_bf16 v[58:61], v[154:157], v[164:167], v[58:61]
	v_mfma_f32_16x16x32_bf16 v[54:57], v[146:149], v[172:175], v[54:57]
	v_mfma_f32_16x16x32_bf16 v[46:49], v[154:157], v[172:175], v[46:49]
	v_mfma_f32_16x16x32_bf16 v[38:41], v[146:149], v[180:183], v[38:41]
	v_mfma_f32_16x16x32_bf16 v[30:33], v[154:157], v[180:183], v[30:33]
	v_mfma_f32_16x16x32_bf16 v[22:25], v[146:149], v[188:191], v[22:25]
	v_mfma_f32_16x16x32_bf16 v[14:17], v[154:157], v[188:191], v[14:17]
	v_mfma_f32_16x16x32_bf16 v[62:65], v[150:153], v[168:171], v[62:65]
	v_mfma_f32_16x16x32_bf16 v[58:61], v[160:163], v[168:171], v[58:61]
	v_mfma_f32_16x16x32_bf16 v[54:57], v[150:153], v[176:179], v[54:57]
	v_mfma_f32_16x16x32_bf16 v[46:49], v[160:163], v[176:179], v[46:49]
	v_mfma_f32_16x16x32_bf16 v[38:41], v[150:153], v[184:187], v[38:41]
	v_mfma_f32_16x16x32_bf16 v[30:33], v[160:163], v[184:187], v[30:33]
	v_mfma_f32_16x16x32_bf16 v[22:25], v[150:153], v[192:195], v[22:25]
	v_mfma_f32_16x16x32_bf16 v[14:17], v[160:163], v[192:195], v[14:17]
	s_barrier
	s_add_i32 s4, s5, s3
	s_add_i32 m0, s4, 0xffffff80
	s_nop 0
	global_load_lds_dwordx4 v[230:231], off offset:128
	s_add_i32 m0, s4, 0x1f80
	s_nop 0
	global_load_lds_dwordx4 v[232:233], off offset:128
	s_waitcnt vmcnt(6)
	s_barrier
	v_mfma_f32_16x16x32_bf16 v[50:53], v[196:199], v[164:167], v[50:53]
	v_mfma_f32_16x16x32_bf16 v[42:45], v[204:207], v[164:167], v[42:45]
	v_mfma_f32_16x16x32_bf16 v[34:37], v[196:199], v[172:175], v[34:37]
	v_mfma_f32_16x16x32_bf16 v[26:29], v[204:207], v[172:175], v[26:29]
	v_mfma_f32_16x16x32_bf16 v[18:21], v[196:199], v[180:183], v[18:21]
	v_mfma_f32_16x16x32_bf16 v[10:13], v[204:207], v[180:183], v[10:13]
	v_mfma_f32_16x16x32_bf16 v[6:9], v[196:199], v[188:191], v[6:9]
	v_mfma_f32_16x16x32_bf16 v[2:5], v[204:207], v[188:191], v[2:5]
	v_mfma_f32_16x16x32_bf16 v[50:53], v[200:203], v[168:171], v[50:53]
	v_mfma_f32_16x16x32_bf16 v[42:45], v[208:211], v[168:171], v[42:45]
	v_mfma_f32_16x16x32_bf16 v[34:37], v[200:203], v[176:179], v[34:37]
	v_mfma_f32_16x16x32_bf16 v[26:29], v[208:211], v[176:179], v[26:29]
	v_mfma_f32_16x16x32_bf16 v[18:21], v[200:203], v[184:187], v[18:21]
	v_mfma_f32_16x16x32_bf16 v[10:13], v[208:211], v[184:187], v[10:13]
	v_mfma_f32_16x16x32_bf16 v[6:9], v[200:203], v[192:195], v[6:9]
	v_mfma_f32_16x16x32_bf16 v[2:5], v[208:211], v[192:195], v[2:5]
	s_add_u32 s6, s6, 0x100
	s_addc_u32 s7, s7, 0
	v_lshl_add_u64 v[142:143], v[142:143], 0, s[86:87]
	s_cmp_ge_u32 s40, s13
	s_mov_b32 s4, s40
	s_barrier
	s_cbranch_scc0 .LBB0_440
	s_lshl_b32 s5, s54, 22
	s_ashr_i32 s4, s54, 3
	s_and_b32 s5, s5, 0x1000000
	v_readlane_b32 s6, v251, 0
	s_add_u32 s6, s6, s5
	v_readlane_b32 s5, v251, 1
	s_addc_u32 s7, s5, 0
	s_ashr_i32 s5, s4, 31
	s_lshl_b64 s[4:5], s[4:5], 22
	s_add_u32 s4, s6, s4
	s_addc_u32 s5, s7, s5
	s_lshl_b32 s6, s54, 9
	s_and_b32 s6, s6, 0x600
	s_add_u32 s4, s4, s6
	v_lshl_add_u32 v146, s90, 8, v1
	s_addc_u32 s5, s5, 0
	v_mov_b32_e32 v139, v0
	v_ashrrev_i32_e32 v147, 31, v146
	v_lshl_add_u64 v[148:149], s[4:5], 0, v[138:139]
	v_lshlrev_b64 v[142:143], 11, v[146:147]
	v_lshl_add_u64 v[142:143], v[148:149], 0, v[142:143]
	v_cvt_pk_bf16_f32 v126, v126, v127
	v_cvt_pk_bf16_f32 v127, v128, v129
	global_store_dwordx2 v[142:143], v[126:127], off
	v_cvt_pk_bf16_f32 v122, v122, v123
	v_cvt_pk_bf16_f32 v123, v124, v125
	global_store_dwordx2 v[142:143], v[122:123], off offset:32
	v_cvt_pk_bf16_f32 v114, v114, v115
	v_cvt_pk_bf16_f32 v115, v116, v117
	global_store_dwordx2 v[142:143], v[114:115], off offset:256
	v_cvt_pk_bf16_f32 v106, v106, v107
	v_cvt_pk_bf16_f32 v107, v108, v109
	global_store_dwordx2 v[142:143], v[106:107], off offset:288
	v_or_b32_e32 v106, 16, v146
	v_ashrrev_i32_e32 v107, 31, v106
	v_lshlrev_b64 v[106:107], 11, v[106:107]
	v_lshl_add_u64 v[106:107], v[148:149], 0, v[106:107]
	v_cvt_pk_bf16_f32 v108, v118, v119
	v_cvt_pk_bf16_f32 v109, v120, v121
	global_store_dwordx2 v[106:107], v[108:109], off
	v_cvt_pk_bf16_f32 v108, v110, v111
	v_cvt_pk_bf16_f32 v109, v112, v113
	global_store_dwordx2 v[106:107], v[108:109], off offset:32
	v_cvt_pk_bf16_f32 v98, v98, v99
	v_cvt_pk_bf16_f32 v99, v100, v101
	global_store_dwordx2 v[106:107], v[98:99], off offset:256
	v_cvt_pk_bf16_f32 v90, v90, v91
	v_cvt_pk_bf16_f32 v91, v92, v93
	global_store_dwordx2 v[106:107], v[90:91], off offset:288
	v_or_b32_e32 v90, 32, v146
	v_ashrrev_i32_e32 v91, 31, v90
	v_lshlrev_b64 v[90:91], 11, v[90:91]
	v_lshl_add_u64 v[90:91], v[148:149], 0, v[90:91]
	v_cvt_pk_bf16_f32 v92, v102, v103
	v_cvt_pk_bf16_f32 v93, v104, v105
	global_store_dwordx2 v[90:91], v[92:93], off
	v_cvt_pk_bf16_f32 v92, v94, v95
	v_cvt_pk_bf16_f32 v93, v96, v97
	global_store_dwordx2 v[90:91], v[92:93], off offset:32
	v_cvt_pk_bf16_f32 v82, v82, v83
	v_cvt_pk_bf16_f32 v83, v84, v85
	global_store_dwordx2 v[90:91], v[82:83], off offset:256
	v_cvt_pk_bf16_f32 v74, v74, v75
	v_cvt_pk_bf16_f32 v75, v76, v77
	global_store_dwordx2 v[90:91], v[74:75], off offset:288
	v_or_b32_e32 v74, 48, v146
	v_ashrrev_i32_e32 v75, 31, v74
	v_lshlrev_b64 v[74:75], 11, v[74:75]
	v_lshl_add_u64 v[74:75], v[148:149], 0, v[74:75]
	v_cvt_pk_bf16_f32 v76, v86, v87
	v_cvt_pk_bf16_f32 v77, v88, v89
	global_store_dwordx2 v[74:75], v[76:77], off
	v_cvt_pk_bf16_f32 v76, v78, v79
	v_cvt_pk_bf16_f32 v77, v80, v81
	global_store_dwordx2 v[74:75], v[76:77], off offset:32
	v_cvt_pk_bf16_f32 v70, v70, v71
	v_cvt_pk_bf16_f32 v71, v72, v73
	global_store_dwordx2 v[74:75], v[70:71], off offset:256
	v_cvt_pk_bf16_f32 v66, v66, v67
	v_cvt_pk_bf16_f32 v67, v68, v69
	s_mov_b64 s[4:5], 0x40000
	global_store_dwordx2 v[74:75], v[66:67], off offset:288
	v_lshl_add_u64 v[66:67], v[142:143], 0, s[4:5]
	s_mov_b32 s4, 0x40000
	v_cvt_pk_bf16_f32 v62, v62, v63
	v_cvt_pk_bf16_f32 v63, v64, v65
	v_add_co_u32_e32 v64, vcc, s4, v142
	s_mov_b64 s[4:5], 0x48000
	s_nop 0
	v_addc_co_u32_e32 v65, vcc, 0, v143, vcc
	global_store_dwordx2 v[64:65], v[62:63], off
	v_cvt_pk_bf16_f32 v58, v58, v59
	v_cvt_pk_bf16_f32 v59, v60, v61
	global_store_dwordx2 v[66:67], v[58:59], off offset:32
	v_cvt_pk_bf16_f32 v50, v50, v51
	v_cvt_pk_bf16_f32 v51, v52, v53
	global_store_dwordx2 v[66:67], v[50:51], off offset:256
	v_cvt_pk_bf16_f32 v42, v42, v43
	v_cvt_pk_bf16_f32 v43, v44, v45
	global_store_dwordx2 v[66:67], v[42:43], off offset:288
	v_lshl_add_u64 v[42:43], v[142:143], 0, s[4:5]
	s_mov_b32 s4, 0x48000
	v_add_co_u32_e32 v50, vcc, s4, v142
	v_cvt_pk_bf16_f32 v44, v54, v55
	v_cvt_pk_bf16_f32 v45, v56, v57
	s_mov_b64 s[4:5], 0x50000
	s_nop 0
	v_addc_co_u32_e32 v51, vcc, 0, v143, vcc
	global_store_dwordx2 v[50:51], v[44:45], off
	v_cvt_pk_bf16_f32 v44, v46, v47
	v_cvt_pk_bf16_f32 v45, v48, v49
	global_store_dwordx2 v[42:43], v[44:45], off offset:32
	v_cvt_pk_bf16_f32 v34, v34, v35
	v_cvt_pk_bf16_f32 v35, v36, v37
	global_store_dwordx2 v[42:43], v[34:35], off offset:256
	v_cvt_pk_bf16_f32 v26, v26, v27
	v_cvt_pk_bf16_f32 v27, v28, v29
	global_store_dwordx2 v[42:43], v[26:27], off offset:288
	v_lshl_add_u64 v[26:27], v[142:143], 0, s[4:5]
	s_mov_b32 s4, 0x50000
	v_add_co_u32_e32 v34, vcc, s4, v142
	v_cvt_pk_bf16_f32 v28, v38, v39
	v_cvt_pk_bf16_f32 v29, v40, v41
	s_mov_b64 s[4:5], 0x58000
	s_nop 0
	v_addc_co_u32_e32 v35, vcc, 0, v143, vcc
	global_store_dwordx2 v[34:35], v[28:29], off
	v_cvt_pk_bf16_f32 v28, v30, v31
	v_cvt_pk_bf16_f32 v29, v32, v33
	global_store_dwordx2 v[26:27], v[28:29], off offset:32
	v_cvt_pk_bf16_f32 v18, v18, v19
	v_cvt_pk_bf16_f32 v19, v20, v21
	global_store_dwordx2 v[26:27], v[18:19], off offset:256
	v_cvt_pk_bf16_f32 v10, v10, v11
	v_cvt_pk_bf16_f32 v11, v12, v13
	global_store_dwordx2 v[26:27], v[10:11], off offset:288
	v_lshl_add_u64 v[10:11], v[142:143], 0, s[4:5]
	s_mov_b32 s4, 0x58000
	v_add_co_u32_e32 v18, vcc, s4, v142
	v_cvt_pk_bf16_f32 v12, v22, v23
	v_cvt_pk_bf16_f32 v13, v24, v25
	s_mov_b32 s54, s44
	s_nop 0
	v_addc_co_u32_e32 v19, vcc, 0, v143, vcc
	global_store_dwordx2 v[18:19], v[12:13], off
	v_cvt_pk_bf16_f32 v12, v14, v15
	v_cvt_pk_bf16_f32 v13, v16, v17
	global_store_dwordx2 v[10:11], v[12:13], off offset:32
	v_cvt_pk_bf16_f32 v6, v6, v7
	v_cvt_pk_bf16_f32 v7, v8, v9
	global_store_dwordx2 v[10:11], v[6:7], off offset:256
	v_cvt_pk_bf16_f32 v2, v2, v3
	v_cvt_pk_bf16_f32 v3, v4, v5
	global_store_dwordx2 v[10:11], v[2:3], off offset:288
	s_and_b64 vcc, exec, s[38:39]
	s_mov_b32 s90, s45
	s_mov_b64 s[4:5], s[0:1]
	v_mov_b64_e32 v[2:3], v[140:141]
	s_cbranch_vccz .LBB0_433
	s_waitcnt vmcnt(0)
	s_cmpk_gt_u32 s2, 0xff
	s_mov_b32 s36, s65
	s_cbranch_scc1 .LBB0_444
	s_barrier

.LBB0_452:
	v_mov_b32_e32 v131, v0
	s_add_i32 m0, s8, 0x17f80
	v_lshl_add_u64 v[20:21], v[2:3], 0, v[130:131]
	v_mov_b32_e32 v135, v0
	s_waitcnt vmcnt(4)
	s_barrier
	global_load_lds_dwordx4 v[4:5], off offset:128
	s_add_i32 m0, s8, 0x19f80
	s_add_i32 s12, s8, 0x8000
	v_lshl_add_u64 v[22:23], v[2:3], 0, v[134:135]
	global_load_lds_dwordx4 v[6:7], off offset:128
	s_add_i32 m0, s12, 0xffffff80
	s_add_i32 s22, s8, 0xa000
	global_load_lds_dwordx4 v[20:21], off offset:128
	s_add_i32 m0, s22, 0xffffff80
	v_and_b32_e32 v6, 15, v12
	global_load_lds_dwordx4 v[22:23], off offset:128
	s_add_i32 m0, s8, 0x1bf80
	global_load_lds_dwordx4 v[8:9], off offset:128
	s_add_i32 m0, s8, 0x1df80
	v_and_b32_e32 v8, 48, v12
	global_load_lds_dwordx4 v[10:11], off offset:128
	v_bfe_u32 v5, v12, 4, 2
	s_and_b32 s2, s0, 3
	v_lshl_or_b32 v1, s1, 6, v6
	v_lshlrev_b32_e32 v7, 3, v5
	v_lshl_or_b32 v6, v6, 6, v8
	v_lshlrev_b32_e32 v8, 2, v12
	s_lshl_b32 s0, s0, 11
	s_lshl_b32 s36, s16, 3
	s_lshl_b32 s1, s1, 13
	v_and_b32_e32 v8, 32, v8
	v_lshl_or_b32 v167, s2, 5, v7
	s_add_i32 s23, s0, 0
	s_ashr_i32 s0, s37, 31
	v_cvt_f32_u32_e32 v7, s36
	v_bitop3_b32 v9, v6, s1, v8 bitop3:0xde
	s_lshl_b32 s1, s2, 12
	v_writelane_b32 v255, s0, 27
	s_ashr_i32 s0, s14, 31
	v_and_b32_e32 v4, 63, v12
	v_bitop3_b32 v166, v6, s1, v8 bitop3:0xde
	v_writelane_b32 v255, s0, 28
	v_readlane_b32 s0, v250, 12
	v_lshlrev_b32_e32 v6, 2, v4
	v_cmp_gt_u32_e64 s[38:39], 16, v4
	v_lshlrev_b32_e32 v4, 2, v5
	v_mov_b32_e32 v5, v0
	v_readlane_b32 s1, v250, 13
	s_waitcnt vmcnt(6)
	s_add_i32 s23, s23, 0x22100
	s_add_i32 s28, s13, -2
	v_lshl_add_u64 v[138:139], s[0:1], 0, v[4:5]
	v_rcp_iflag_f32_e32 v4, v7
	s_lshr_b32 s0, s24, 3
	v_writelane_b32 v255, s0, 25
	s_lshl_b32 s0, s2, 3
	v_mul_f32_e32 v4, 0x4f7ffffe, v4
	v_cvt_u32_f32_e32 v4, v4
	s_add_i32 s45, s0, 0
	s_sub_i32 s0, 0, s36
	v_lshlrev_b32_e32 v168, 5, v1
	v_readfirstlane_b32 s1, v4
	v_add_u32_e32 v4, v15, v13
	s_mul_i32 s0, s0, s1
	v_add_lshl_u32 v4, v4, v14, 1
	s_mul_hi_u32 s0, s1, s0
	v_lshl_add_u64 v[140:141], s[94:95], 0, v[4:5]
	v_add_u32_e32 v4, v18, v16
	s_add_i32 s0, s1, s0
	v_add_lshl_u32 v4, v4, v17, 1
	s_mov_b32 s25, s95
	s_add_i32 s45, s45, 0x20000
	s_mov_b32 s54, 0
	v_writelane_b32 v255, s0, 33
	v_lshl_add_u64 v[142:143], s[94:95], 0, v[4:5]
	s_add_i32 s91, s23, 0x300
	s_add_i32 s2, s23, 0x500
	s_add_i32 s44, s23, 0x700
	v_add_u32_e32 v169, 0, v9
	v_add_u32_e32 v170, s23, v6
	s_mov_b32 s89, 0xff61b1e6
	s_barrier
	s_branch .LBB0_454

.LBB0_461:
	s_add_i32 s17, s4, 2
	s_add_i32 s42, 0, 0x10000
	s_cmp_eq_u32 s28, s4
	v_lshl_add_u64 v[150:151], v[148:149], 0, s[84:85]
	s_cselect_b64 vcc, -1, 0
	v_add_u32_e32 v171, s42, v166
	v_cndmask_b32_e32 v165, v151, v145, vcc
	v_cndmask_b32_e32 v164, v150, v144, vcc
	ds_read_b128 v[150:153], v171
	ds_read_b128 v[154:157], v171 offset:1024
	ds_read_b128 v[160:163], v171 offset:2048
	ds_read_b128 v[172:175], v171 offset:3072
	s_cselect_b32 s4, s0, s6
	s_cselect_b32 s5, s1, s7
	v_lshl_add_u64 v[208:209], v[148:149], 0, v[140:141]
	s_add_i32 m0, s8, 0xc000
	ds_read_b128 v[176:179], v169
	ds_read_b128 v[180:183], v169 offset:1024
	ds_read_b128 v[184:187], v169 offset:2048
	ds_read_b128 v[188:191], v169 offset:3072
	ds_read_b128 v[192:195], v169 offset:4096
	ds_read_b128 v[196:199], v169 offset:5120
	ds_read_b128 v[200:203], v169 offset:6144
	ds_read_b128 v[204:207], v169 offset:7168
	global_load_lds_dwordx4 v[208:209], off
	v_lshl_add_u64 v[208:209], v[148:149], 0, v[142:143]
	s_add_i32 m0, s8, 0xe000
	s_nop 0
	global_load_lds_dwordx4 v[208:209], off
	s_waitcnt lgkmcnt(8)
	s_barrier
	s_waitcnt lgkmcnt(0)
	s_waitcnt lgkmcnt(0)
	v_mfma_f32_16x16x32_bf16 v[126:129], v[150:153], v[176:179], v[126:129]
	v_mfma_f32_16x16x32_bf16 v[122:125], v[160:163], v[176:179], v[122:125]
	v_mfma_f32_16x16x32_bf16 v[110:113], v[150:153], v[184:187], v[110:113]
	v_mfma_f32_16x16x32_bf16 v[106:109], v[160:163], v[184:187], v[106:109]
	v_mfma_f32_16x16x32_bf16 v[94:97], v[150:153], v[192:195], v[94:97]
	v_mfma_f32_16x16x32_bf16 v[90:93], v[160:163], v[192:195], v[90:93]
	v_mfma_f32_16x16x32_bf16 v[78:81], v[150:153], v[200:203], v[78:81]
	v_mfma_f32_16x16x32_bf16 v[74:77], v[160:163], v[200:203], v[74:77]
	v_mfma_f32_16x16x32_bf16 v[126:129], v[154:157], v[180:183], v[126:129]
	v_mfma_f32_16x16x32_bf16 v[122:125], v[172:175], v[180:183], v[122:125]
	v_mfma_f32_16x16x32_bf16 v[110:113], v[154:157], v[188:191], v[110:113]
	v_mfma_f32_16x16x32_bf16 v[106:109], v[172:175], v[188:191], v[106:109]
	v_mfma_f32_16x16x32_bf16 v[94:97], v[154:157], v[196:199], v[94:97]
	v_mfma_f32_16x16x32_bf16 v[90:93], v[172:175], v[196:199], v[90:93]
	v_mfma_f32_16x16x32_bf16 v[78:81], v[154:157], v[204:207], v[78:81]
	v_mfma_f32_16x16x32_bf16 v[74:77], v[172:175], v[204:207], v[74:77]
	s_barrier
	s_add_i32 s43, 0, 0x14000
	s_add_i32 s42, s42, s3
	v_add_u32_e32 v171, s43, v166
	v_lshl_add_u64 v[224:225], s[4:5], 0, v[132:133]
	s_mov_b32 m0, s42
	ds_read_b128 v[208:211], v171
	ds_read_b128 v[212:215], v171 offset:1024
	ds_read_b128 v[216:219], v171 offset:2048
	ds_read_b128 v[238:241], v171 offset:3072
	global_load_lds_dwordx4 v[224:225], off
	v_lshl_add_u64 v[230:231], s[4:5], 0, v[136:137]
	s_add_i32 m0, s42, 0x2000
	s_nop 0
	global_load_lds_dwordx4 v[230:231], off
	s_barrier
	s_waitcnt lgkmcnt(0)
	s_waitcnt lgkmcnt(0)
	v_mfma_f32_16x16x32_bf16 v[118:121], v[208:211], v[176:179], v[118:121]
	v_mfma_f32_16x16x32_bf16 v[114:117], v[216:219], v[176:179], v[114:117]
	v_mfma_f32_16x16x32_bf16 v[102:105], v[208:211], v[184:187], v[102:105]
	v_mfma_f32_16x16x32_bf16 v[98:101], v[216:219], v[184:187], v[98:101]
	v_mfma_f32_16x16x32_bf16 v[86:89], v[208:211], v[192:195], v[86:89]
	v_mfma_f32_16x16x32_bf16 v[82:85], v[216:219], v[192:195], v[82:85]
	v_mfma_f32_16x16x32_bf16 v[70:73], v[208:211], v[200:203], v[70:73]
	v_mfma_f32_16x16x32_bf16 v[66:69], v[216:219], v[200:203], v[66:69]
	v_mfma_f32_16x16x32_bf16 v[118:121], v[212:215], v[180:183], v[118:121]
	v_mfma_f32_16x16x32_bf16 v[114:117], v[238:241], v[180:183], v[114:117]
	v_mfma_f32_16x16x32_bf16 v[102:105], v[212:215], v[188:191], v[102:105]
	v_mfma_f32_16x16x32_bf16 v[98:101], v[238:241], v[188:191], v[98:101]
	v_mfma_f32_16x16x32_bf16 v[86:89], v[212:215], v[196:199], v[86:89]
	v_mfma_f32_16x16x32_bf16 v[82:85], v[238:241], v[196:199], v[82:85]
	v_mfma_f32_16x16x32_bf16 v[70:73], v[212:215], v[204:207], v[70:73]
	v_mfma_f32_16x16x32_bf16 v[66:69], v[238:241], v[204:207], v[66:69]
	s_mov_b32 m0, s8
	v_lshl_add_u64 v[232:233], v[164:165], 0, v[130:131]
	s_barrier
	ds_read_b128 v[176:179], v169 offset:16384
	ds_read_b128 v[180:183], v169 offset:17408
	ds_read_b128 v[184:187], v169 offset:18432
	ds_read_b128 v[188:191], v169 offset:19456
	ds_read_b128 v[192:195], v169 offset:20480
	ds_read_b128 v[196:199], v169 offset:21504
	ds_read_b128 v[200:203], v169 offset:22528
	ds_read_b128 v[204:207], v169 offset:23552
	global_load_lds_dwordx4 v[232:233], off
	v_lshl_add_u64 v[242:243], v[164:165], 0, v[134:135]
	s_mov_b32 m0, s9
	s_nop 0
	global_load_lds_dwordx4 v[242:243], off
	s_barrier
	s_waitcnt lgkmcnt(0)
	s_waitcnt lgkmcnt(0)
	v_mfma_f32_16x16x32_bf16 v[54:57], v[150:153], v[176:179], v[54:57]
	v_mfma_f32_16x16x32_bf16 v[50:53], v[160:163], v[176:179], v[50:53]
	v_mfma_f32_16x16x32_bf16 v[38:41], v[150:153], v[184:187], v[38:41]
	v_mfma_f32_16x16x32_bf16 v[34:37], v[160:163], v[184:187], v[34:37]
	v_mfma_f32_16x16x32_bf16 v[22:25], v[150:153], v[192:195], v[22:25]
	v_mfma_f32_16x16x32_bf16 v[18:21], v[160:163], v[192:195], v[18:21]
	v_mfma_f32_16x16x32_bf16 v[6:9], v[150:153], v[200:203], v[6:9]
	v_mfma_f32_16x16x32_bf16 v[2:5], v[160:163], v[200:203], v[2:5]
	v_mfma_f32_16x16x32_bf16 v[54:57], v[154:157], v[180:183], v[54:57]
	v_mfma_f32_16x16x32_bf16 v[50:53], v[172:175], v[180:183], v[50:53]
	v_mfma_f32_16x16x32_bf16 v[38:41], v[154:157], v[188:191], v[38:41]
	v_mfma_f32_16x16x32_bf16 v[34:37], v[172:175], v[188:191], v[34:37]
	v_mfma_f32_16x16x32_bf16 v[22:25], v[154:157], v[196:199], v[22:25]
	v_mfma_f32_16x16x32_bf16 v[18:21], v[172:175], v[196:199], v[18:21]
	v_mfma_f32_16x16x32_bf16 v[6:9], v[154:157], v[204:207], v[6:9]
	v_mfma_f32_16x16x32_bf16 v[2:5], v[172:175], v[204:207], v[2:5]
	s_barrier
	s_add_u32 s4, s4, s94
	s_addc_u32 s5, s5, 0
	s_add_i32 s42, s43, s3
	v_lshl_add_u64 v[244:245], s[4:5], 0, v[132:133]
	s_mov_b32 m0, s42
	v_lshl_add_u64 v[246:247], s[4:5], 0, v[136:137]
	global_load_lds_dwordx4 v[244:245], off
	s_add_i32 m0, s42, 0x2000
	s_nop 0
	global_load_lds_dwordx4 v[246:247], off
	s_waitcnt vmcnt(6)
	s_barrier
	v_mfma_f32_16x16x32_bf16 v[62:65], v[208:211], v[176:179], v[62:65]
	v_mfma_f32_16x16x32_bf16 v[58:61], v[216:219], v[176:179], v[58:61]
	v_mfma_f32_16x16x32_bf16 v[46:49], v[208:211], v[184:187], v[46:49]
	v_mfma_f32_16x16x32_bf16 v[42:45], v[216:219], v[184:187], v[42:45]
	v_mfma_f32_16x16x32_bf16 v[30:33], v[208:211], v[192:195], v[30:33]
	v_mfma_f32_16x16x32_bf16 v[26:29], v[216:219], v[192:195], v[26:29]
	v_mfma_f32_16x16x32_bf16 v[14:17], v[208:211], v[200:203], v[14:17]
	v_mfma_f32_16x16x32_bf16 v[10:13], v[216:219], v[200:203], v[10:13]
	v_mfma_f32_16x16x32_bf16 v[62:65], v[212:215], v[180:183], v[62:65]
	v_mfma_f32_16x16x32_bf16 v[58:61], v[238:241], v[180:183], v[58:61]
	v_mfma_f32_16x16x32_bf16 v[46:49], v[212:215], v[188:191], v[46:49]
	v_mfma_f32_16x16x32_bf16 v[42:45], v[238:241], v[188:191], v[42:45]
	v_mfma_f32_16x16x32_bf16 v[30:33], v[212:215], v[196:199], v[30:33]
	v_mfma_f32_16x16x32_bf16 v[26:29], v[238:241], v[196:199], v[26:29]
	v_mfma_f32_16x16x32_bf16 v[14:17], v[212:215], v[204:207], v[14:17]
	v_mfma_f32_16x16x32_bf16 v[10:13], v[238:241], v[204:207], v[10:13]
	s_add_i32 s4, 0, 0x18000
	v_add_u32_e32 v171, s4, v166
	s_barrier
	ds_read_b128 v[150:153], v171
	ds_read_b128 v[154:157], v171 offset:1024
	ds_read_b128 v[160:163], v171 offset:2048
	ds_read_b128 v[172:175], v171 offset:3072
	v_lshl_add_u64 v[164:165], v[164:165], 0, s[94:95]
	s_mov_b32 m0, s10
	v_lshl_add_u64 v[208:209], v[164:165], 0, v[130:131]
	ds_read_b128 v[176:179], v169 offset:32768
	ds_read_b128 v[180:183], v169 offset:33792
	ds_read_b128 v[184:187], v169 offset:34816
	ds_read_b128 v[188:191], v169 offset:35840
	ds_read_b128 v[192:195], v169 offset:36864
	ds_read_b128 v[196:199], v169 offset:37888
	ds_read_b128 v[200:203], v169 offset:38912
	ds_read_b128 v[204:207], v169 offset:39936
	global_load_lds_dwordx4 v[208:209], off
	v_lshl_add_u64 v[164:165], v[164:165], 0, v[134:135]
	s_mov_b32 m0, s11
	s_nop 0
	global_load_lds_dwordx4 v[164:165], off
	s_waitcnt lgkmcnt(8)
	s_barrier
	s_waitcnt lgkmcnt(0)
	s_waitcnt lgkmcnt(0)
	v_mfma_f32_16x16x32_bf16 v[126:129], v[150:153], v[176:179], v[126:129]
	v_mfma_f32_16x16x32_bf16 v[122:125], v[160:163], v[176:179], v[122:125]
	v_mfma_f32_16x16x32_bf16 v[110:113], v[150:153], v[184:187], v[110:113]
	v_mfma_f32_16x16x32_bf16 v[106:109], v[160:163], v[184:187], v[106:109]
	v_mfma_f32_16x16x32_bf16 v[94:97], v[150:153], v[192:195], v[94:97]
	v_mfma_f32_16x16x32_bf16 v[90:93], v[160:163], v[192:195], v[90:93]
	v_mfma_f32_16x16x32_bf16 v[78:81], v[150:153], v[200:203], v[78:81]
	v_mfma_f32_16x16x32_bf16 v[74:77], v[160:163], v[200:203], v[74:77]
	v_mfma_f32_16x16x32_bf16 v[126:129], v[154:157], v[180:183], v[126:129]
	v_mfma_f32_16x16x32_bf16 v[122:125], v[172:175], v[180:183], v[122:125]
	v_mfma_f32_16x16x32_bf16 v[110:113], v[154:157], v[188:191], v[110:113]
	v_mfma_f32_16x16x32_bf16 v[106:109], v[172:175], v[188:191], v[106:109]
	v_mfma_f32_16x16x32_bf16 v[94:97], v[154:157], v[196:199], v[94:97]
	v_mfma_f32_16x16x32_bf16 v[90:93], v[172:175], v[196:199], v[90:93]
	v_mfma_f32_16x16x32_bf16 v[78:81], v[154:157], v[204:207], v[78:81]
	v_mfma_f32_16x16x32_bf16 v[74:77], v[172:175], v[204:207], v[74:77]
	s_barrier
	s_add_i32 s5, 0, 0x1c000
	v_add_u32_e32 v164, s5, v166
	s_add_i32 s4, s4, s3
	ds_read_b128 v[208:211], v164
	ds_read_b128 v[212:215], v164 offset:1024
	ds_read_b128 v[216:219], v164 offset:2048
	ds_read_b128 v[238:241], v164 offset:3072
	s_add_i32 m0, s4, 0xffffff80
	s_nop 0
	global_load_lds_dwordx4 v[224:225], off offset:128
	s_add_i32 m0, s4, 0x1f80
	s_nop 0
	global_load_lds_dwordx4 v[230:231], off offset:128
	s_barrier
	s_waitcnt lgkmcnt(0)
	s_waitcnt lgkmcnt(0)
	v_mfma_f32_16x16x32_bf16 v[118:121], v[208:211], v[176:179], v[118:121]
	v_mfma_f32_16x16x32_bf16 v[114:117], v[216:219], v[176:179], v[114:117]
	v_mfma_f32_16x16x32_bf16 v[102:105], v[208:211], v[184:187], v[102:105]
	v_mfma_f32_16x16x32_bf16 v[98:101], v[216:219], v[184:187], v[98:101]
	v_mfma_f32_16x16x32_bf16 v[86:89], v[208:211], v[192:195], v[86:89]
	v_mfma_f32_16x16x32_bf16 v[82:85], v[216:219], v[192:195], v[82:85]
	v_mfma_f32_16x16x32_bf16 v[70:73], v[208:211], v[200:203], v[70:73]
	v_mfma_f32_16x16x32_bf16 v[66:69], v[216:219], v[200:203], v[66:69]
	v_mfma_f32_16x16x32_bf16 v[118:121], v[212:215], v[180:183], v[118:121]
	v_mfma_f32_16x16x32_bf16 v[114:117], v[238:241], v[180:183], v[114:117]
	v_mfma_f32_16x16x32_bf16 v[102:105], v[212:215], v[188:191], v[102:105]
	v_mfma_f32_16x16x32_bf16 v[98:101], v[238:241], v[188:191], v[98:101]
	v_mfma_f32_16x16x32_bf16 v[86:89], v[212:215], v[196:199], v[86:89]
	v_mfma_f32_16x16x32_bf16 v[82:85], v[238:241], v[196:199], v[82:85]
	v_mfma_f32_16x16x32_bf16 v[70:73], v[212:215], v[204:207], v[70:73]
	v_mfma_f32_16x16x32_bf16 v[66:69], v[238:241], v[204:207], v[66:69]
	s_add_i32 m0, s12, 0xffffff80
	s_barrier
	ds_read_b128 v[176:179], v169 offset:49152
	ds_read_b128 v[180:183], v169 offset:50176
	ds_read_b128 v[184:187], v169 offset:51200
	ds_read_b128 v[188:191], v169 offset:52224
	ds_read_b128 v[192:195], v169 offset:53248
	ds_read_b128 v[196:199], v169 offset:54272
	ds_read_b128 v[200:203], v169 offset:55296
	ds_read_b128 v[204:207], v169 offset:56320
	global_load_lds_dwordx4 v[232:233], off offset:128
	s_add_i32 m0, s22, 0xffffff80
	s_nop 0
	global_load_lds_dwordx4 v[242:243], off offset:128
	s_barrier
	s_waitcnt lgkmcnt(0)
	s_waitcnt lgkmcnt(0)
	v_mfma_f32_16x16x32_bf16 v[54:57], v[150:153], v[176:179], v[54:57]
	v_mfma_f32_16x16x32_bf16 v[50:53], v[160:163], v[176:179], v[50:53]
	v_mfma_f32_16x16x32_bf16 v[38:41], v[150:153], v[184:187], v[38:41]
	v_mfma_f32_16x16x32_bf16 v[34:37], v[160:163], v[184:187], v[34:37]
	v_mfma_f32_16x16x32_bf16 v[22:25], v[150:153], v[192:195], v[22:25]
	v_mfma_f32_16x16x32_bf16 v[18:21], v[160:163], v[192:195], v[18:21]
	v_mfma_f32_16x16x32_bf16 v[6:9], v[150:153], v[200:203], v[6:9]
	v_mfma_f32_16x16x32_bf16 v[2:5], v[160:163], v[200:203], v[2:5]
	v_mfma_f32_16x16x32_bf16 v[54:57], v[154:157], v[180:183], v[54:57]
	v_mfma_f32_16x16x32_bf16 v[50:53], v[172:175], v[180:183], v[50:53]
	v_mfma_f32_16x16x32_bf16 v[38:41], v[154:157], v[188:191], v[38:41]
	v_mfma_f32_16x16x32_bf16 v[34:37], v[172:175], v[188:191], v[34:37]
	v_mfma_f32_16x16x32_bf16 v[22:25], v[154:157], v[196:199], v[22:25]
	v_mfma_f32_16x16x32_bf16 v[18:21], v[172:175], v[196:199], v[18:21]
	v_mfma_f32_16x16x32_bf16 v[6:9], v[154:157], v[204:207], v[6:9]
	v_mfma_f32_16x16x32_bf16 v[2:5], v[172:175], v[204:207], v[2:5]
	s_barrier
	s_add_i32 s4, s5, s3
	s_add_i32 m0, s4, 0xffffff80
	s_nop 0
	global_load_lds_dwordx4 v[244:245], off offset:128
	s_add_i32 m0, s4, 0x1f80
	s_nop 0
	global_load_lds_dwordx4 v[246:247], off offset:128
	s_waitcnt vmcnt(6)
	s_barrier
	v_mfma_f32_16x16x32_bf16 v[62:65], v[208:211], v[176:179], v[62:65]
	v_mfma_f32_16x16x32_bf16 v[58:61], v[216:219], v[176:179], v[58:61]
	v_mfma_f32_16x16x32_bf16 v[46:49], v[208:211], v[184:187], v[46:49]
	v_mfma_f32_16x16x32_bf16 v[42:45], v[216:219], v[184:187], v[42:45]
	v_mfma_f32_16x16x32_bf16 v[30:33], v[208:211], v[192:195], v[30:33]
	v_mfma_f32_16x16x32_bf16 v[26:29], v[216:219], v[192:195], v[26:29]
	v_mfma_f32_16x16x32_bf16 v[14:17], v[208:211], v[200:203], v[14:17]
	v_mfma_f32_16x16x32_bf16 v[10:13], v[216:219], v[200:203], v[10:13]
	v_mfma_f32_16x16x32_bf16 v[62:65], v[212:215], v[180:183], v[62:65]
	v_mfma_f32_16x16x32_bf16 v[58:61], v[238:241], v[180:183], v[58:61]
	v_mfma_f32_16x16x32_bf16 v[46:49], v[212:215], v[188:191], v[46:49]
	v_mfma_f32_16x16x32_bf16 v[42:45], v[238:241], v[188:191], v[42:45]
	v_mfma_f32_16x16x32_bf16 v[30:33], v[212:215], v[196:199], v[30:33]
	v_mfma_f32_16x16x32_bf16 v[26:29], v[238:241], v[196:199], v[26:29]
	v_mfma_f32_16x16x32_bf16 v[14:17], v[212:215], v[204:207], v[14:17]
	v_mfma_f32_16x16x32_bf16 v[10:13], v[238:241], v[204:207], v[10:13]
	s_add_u32 s6, s6, 0x100
	s_addc_u32 s7, s7, 0
	v_lshl_add_u64 v[148:149], v[148:149], 0, s[86:87]
	s_cmp_ge_u32 s17, s13
	s_mov_b32 s4, s17
	s_barrier
	s_cbranch_scc0 .LBB0_461
	v_cmp_lt_i32_e32 vcc, v227, v222
	ds_read2st64_b32 v[148:149], v170 offset1:1
	ds_read2st64_b32 v[150:151], v170 offset0:2 offset1:3
	ds_read2st64_b32 v[156:157], v170 offset0:4 offset1:5
	ds_read2st64_b32 v[160:161], v170 offset0:6 offset1:7
	v_cndmask_b32_e32 v152, v221, v227, vcc
	v_lshlrev_b32_e32 v171, 2, v152
	s_waitcnt lgkmcnt(0)
	ds_bpermute_b32 v153, v171, v148
	ds_bpermute_b32 v152, v171, v149
	v_cmp_lt_i32_e32 vcc, v228, v222
	v_mov_b32_e32 v155, v148
	s_mov_b32 s4, 0x3a800000
	v_cndmask_b32_e32 v154, v221, v228, vcc
	v_lshlrev_b32_e32 v172, 2, v154
	v_mov_b32_e32 v154, v149
	s_waitcnt lgkmcnt(0)
	v_pk_add_f32 v[148:149], v[154:155], v[152:153]
	ds_bpermute_b32 v153, v172, v149
	ds_bpermute_b32 v152, v172, v148
	ds_bpermute_b32 v174, v171, v161
	ds_bpermute_b32 v175, v171, v160
	s_waitcnt lgkmcnt(0)
	v_pk_add_f32 v[148:149], v[148:149], v[152:153]
	s_nop 0
	v_pk_fma_f32 v[162:163], v[148:149], s[4:5], v[158:159] op_sel_hi:[1,0,0]
	ds_bpermute_b32 v149, v171, v150
	v_mul_f32_e32 v148, 0x4b800000, v163
	v_cmp_gt_f32_e32 vcc, s88, v163
	s_nop 1
	v_cndmask_b32_e32 v148, v163, v148, vcc
	v_rsq_f32_e32 v152, v148
	ds_bpermute_b32 v148, v171, v151
	v_mul_f32_e32 v153, 0x45800000, v152
	v_cndmask_b32_e32 v164, v152, v153, vcc
	v_mov_b32_e32 v152, v151
	v_mov_b32_e32 v153, v150
	v_pk_mul_f32 v[128:129], v[128:129], v[164:165] op_sel_hi:[1,0]
	v_pk_mul_f32 v[124:125], v[124:125], v[164:165] op_sel_hi:[1,0]
	s_waitcnt lgkmcnt(0)
	v_pk_add_f32 v[152:153], v[152:153], v[148:149]
	v_pk_mul_f32 v[126:127], v[126:127], v[164:165] op_sel_hi:[1,0]
	v_max_f32_e32 v148, v128, v129
	v_pk_mul_f32 v[122:123], v[122:123], v[164:165] op_sel_hi:[1,0]
	v_max_f32_e32 v149, v124, v125
	v_max3_f32 v148, v126, v127, v148
	v_max3_f32 v149, v122, v123, v149
	v_pk_mul_f32 v[120:121], v[120:121], v[164:165] op_sel_hi:[1,0]
	v_pk_mul_f32 v[116:117], v[116:117], v[164:165] op_sel_hi:[1,0]
	v_max3_f32 v148, v148, s89, v149
	v_pk_mul_f32 v[118:119], v[118:119], v[164:165] op_sel_hi:[1,0]
	v_max_f32_e32 v149, v120, v121
	v_pk_mul_f32 v[114:115], v[114:115], v[164:165] op_sel_hi:[1,0]
	v_max_f32_e32 v150, v116, v117
	v_max3_f32 v149, v118, v119, v149
	v_max3_f32 v150, v114, v115, v150
	v_max3_f32 v163, v148, v149, v150
	ds_bpermute_b32 v164, v171, v163
	ds_bpermute_b32 v151, v171, v156
	v_mov_b32_e32 v149, v156
	v_mov_b32_e32 v148, v157
	ds_bpermute_b32 v150, v171, v157
	s_waitcnt lgkmcnt(0)
	v_max_f32_e32 v156, v164, v164
	v_max_f32_e32 v157, v163, v156
	ds_bpermute_b32 v163, v172, v157
	v_mov_b32_e32 v156, v161
	v_pk_add_f32 v[148:149], v[148:149], v[150:151]
	ds_bpermute_b32 v155, v172, v153
	ds_bpermute_b32 v154, v172, v152
	s_waitcnt lgkmcnt(0)
	v_max_f32_e32 v163, v163, v163
	v_max_f32_e32 v164, v157, v163
	v_sub_f32_e32 v157, v126, v164
	v_sub_f32_e32 v163, v127, v164
	v_sub_f32_e32 v165, v128, v164
	v_sub_f32_e32 v173, v129, v164
	v_mul_f32_e32 v157, 0x3fb8aa3b, v157
	v_mul_f32_e32 v163, 0x3fb8aa3b, v163
	v_mul_f32_e32 v165, 0x3fb8aa3b, v165
	v_mul_f32_e32 v173, 0x3fb8aa3b, v173
	v_exp_f32_e32 v157, v157
	v_exp_f32_e32 v163, v163
	v_exp_f32_e32 v165, v165
	v_exp_f32_e32 v173, v173
	v_sub_f32_e32 v176, v125, v164
	v_add_f32_e32 v157, v157, v163
	v_sub_f32_e32 v163, v122, v164
	v_add_f32_e32 v161, v165, v173
	v_sub_f32_e32 v165, v123, v164
	v_sub_f32_e32 v173, v124, v164
	v_mul_f32_e32 v163, 0x3fb8aa3b, v163
	v_mul_f32_e32 v165, 0x3fb8aa3b, v165
	v_mul_f32_e32 v173, 0x3fb8aa3b, v173
	v_mul_f32_e32 v176, 0x3fb8aa3b, v176
	v_exp_f32_e32 v163, v163
	v_exp_f32_e32 v165, v165
	v_exp_f32_e32 v173, v173
	v_exp_f32_e32 v176, v176
	v_add_f32_e32 v157, v157, v161
	v_add_f32_e32 v161, v163, v165
	v_sub_f32_e32 v165, v118, v164
	v_add_f32_e32 v163, v173, v176
	v_sub_f32_e32 v173, v119, v164
	v_sub_f32_e32 v176, v120, v164
	v_sub_f32_e32 v177, v121, v164
	v_mul_f32_e32 v165, 0x3fb8aa3b, v165
	v_mul_f32_e32 v173, 0x3fb8aa3b, v173
	v_mul_f32_e32 v176, 0x3fb8aa3b, v176
	v_mul_f32_e32 v177, 0x3fb8aa3b, v177
	v_exp_f32_e32 v165, v165
	v_exp_f32_e32 v173, v173
	v_exp_f32_e32 v176, v176
	v_exp_f32_e32 v177, v177
	v_add_f32_e32 v157, 0, v157
	v_add_f32_e32 v161, v161, v163
	v_add_f32_e32 v157, v161, v157
	v_add_f32_e32 v161, v165, v173
	v_add_f32_e32 v163, v176, v177
	v_sub_f32_e32 v165, v114, v164
	v_sub_f32_e32 v173, v115, v164
	v_sub_f32_e32 v176, v116, v164
	v_sub_f32_e32 v177, v117, v164
	v_mul_f32_e32 v165, 0x3fb8aa3b, v165
	v_mul_f32_e32 v173, 0x3fb8aa3b, v173
	v_mul_f32_e32 v176, 0x3fb8aa3b, v176
	v_mul_f32_e32 v177, 0x3fb8aa3b, v177
	v_exp_f32_e32 v165, v165
	v_exp_f32_e32 v173, v173
	v_exp_f32_e32 v176, v176
	v_exp_f32_e32 v177, v177
	v_add_f32_e32 v161, v161, v163
	v_add_f32_e32 v157, v161, v157
	v_add_f32_e32 v161, v165, v173
	v_add_f32_e32 v163, v176, v177
	v_add_f32_e32 v161, v161, v163
	v_add_f32_e32 v163, v161, v157
	ds_bpermute_b32 v165, v171, v163
	v_mov_b32_e32 v157, v160
	v_pk_add_f32 v[156:157], v[156:157], v[174:175]
	ds_bpermute_b32 v151, v172, v149
	ds_bpermute_b32 v150, v172, v148
	s_waitcnt lgkmcnt(0)
	v_add_f32_e32 v163, v163, v165
	ds_bpermute_b32 v161, v172, v157
	ds_bpermute_b32 v160, v172, v156
	ds_bpermute_b32 v165, v172, v163
	v_cmp_gt_f32_e32 vcc, s88, v162
	v_add_u32_e32 v173, s45, v168
	s_and_saveexec_b64 s[4:5], s[38:39]
	s_cbranch_execz .LBB0_464
	s_waitcnt lgkmcnt(0)
	v_add_f32_e32 v165, v163, v165
	ds_write_b64 v173, v[164:165]

.LBB0_509:
	v_readlane_b32 s68, v253, 7
	v_writelane_b32 v255, s38, 29
	s_lshl_b64 s[6:7], s[38:39], 2
	v_readlane_b32 s78, v253, 17
	v_readlane_b32 s69, v253, 8
	v_readlane_b32 s79, v253, 18
	s_add_u32 s68, s78, s6
	v_readlane_b32 s70, v253, 9
	v_readlane_b32 s82, v253, 21
	s_addc_u32 s69, s79, s7
	v_readlane_b32 s71, v253, 10
	v_readlane_b32 s83, v253, 22
	s_add_u32 s70, s82, s6
	v_mov_b32_e32 v141, v0
	s_addc_u32 s71, s83, s7
	s_add_i32 m0, s12, 0x17f80
	v_lshl_add_u64 v[18:19], v[2:3], 0, v[140:141]
	v_mov_b32_e32 v145, v0
	s_waitcnt vmcnt(4)
	s_barrier
	global_load_lds_dwordx4 v[4:5], off offset:128
	s_add_i32 m0, s12, 0x19f80
	s_add_i32 s54, s12, 0x8000
	v_lshl_add_u64 v[20:21], v[2:3], 0, v[144:145]
	global_load_lds_dwordx4 v[6:7], off offset:128
	s_add_i32 m0, s54, 0xffffff80
	s_add_i32 s2, s12, 0xa000
	global_load_lds_dwordx4 v[18:19], off offset:128
	s_add_i32 m0, s2, 0xffffff80
	s_lshl_b32 s0, s0, 5
	global_load_lds_dwordx4 v[20:21], off offset:128
	s_add_i32 m0, s12, 0x1bf80
	global_load_lds_dwordx4 v[8:9], off offset:128
	s_add_i32 m0, s12, 0x1df80
	s_and_b32 s0, s0, 0x60
	global_load_lds_dwordx4 v[10:11], off offset:128
	v_lshrrev_b32_e32 v5, 1, v1
	v_and_b32_e32 v5, 24, v5
	v_and_b32_e32 v4, 15, v1
	v_lshlrev_b32_e32 v6, 1, v5
	v_lshlrev_b32_e32 v1, 2, v1
	v_lshl_or_b32 v166, s1, 6, v4
	v_lshl_or_b32 v4, v4, 6, v6
	s_lshl_b32 s1, s1, 13
	v_and_b32_e32 v1, 32, v1
	v_bitop3_b32 v6, v4, s1, v1 bitop3:0xde
	s_lshl_b32 s1, s0, 7
	s_lshl_b32 s22, s16, 3
	v_bitop3_b32 v167, v4, s1, v1 bitop3:0xde
	v_cvt_f32_u32_e32 v1, s22
	v_or_b32_e32 v148, s0, v5
	s_sub_i32 s0, 0, s22
	s_waitcnt vmcnt(6)
	v_rcp_iflag_f32_e32 v1, v1
	v_mov_b32_e32 v5, v0
	v_readlane_b32 s72, v253, 11
	v_readlane_b32 s73, v253, 12
	v_mul_f32_e32 v1, 0x4f7ffffe, v1
	v_cvt_u32_f32_e32 v1, v1
	v_readlane_b32 s52, v250, 49
	v_writelane_b32 v255, s39, 30
	s_mov_b32 s65, s16
	v_readfirstlane_b32 s1, v1
	v_add_u32_e32 v1, v14, v12
	s_mul_i32 s0, s0, s1
	v_add_lshl_u32 v4, v1, v13, 1
	v_add_u32_e32 v1, v17, v15
	s_mul_hi_u32 s0, s1, s0
	v_lshl_add_u64 v[150:151], s[94:95], 0, v[4:5]
	v_add_lshl_u32 v4, v1, v16, 1
	s_add_i32 s23, s13, -2
	s_ashr_i32 s28, s37, 31
	s_ashr_i32 s29, s14, 31
	s_mov_b32 s25, s95
	s_lshr_b32 s72, s24, 3
	s_mov_b32 s90, 0
	s_add_i32 s73, s1, s0
	v_mov_b32_e32 v149, v0
	v_lshl_add_u64 v[152:153], s[94:95], 0, v[4:5]
	v_add_u32_e32 v168, 0, v6
	s_movk_i32 s89, 0x900
	v_readlane_b32 s53, v250, 50
	s_mov_b32 s16, 0xbf1b459e
	v_readlane_b32 s74, v253, 13
	v_readlane_b32 s75, v253, 14
	v_readlane_b32 s76, v253, 15
	v_readlane_b32 s77, v253, 16
	v_readlane_b32 s80, v253, 19
	v_readlane_b32 s81, v253, 20
	s_barrier
	s_branch .LBB0_512

.LBB0_519:
	s_add_i32 s10, s4, 2
	s_add_i32 s11, 0, 0x10000
	s_cmp_eq_u32 s23, s4
	v_lshl_add_u64 v[100:101], v[2:3], 0, s[84:85]
	s_cselect_b64 vcc, -1, 0
	v_add_u32_e32 v1, s11, v167
	v_cndmask_b32_e32 v157, v101, v155, vcc
	v_cndmask_b32_e32 v156, v100, v154, vcc
	ds_read_b128 v[100:103], v1
	ds_read_b128 v[104:107], v1 offset:1024
	ds_read_b128 v[160:163], v1 offset:2048
	ds_read_b128 v[170:173], v1 offset:3072
	s_cselect_b32 s4, s0, s6
	s_cselect_b32 s5, s1, s7
	v_lshl_add_u64 v[164:165], v[2:3], 0, v[150:151]
	s_add_i32 m0, s12, 0xc000
	ds_read_b128 v[174:177], v168
	ds_read_b128 v[178:181], v168 offset:1024
	ds_read_b128 v[182:185], v168 offset:2048
	ds_read_b128 v[186:189], v168 offset:3072
	ds_read_b128 v[190:193], v168 offset:4096
	ds_read_b128 v[194:197], v168 offset:5120
	ds_read_b128 v[198:201], v168 offset:6144
	ds_read_b128 v[202:205], v168 offset:7168
	global_load_lds_dwordx4 v[164:165], off
	v_lshl_add_u64 v[164:165], v[2:3], 0, v[152:153]
	s_add_i32 m0, s12, 0xe000
	s_nop 0
	global_load_lds_dwordx4 v[164:165], off
	s_waitcnt lgkmcnt(8)
	s_barrier
	s_waitcnt lgkmcnt(0)
	s_waitcnt lgkmcnt(0)
	v_mfma_f32_16x16x32_bf16 v[136:139], v[100:103], v[174:177], v[136:139]
	v_mfma_f32_16x16x32_bf16 v[132:135], v[160:163], v[174:177], v[132:135]
	v_mfma_f32_16x16x32_bf16 v[128:131], v[100:103], v[182:185], v[128:131]
	v_mfma_f32_16x16x32_bf16 v[124:127], v[160:163], v[182:185], v[124:127]
	v_mfma_f32_16x16x32_bf16 v[120:123], v[100:103], v[190:193], v[120:123]
	v_mfma_f32_16x16x32_bf16 v[116:119], v[160:163], v[190:193], v[116:119]
	v_mfma_f32_16x16x32_bf16 v[112:115], v[100:103], v[198:201], v[112:115]
	v_mfma_f32_16x16x32_bf16 v[108:111], v[160:163], v[198:201], v[108:111]
	v_mfma_f32_16x16x32_bf16 v[136:139], v[104:107], v[178:181], v[136:139]
	v_mfma_f32_16x16x32_bf16 v[132:135], v[170:173], v[178:181], v[132:135]
	v_mfma_f32_16x16x32_bf16 v[128:131], v[104:107], v[186:189], v[128:131]
	v_mfma_f32_16x16x32_bf16 v[124:127], v[170:173], v[186:189], v[124:127]
	v_mfma_f32_16x16x32_bf16 v[120:123], v[104:107], v[194:197], v[120:123]
	v_mfma_f32_16x16x32_bf16 v[116:119], v[170:173], v[194:197], v[116:119]
	v_mfma_f32_16x16x32_bf16 v[112:115], v[104:107], v[202:205], v[112:115]
	v_mfma_f32_16x16x32_bf16 v[108:111], v[170:173], v[202:205], v[108:111]
	s_barrier
	s_add_i32 s17, 0, 0x14000
	s_add_i32 s11, s11, s3
	v_add_u32_e32 v1, s17, v167
	v_lshl_add_u64 v[164:165], s[4:5], 0, v[142:143]
	s_mov_b32 m0, s11
	ds_read_b128 v[206:209], v1
	ds_read_b128 v[210:213], v1 offset:1024
	ds_read_b128 v[214:217], v1 offset:2048
	ds_read_b128 v[238:241], v1 offset:3072
	global_load_lds_dwordx4 v[164:165], off
	v_lshl_add_u64 v[218:219], s[4:5], 0, v[146:147]
	s_add_i32 m0, s11, 0x2000
	s_nop 0
	global_load_lds_dwordx4 v[218:219], off
	s_barrier
	s_waitcnt lgkmcnt(0)
	s_waitcnt lgkmcnt(0)
	v_mfma_f32_16x16x32_bf16 v[64:67], v[206:209], v[174:177], v[64:67]
	v_mfma_f32_16x16x32_bf16 v[60:63], v[214:217], v[174:177], v[60:63]
	v_mfma_f32_16x16x32_bf16 v[56:59], v[206:209], v[182:185], v[56:59]
	v_mfma_f32_16x16x32_bf16 v[52:55], v[214:217], v[182:185], v[52:55]
	v_mfma_f32_16x16x32_bf16 v[48:51], v[206:209], v[190:193], v[48:51]
	v_mfma_f32_16x16x32_bf16 v[44:47], v[214:217], v[190:193], v[44:47]
	v_mfma_f32_16x16x32_bf16 v[40:43], v[206:209], v[198:201], v[40:43]
	v_mfma_f32_16x16x32_bf16 v[36:39], v[214:217], v[198:201], v[36:39]
	v_mfma_f32_16x16x32_bf16 v[64:67], v[210:213], v[178:181], v[64:67]
	v_mfma_f32_16x16x32_bf16 v[60:63], v[238:241], v[178:181], v[60:63]
	v_mfma_f32_16x16x32_bf16 v[56:59], v[210:213], v[186:189], v[56:59]
	v_mfma_f32_16x16x32_bf16 v[52:55], v[238:241], v[186:189], v[52:55]
	v_mfma_f32_16x16x32_bf16 v[48:51], v[210:213], v[194:197], v[48:51]
	v_mfma_f32_16x16x32_bf16 v[44:47], v[238:241], v[194:197], v[44:47]
	v_mfma_f32_16x16x32_bf16 v[40:43], v[210:213], v[202:205], v[40:43]
	v_mfma_f32_16x16x32_bf16 v[36:39], v[238:241], v[202:205], v[36:39]
	s_mov_b32 m0, s12
	v_lshl_add_u64 v[224:225], v[156:157], 0, v[140:141]
	s_barrier
	ds_read_b128 v[174:177], v168 offset:16384
	ds_read_b128 v[178:181], v168 offset:17408
	ds_read_b128 v[182:185], v168 offset:18432
	ds_read_b128 v[186:189], v168 offset:19456
	ds_read_b128 v[190:193], v168 offset:20480
	ds_read_b128 v[194:197], v168 offset:21504
	ds_read_b128 v[198:201], v168 offset:22528
	ds_read_b128 v[202:205], v168 offset:23552
	global_load_lds_dwordx4 v[224:225], off
	v_lshl_add_u64 v[230:231], v[156:157], 0, v[144:145]
	s_mov_b32 m0, s35
	s_nop 0
	global_load_lds_dwordx4 v[230:231], off
	s_barrier
	s_waitcnt lgkmcnt(0)
	s_waitcnt lgkmcnt(0)
	v_mfma_f32_16x16x32_bf16 v[96:99], v[100:103], v[174:177], v[96:99]
	v_mfma_f32_16x16x32_bf16 v[92:95], v[160:163], v[174:177], v[92:95]
	v_mfma_f32_16x16x32_bf16 v[88:91], v[100:103], v[182:185], v[88:91]
	v_mfma_f32_16x16x32_bf16 v[84:87], v[160:163], v[182:185], v[84:87]
	v_mfma_f32_16x16x32_bf16 v[80:83], v[100:103], v[190:193], v[80:83]
	v_mfma_f32_16x16x32_bf16 v[76:79], v[160:163], v[190:193], v[76:79]
	v_mfma_f32_16x16x32_bf16 v[72:75], v[100:103], v[198:201], v[72:75]
	v_mfma_f32_16x16x32_bf16 v[68:71], v[160:163], v[198:201], v[68:71]
	v_mfma_f32_16x16x32_bf16 v[96:99], v[104:107], v[178:181], v[96:99]
	v_mfma_f32_16x16x32_bf16 v[92:95], v[170:173], v[178:181], v[92:95]
	v_mfma_f32_16x16x32_bf16 v[88:91], v[104:107], v[186:189], v[88:91]
	v_mfma_f32_16x16x32_bf16 v[84:87], v[170:173], v[186:189], v[84:87]
	v_mfma_f32_16x16x32_bf16 v[80:83], v[104:107], v[194:197], v[80:83]
	v_mfma_f32_16x16x32_bf16 v[76:79], v[170:173], v[194:197], v[76:79]
	v_mfma_f32_16x16x32_bf16 v[72:75], v[104:107], v[202:205], v[72:75]
	v_mfma_f32_16x16x32_bf16 v[68:71], v[170:173], v[202:205], v[68:71]
	s_barrier
	s_add_u32 s4, s4, s94
	s_addc_u32 s5, s5, 0
	s_add_i32 s11, s17, s3
	v_lshl_add_u64 v[232:233], s[4:5], 0, v[142:143]
	s_mov_b32 m0, s11
	v_lshl_add_u64 v[242:243], s[4:5], 0, v[146:147]
	global_load_lds_dwordx4 v[232:233], off
	s_add_i32 m0, s11, 0x2000
	s_nop 0
	global_load_lds_dwordx4 v[242:243], off
	s_waitcnt vmcnt(6)
	s_barrier
	v_mfma_f32_16x16x32_bf16 v[32:35], v[206:209], v[174:177], v[32:35]
	v_mfma_f32_16x16x32_bf16 v[28:31], v[214:217], v[174:177], v[28:31]
	v_mfma_f32_16x16x32_bf16 v[24:27], v[206:209], v[182:185], v[24:27]
	v_mfma_f32_16x16x32_bf16 v[20:23], v[214:217], v[182:185], v[20:23]
	v_mfma_f32_16x16x32_bf16 v[16:19], v[206:209], v[190:193], v[16:19]
	v_mfma_f32_16x16x32_bf16 v[12:15], v[214:217], v[190:193], v[12:15]
	v_mfma_f32_16x16x32_bf16 v[8:11], v[206:209], v[198:201], v[8:11]
	v_mfma_f32_16x16x32_bf16 v[4:7], v[214:217], v[198:201], v[4:7]
	v_mfma_f32_16x16x32_bf16 v[32:35], v[210:213], v[178:181], v[32:35]
	v_mfma_f32_16x16x32_bf16 v[28:31], v[238:241], v[178:181], v[28:31]
	v_mfma_f32_16x16x32_bf16 v[24:27], v[210:213], v[186:189], v[24:27]
	v_mfma_f32_16x16x32_bf16 v[20:23], v[238:241], v[186:189], v[20:23]
	v_mfma_f32_16x16x32_bf16 v[16:19], v[210:213], v[194:197], v[16:19]
	v_mfma_f32_16x16x32_bf16 v[12:15], v[238:241], v[194:197], v[12:15]
	v_mfma_f32_16x16x32_bf16 v[8:11], v[210:213], v[202:205], v[8:11]
	v_mfma_f32_16x16x32_bf16 v[4:7], v[238:241], v[202:205], v[4:7]
	s_add_i32 s4, 0, 0x18000
	v_add_u32_e32 v1, s4, v167
	s_barrier
	ds_read_b128 v[100:103], v1
	ds_read_b128 v[104:107], v1 offset:1024
	ds_read_b128 v[160:163], v1 offset:2048
	ds_read_b128 v[170:173], v1 offset:3072
	v_lshl_add_u64 v[156:157], v[156:157], 0, s[94:95]
	s_mov_b32 m0, s44
	v_lshl_add_u64 v[206:207], v[156:157], 0, v[140:141]
	ds_read_b128 v[174:177], v168 offset:32768
	ds_read_b128 v[178:181], v168 offset:33792
	ds_read_b128 v[182:185], v168 offset:34816
	ds_read_b128 v[186:189], v168 offset:35840
	ds_read_b128 v[190:193], v168 offset:36864
	ds_read_b128 v[194:197], v168 offset:37888
	ds_read_b128 v[198:201], v168 offset:38912
	ds_read_b128 v[202:205], v168 offset:39936
	global_load_lds_dwordx4 v[206:207], off
	v_lshl_add_u64 v[156:157], v[156:157], 0, v[144:145]
	s_mov_b32 m0, s45
	s_nop 0
	global_load_lds_dwordx4 v[156:157], off
	s_waitcnt lgkmcnt(8)
	s_barrier
	s_waitcnt lgkmcnt(0)
	s_waitcnt lgkmcnt(0)
	v_mfma_f32_16x16x32_bf16 v[136:139], v[100:103], v[174:177], v[136:139]
	v_mfma_f32_16x16x32_bf16 v[132:135], v[160:163], v[174:177], v[132:135]
	v_mfma_f32_16x16x32_bf16 v[128:131], v[100:103], v[182:185], v[128:131]
	v_mfma_f32_16x16x32_bf16 v[124:127], v[160:163], v[182:185], v[124:127]
	v_mfma_f32_16x16x32_bf16 v[120:123], v[100:103], v[190:193], v[120:123]
	v_mfma_f32_16x16x32_bf16 v[116:119], v[160:163], v[190:193], v[116:119]
	v_mfma_f32_16x16x32_bf16 v[112:115], v[100:103], v[198:201], v[112:115]
	v_mfma_f32_16x16x32_bf16 v[108:111], v[160:163], v[198:201], v[108:111]
	v_mfma_f32_16x16x32_bf16 v[136:139], v[104:107], v[178:181], v[136:139]
	v_mfma_f32_16x16x32_bf16 v[132:135], v[170:173], v[178:181], v[132:135]
	v_mfma_f32_16x16x32_bf16 v[128:131], v[104:107], v[186:189], v[128:131]
	v_mfma_f32_16x16x32_bf16 v[124:127], v[170:173], v[186:189], v[124:127]
	v_mfma_f32_16x16x32_bf16 v[120:123], v[104:107], v[194:197], v[120:123]
	v_mfma_f32_16x16x32_bf16 v[116:119], v[170:173], v[194:197], v[116:119]
	v_mfma_f32_16x16x32_bf16 v[112:115], v[104:107], v[202:205], v[112:115]
	v_mfma_f32_16x16x32_bf16 v[108:111], v[170:173], v[202:205], v[108:111]
	s_barrier
	s_add_i32 s5, 0, 0x1c000
	s_add_i32 s4, s4, s3
	v_add_u32_e32 v1, s5, v167
	s_add_i32 m0, s4, 0xffffff80
	ds_read_b128 v[206:209], v1
	ds_read_b128 v[210:213], v1 offset:1024
	ds_read_b128 v[214:217], v1 offset:2048
	ds_read_b128 v[238:241], v1 offset:3072
	global_load_lds_dwordx4 v[164:165], off offset:128
	s_add_i32 m0, s4, 0x1f80
	s_nop 0
	global_load_lds_dwordx4 v[218:219], off offset:128
	s_barrier
	s_waitcnt lgkmcnt(0)
	s_waitcnt lgkmcnt(0)
	v_mfma_f32_16x16x32_bf16 v[64:67], v[206:209], v[174:177], v[64:67]
	v_mfma_f32_16x16x32_bf16 v[60:63], v[214:217], v[174:177], v[60:63]
	v_mfma_f32_16x16x32_bf16 v[56:59], v[206:209], v[182:185], v[56:59]
	v_mfma_f32_16x16x32_bf16 v[52:55], v[214:217], v[182:185], v[52:55]
	v_mfma_f32_16x16x32_bf16 v[48:51], v[206:209], v[190:193], v[48:51]
	v_mfma_f32_16x16x32_bf16 v[44:47], v[214:217], v[190:193], v[44:47]
	v_mfma_f32_16x16x32_bf16 v[40:43], v[206:209], v[198:201], v[40:43]
	v_mfma_f32_16x16x32_bf16 v[36:39], v[214:217], v[198:201], v[36:39]
	v_mfma_f32_16x16x32_bf16 v[64:67], v[210:213], v[178:181], v[64:67]
	v_mfma_f32_16x16x32_bf16 v[60:63], v[238:241], v[178:181], v[60:63]
	v_mfma_f32_16x16x32_bf16 v[56:59], v[210:213], v[186:189], v[56:59]
	v_mfma_f32_16x16x32_bf16 v[52:55], v[238:241], v[186:189], v[52:55]
	v_mfma_f32_16x16x32_bf16 v[48:51], v[210:213], v[194:197], v[48:51]
	v_mfma_f32_16x16x32_bf16 v[44:47], v[238:241], v[194:197], v[44:47]
	v_mfma_f32_16x16x32_bf16 v[40:43], v[210:213], v[202:205], v[40:43]
	v_mfma_f32_16x16x32_bf16 v[36:39], v[238:241], v[202:205], v[36:39]
	s_add_i32 m0, s54, 0xffffff80
	s_barrier
	ds_read_b128 v[174:177], v168 offset:49152
	ds_read_b128 v[178:181], v168 offset:50176
	ds_read_b128 v[182:185], v168 offset:51200
	ds_read_b128 v[186:189], v168 offset:52224
	ds_read_b128 v[190:193], v168 offset:53248
	ds_read_b128 v[194:197], v168 offset:54272
	ds_read_b128 v[198:201], v168 offset:55296
	ds_read_b128 v[202:205], v168 offset:56320
	global_load_lds_dwordx4 v[224:225], off offset:128
	s_add_i32 m0, s2, 0xffffff80
	s_nop 0
	global_load_lds_dwordx4 v[230:231], off offset:128
	s_barrier
	s_waitcnt lgkmcnt(0)
	s_waitcnt lgkmcnt(0)
	v_mfma_f32_16x16x32_bf16 v[96:99], v[100:103], v[174:177], v[96:99]
	v_mfma_f32_16x16x32_bf16 v[92:95], v[160:163], v[174:177], v[92:95]
	v_mfma_f32_16x16x32_bf16 v[88:91], v[100:103], v[182:185], v[88:91]
	v_mfma_f32_16x16x32_bf16 v[84:87], v[160:163], v[182:185], v[84:87]
	v_mfma_f32_16x16x32_bf16 v[80:83], v[100:103], v[190:193], v[80:83]
	v_mfma_f32_16x16x32_bf16 v[76:79], v[160:163], v[190:193], v[76:79]
	v_mfma_f32_16x16x32_bf16 v[72:75], v[100:103], v[198:201], v[72:75]
	v_mfma_f32_16x16x32_bf16 v[68:71], v[160:163], v[198:201], v[68:71]
	v_mfma_f32_16x16x32_bf16 v[96:99], v[104:107], v[178:181], v[96:99]
	v_mfma_f32_16x16x32_bf16 v[92:95], v[170:173], v[178:181], v[92:95]
	v_mfma_f32_16x16x32_bf16 v[88:91], v[104:107], v[186:189], v[88:91]
	v_mfma_f32_16x16x32_bf16 v[84:87], v[170:173], v[186:189], v[84:87]
	v_mfma_f32_16x16x32_bf16 v[80:83], v[104:107], v[194:197], v[80:83]
	v_mfma_f32_16x16x32_bf16 v[76:79], v[170:173], v[194:197], v[76:79]
	v_mfma_f32_16x16x32_bf16 v[72:75], v[104:107], v[202:205], v[72:75]
	v_mfma_f32_16x16x32_bf16 v[68:71], v[170:173], v[202:205], v[68:71]
	s_barrier
	s_add_i32 s4, s5, s3
	s_add_i32 m0, s4, 0xffffff80
	s_nop 0
	global_load_lds_dwordx4 v[232:233], off offset:128
	s_add_i32 m0, s4, 0x1f80
	s_nop 0
	global_load_lds_dwordx4 v[242:243], off offset:128
	s_waitcnt vmcnt(6)
	s_barrier
	v_mfma_f32_16x16x32_bf16 v[32:35], v[206:209], v[174:177], v[32:35]
	v_mfma_f32_16x16x32_bf16 v[28:31], v[214:217], v[174:177], v[28:31]
	v_mfma_f32_16x16x32_bf16 v[24:27], v[206:209], v[182:185], v[24:27]
	v_mfma_f32_16x16x32_bf16 v[20:23], v[214:217], v[182:185], v[20:23]
	v_mfma_f32_16x16x32_bf16 v[16:19], v[206:209], v[190:193], v[16:19]
	v_mfma_f32_16x16x32_bf16 v[12:15], v[214:217], v[190:193], v[12:15]
	v_mfma_f32_16x16x32_bf16 v[8:11], v[206:209], v[198:201], v[8:11]
	v_mfma_f32_16x16x32_bf16 v[4:7], v[214:217], v[198:201], v[4:7]
	v_mfma_f32_16x16x32_bf16 v[32:35], v[210:213], v[178:181], v[32:35]
	v_mfma_f32_16x16x32_bf16 v[28:31], v[238:241], v[178:181], v[28:31]
	v_mfma_f32_16x16x32_bf16 v[24:27], v[210:213], v[186:189], v[24:27]
	v_mfma_f32_16x16x32_bf16 v[20:23], v[238:241], v[186:189], v[20:23]
	v_mfma_f32_16x16x32_bf16 v[16:19], v[210:213], v[194:197], v[16:19]
	v_mfma_f32_16x16x32_bf16 v[12:15], v[238:241], v[194:197], v[12:15]
	v_mfma_f32_16x16x32_bf16 v[8:11], v[210:213], v[202:205], v[8:11]
	v_mfma_f32_16x16x32_bf16 v[4:7], v[238:241], v[202:205], v[4:7]
	s_add_u32 s6, s6, 0x100
	s_addc_u32 s7, s7, 0
	v_lshl_add_u64 v[2:3], v[2:3], 0, s[86:87]
	s_cmp_ge_u32 s10, s13
	s_mov_b32 s4, s10
	s_barrier
	s_cbranch_scc0 .LBB0_519
	s_lshl_b32 s4, s8, 8
	v_lshl_add_u32 v169, s9, 8, v166
	s_cmp_lt_i32 s8, 5
	s_movk_i32 s96, 0x180
	s_cbranch_scc0 .LBB0_575
	s_add_i32 s5, s4, 0x17f
	s_cmpk_gt_u32 s5, 0x2fe
	v_or_b32_e32 v156, s4, v148
	s_cselect_b64 s[6:7], -1, 0
	s_and_b64 vcc, exec, s[6:7]
	v_ashrrev_i32_e32 v157, 31, v156
	s_cbranch_vccnz .LBB0_523
	v_lshl_add_u64 v[2:3], v[156:157], 2, s[68:69]
	global_load_dwordx4 v[100:103], v[2:3], off offset:16
	global_load_dwordx4 v[104:107], v[2:3], off
	s_branch .LBB0_524

.LBB0_640:
	s_cmp_eq_u32 s97, 0
	v_mov_b32_e32 v161, v0
	s_cselect_b64 vcc, -1, 0
	s_add_i32 m0, s8, 0x17f80
	v_lshl_add_u64 v[20:21], v[2:3], 0, v[160:161]
	v_mov_b32_e32 v165, v0
	s_waitcnt vmcnt(4)
	s_barrier
	global_load_lds_dwordx4 v[4:5], off offset:128
	s_add_i32 m0, s8, 0x19f80
	s_add_i32 s12, s8, 0x8000
	v_lshl_add_u64 v[22:23], v[2:3], 0, v[164:165]
	global_load_lds_dwordx4 v[6:7], off offset:128
	s_add_i32 m0, s12, 0xffffff80
	s_add_i32 s28, s8, 0xa000
	global_load_lds_dwordx4 v[20:21], off offset:128
	s_add_i32 m0, s28, 0xffffff80
	s_and_b32 s0, s0, 3
	global_load_lds_dwordx4 v[22:23], off offset:128
	s_add_i32 m0, s8, 0x1bf80
	global_load_lds_dwordx4 v[8:9], off offset:128
	s_add_i32 m0, s8, 0x1df80
	v_lshlrev_b32_e32 v8, 2, v12
	global_load_lds_dwordx4 v[10:11], off offset:128
	v_bfe_u32 v4, v12, 4, 2
	v_and_b32_e32 v5, 15, v12
	v_lshlrev_b32_e32 v7, 4, v4
	s_lshl_b32 s2, s1, 6
	v_lshl_or_b32 v7, v5, 6, v7
	s_lshl_b32 s1, s1, 13
	v_and_b32_e32 v8, 32, v8
	v_bitop3_b32 v9, v7, s1, v8 bitop3:0xde
	s_lshl_b32 s1, s0, 12
	v_bitop3_b32 v237, v7, s1, v8 bitop3:0xde
	s_add_i32 s1, s2, 0x80
	v_lshlrev_b32_e32 v6, 3, v4
	v_cmp_eq_u32_e64 s[38:39], 0, v4
	v_or_b32_e32 v4, s1, v5
	v_lshlrev_b32_e32 v240, 4, v4
	v_lshl_or_b32 v4, s0, 4, v5
	s_lshl_b32 s44, s16, 3
	v_or_b32_e32 v241, s2, v4
	v_cvt_f32_u32_e32 v4, s44
	v_mov_b32_e32 v1, s36
	v_lshl_or_b32 v238, s0, 5, v6
	s_lshl_b32 s0, s0, 2
	v_rcp_iflag_f32_e32 v4, v4
	v_cndmask_b32_e32 v168, 0, v1, vcc
	v_or_b32_e32 v1, s2, v5
	s_add_i32 s90, s0, 0
	v_mul_f32_e32 v4, 0x4f7ffffe, v4
	v_cvt_u32_f32_e32 v4, v4
	s_sub_i32 s0, 0, s44
	v_mov_b32_e32 v5, v0
	s_waitcnt vmcnt(6)
	v_readfirstlane_b32 s1, v4
	v_add_u32_e32 v4, v15, v13
	v_add_lshl_u32 v4, v4, v14, 1
	s_mul_i32 s0, s0, s1
	v_lshl_add_u64 v[172:173], s[94:95], 0, v[4:5]
	v_add_u32_e32 v4, v18, v16
	s_mul_hi_u32 s0, s1, s0
	v_add_lshl_u32 v4, v4, v17, 1
	s_mov_b32 s29, 0
	s_add_i32 s35, s13, -2
	v_lshlrev_b32_e32 v239, 4, v1
	v_add_u32_e32 v242, 0x80, v241
	s_ashr_i32 s36, s37, 31
	s_ashr_i32 s45, s14, 31
	s_mov_b32 s25, s95
	s_lshr_b32 s54, s24, 3
	v_mov_b32_e32 v170, v168
	v_mov_b32_e32 v171, v168
	s_add_i32 s90, s90, 0x20000
	s_add_i32 s91, s1, s0
	v_lshl_add_u64 v[174:175], s[94:95], 0, v[4:5]
	v_add_u32_e32 v243, 0, v9
	s_barrier
	s_branch .LBB0_642

.LBB0_649:
	s_add_i32 s42, s4, 2
	s_add_i32 s43, 0, 0x10000
	s_cmp_eq_u32 s35, s4
	v_lshl_add_u64 v[132:133], v[130:131], 0, s[84:85]
	s_cselect_b64 vcc, -1, 0
	v_add_u32_e32 v144, s43, v237
	v_cndmask_b32_e32 v157, v133, v177, vcc
	v_cndmask_b32_e32 v156, v132, v176, vcc
	ds_read_b128 v[132:135], v144
	ds_read_b128 v[136:139], v144 offset:1024
	ds_read_b128 v[140:143], v144 offset:2048
	ds_read_b128 v[144:147], v144 offset:3072
	s_cselect_b32 s4, s0, s6
	s_cselect_b32 s5, s1, s7
	v_lshl_add_u64 v[202:203], v[130:131], 0, v[172:173]
	s_add_i32 m0, s8, 0xc000
	ds_read_b128 v[148:151], v243
	ds_read_b128 v[152:155], v243 offset:1024
	ds_read_b128 v[178:181], v243 offset:2048
	ds_read_b128 v[182:185], v243 offset:3072
	ds_read_b128 v[186:189], v243 offset:4096
	ds_read_b128 v[190:193], v243 offset:5120
	ds_read_b128 v[194:197], v243 offset:6144
	ds_read_b128 v[198:201], v243 offset:7168
	global_load_lds_dwordx4 v[202:203], off
	v_lshl_add_u64 v[202:203], v[130:131], 0, v[174:175]
	s_add_i32 m0, s8, 0xe000
	s_nop 0
	global_load_lds_dwordx4 v[202:203], off
	s_waitcnt lgkmcnt(8)
	s_barrier
	s_waitcnt lgkmcnt(0)
	s_waitcnt lgkmcnt(0)
	v_mfma_f32_16x16x32_bf16 v[126:129], v[132:135], v[148:151], v[126:129]
	v_mfma_f32_16x16x32_bf16 v[122:125], v[140:143], v[148:151], v[122:125]
	v_mfma_f32_16x16x32_bf16 v[110:113], v[132:135], v[178:181], v[110:113]
	v_mfma_f32_16x16x32_bf16 v[106:109], v[140:143], v[178:181], v[106:109]
	v_mfma_f32_16x16x32_bf16 v[98:101], v[132:135], v[186:189], v[98:101]
	v_mfma_f32_16x16x32_bf16 v[90:93], v[140:143], v[186:189], v[90:93]
	v_mfma_f32_16x16x32_bf16 v[82:85], v[132:135], v[194:197], v[82:85]
	v_mfma_f32_16x16x32_bf16 v[74:77], v[140:143], v[194:197], v[74:77]
	v_mfma_f32_16x16x32_bf16 v[126:129], v[136:139], v[152:155], v[126:129]
	v_mfma_f32_16x16x32_bf16 v[122:125], v[144:147], v[152:155], v[122:125]
	v_mfma_f32_16x16x32_bf16 v[110:113], v[136:139], v[182:185], v[110:113]
	v_mfma_f32_16x16x32_bf16 v[106:109], v[144:147], v[182:185], v[106:109]
	v_mfma_f32_16x16x32_bf16 v[98:101], v[136:139], v[190:193], v[98:101]
	v_mfma_f32_16x16x32_bf16 v[90:93], v[144:147], v[190:193], v[90:93]
	v_mfma_f32_16x16x32_bf16 v[82:85], v[136:139], v[198:201], v[82:85]
	v_mfma_f32_16x16x32_bf16 v[74:77], v[144:147], v[198:201], v[74:77]
	s_barrier
	s_add_i32 s89, 0, 0x14000
	s_add_i32 s43, s43, s3
	v_add_u32_e32 v169, s89, v237
	v_lshl_add_u64 v[218:219], s[4:5], 0, v[162:163]
	s_mov_b32 m0, s43
	ds_read_b128 v[202:205], v169
	ds_read_b128 v[206:209], v169 offset:1024
	ds_read_b128 v[210:213], v169 offset:2048
	ds_read_b128 v[214:217], v169 offset:3072
	global_load_lds_dwordx4 v[218:219], off
	v_lshl_add_u64 v[224:225], s[4:5], 0, v[166:167]
	s_add_i32 m0, s43, 0x2000
	s_nop 0
	global_load_lds_dwordx4 v[224:225], off
	s_barrier
	s_waitcnt lgkmcnt(0)
	s_waitcnt lgkmcnt(0)
	v_mfma_f32_16x16x32_bf16 v[118:121], v[202:205], v[148:151], v[118:121]
	v_mfma_f32_16x16x32_bf16 v[114:117], v[210:213], v[148:151], v[114:117]
	v_mfma_f32_16x16x32_bf16 v[102:105], v[202:205], v[178:181], v[102:105]
	v_mfma_f32_16x16x32_bf16 v[94:97], v[210:213], v[178:181], v[94:97]
	v_mfma_f32_16x16x32_bf16 v[86:89], v[202:205], v[186:189], v[86:89]
	v_mfma_f32_16x16x32_bf16 v[78:81], v[210:213], v[186:189], v[78:81]
	v_mfma_f32_16x16x32_bf16 v[70:73], v[202:205], v[194:197], v[70:73]
	v_mfma_f32_16x16x32_bf16 v[66:69], v[210:213], v[194:197], v[66:69]
	v_mfma_f32_16x16x32_bf16 v[118:121], v[206:209], v[152:155], v[118:121]
	v_mfma_f32_16x16x32_bf16 v[114:117], v[214:217], v[152:155], v[114:117]
	v_mfma_f32_16x16x32_bf16 v[102:105], v[206:209], v[182:185], v[102:105]
	v_mfma_f32_16x16x32_bf16 v[94:97], v[214:217], v[182:185], v[94:97]
	v_mfma_f32_16x16x32_bf16 v[86:89], v[206:209], v[190:193], v[86:89]
	v_mfma_f32_16x16x32_bf16 v[78:81], v[214:217], v[190:193], v[78:81]
	v_mfma_f32_16x16x32_bf16 v[70:73], v[206:209], v[198:201], v[70:73]
	v_mfma_f32_16x16x32_bf16 v[66:69], v[214:217], v[198:201], v[66:69]
	s_mov_b32 m0, s8
	v_lshl_add_u64 v[230:231], v[156:157], 0, v[160:161]
	s_barrier
	ds_read_b128 v[148:151], v243 offset:16384
	ds_read_b128 v[152:155], v243 offset:17408
	ds_read_b128 v[178:181], v243 offset:18432
	ds_read_b128 v[182:185], v243 offset:19456
	ds_read_b128 v[186:189], v243 offset:20480
	ds_read_b128 v[190:193], v243 offset:21504
	ds_read_b128 v[194:197], v243 offset:22528
	ds_read_b128 v[198:201], v243 offset:23552
	global_load_lds_dwordx4 v[230:231], off
	v_lshl_add_u64 v[232:233], v[156:157], 0, v[164:165]
	s_mov_b32 m0, s9
	s_nop 0
	global_load_lds_dwordx4 v[232:233], off
	s_barrier
	s_waitcnt lgkmcnt(0)
	s_waitcnt lgkmcnt(0)
	v_mfma_f32_16x16x32_bf16 v[62:65], v[132:135], v[148:151], v[62:65]
	v_mfma_f32_16x16x32_bf16 v[58:61], v[140:143], v[148:151], v[58:61]
	v_mfma_f32_16x16x32_bf16 v[46:49], v[132:135], v[178:181], v[46:49]
	v_mfma_f32_16x16x32_bf16 v[42:45], v[140:143], v[178:181], v[42:45]
	v_mfma_f32_16x16x32_bf16 v[34:37], v[132:135], v[186:189], v[34:37]
	v_mfma_f32_16x16x32_bf16 v[26:29], v[140:143], v[186:189], v[26:29]
	v_mfma_f32_16x16x32_bf16 v[18:21], v[132:135], v[194:197], v[18:21]
	v_mfma_f32_16x16x32_bf16 v[10:13], v[140:143], v[194:197], v[10:13]
	v_mfma_f32_16x16x32_bf16 v[62:65], v[136:139], v[152:155], v[62:65]
	v_mfma_f32_16x16x32_bf16 v[58:61], v[144:147], v[152:155], v[58:61]
	v_mfma_f32_16x16x32_bf16 v[46:49], v[136:139], v[182:185], v[46:49]
	v_mfma_f32_16x16x32_bf16 v[42:45], v[144:147], v[182:185], v[42:45]
	v_mfma_f32_16x16x32_bf16 v[34:37], v[136:139], v[190:193], v[34:37]
	v_mfma_f32_16x16x32_bf16 v[26:29], v[144:147], v[190:193], v[26:29]
	v_mfma_f32_16x16x32_bf16 v[18:21], v[136:139], v[198:201], v[18:21]
	v_mfma_f32_16x16x32_bf16 v[10:13], v[144:147], v[198:201], v[10:13]
	s_barrier
	s_add_u32 s4, s4, s94
	s_addc_u32 s5, s5, 0
	s_add_i32 s43, s89, s3
	v_lshl_add_u64 v[244:245], s[4:5], 0, v[162:163]
	s_mov_b32 m0, s43
	v_lshl_add_u64 v[246:247], s[4:5], 0, v[166:167]
	global_load_lds_dwordx4 v[244:245], off
	s_add_i32 m0, s43, 0x2000
	s_nop 0
	global_load_lds_dwordx4 v[246:247], off
	s_waitcnt vmcnt(6)
	s_barrier
	v_mfma_f32_16x16x32_bf16 v[54:57], v[202:205], v[148:151], v[54:57]
	v_mfma_f32_16x16x32_bf16 v[50:53], v[210:213], v[148:151], v[50:53]
	v_mfma_f32_16x16x32_bf16 v[38:41], v[202:205], v[178:181], v[38:41]
	v_mfma_f32_16x16x32_bf16 v[30:33], v[210:213], v[178:181], v[30:33]
	v_mfma_f32_16x16x32_bf16 v[22:25], v[202:205], v[186:189], v[22:25]
	v_mfma_f32_16x16x32_bf16 v[14:17], v[210:213], v[186:189], v[14:17]
	v_mfma_f32_16x16x32_bf16 v[6:9], v[202:205], v[194:197], v[6:9]
	v_mfma_f32_16x16x32_bf16 v[2:5], v[210:213], v[194:197], v[2:5]
	v_mfma_f32_16x16x32_bf16 v[54:57], v[206:209], v[152:155], v[54:57]
	v_mfma_f32_16x16x32_bf16 v[50:53], v[214:217], v[152:155], v[50:53]
	v_mfma_f32_16x16x32_bf16 v[38:41], v[206:209], v[182:185], v[38:41]
	v_mfma_f32_16x16x32_bf16 v[30:33], v[214:217], v[182:185], v[30:33]
	v_mfma_f32_16x16x32_bf16 v[22:25], v[206:209], v[190:193], v[22:25]
	v_mfma_f32_16x16x32_bf16 v[14:17], v[214:217], v[190:193], v[14:17]
	v_mfma_f32_16x16x32_bf16 v[6:9], v[206:209], v[198:201], v[6:9]
	v_mfma_f32_16x16x32_bf16 v[2:5], v[214:217], v[198:201], v[2:5]
	s_add_i32 s4, 0, 0x18000
	v_add_u32_e32 v144, s4, v237
	s_barrier
	ds_read_b128 v[132:135], v144
	ds_read_b128 v[136:139], v144 offset:1024
	ds_read_b128 v[140:143], v144 offset:2048
	ds_read_b128 v[144:147], v144 offset:3072
	v_lshl_add_u64 v[156:157], v[156:157], 0, s[94:95]
	s_mov_b32 m0, s10
	v_lshl_add_u64 v[202:203], v[156:157], 0, v[160:161]
	ds_read_b128 v[148:151], v243 offset:32768
	ds_read_b128 v[152:155], v243 offset:33792
	ds_read_b128 v[178:181], v243 offset:34816
	ds_read_b128 v[182:185], v243 offset:35840
	ds_read_b128 v[186:189], v243 offset:36864
	ds_read_b128 v[190:193], v243 offset:37888
	ds_read_b128 v[194:197], v243 offset:38912
	ds_read_b128 v[198:201], v243 offset:39936
	global_load_lds_dwordx4 v[202:203], off
	v_lshl_add_u64 v[156:157], v[156:157], 0, v[164:165]
	s_mov_b32 m0, s11
	s_nop 0
	global_load_lds_dwordx4 v[156:157], off
	s_waitcnt lgkmcnt(8)
	s_barrier
	s_waitcnt lgkmcnt(0)
	s_waitcnt lgkmcnt(0)
	v_mfma_f32_16x16x32_bf16 v[126:129], v[132:135], v[148:151], v[126:129]
	v_mfma_f32_16x16x32_bf16 v[122:125], v[140:143], v[148:151], v[122:125]
	v_mfma_f32_16x16x32_bf16 v[110:113], v[132:135], v[178:181], v[110:113]
	v_mfma_f32_16x16x32_bf16 v[106:109], v[140:143], v[178:181], v[106:109]
	v_mfma_f32_16x16x32_bf16 v[98:101], v[132:135], v[186:189], v[98:101]
	v_mfma_f32_16x16x32_bf16 v[90:93], v[140:143], v[186:189], v[90:93]
	v_mfma_f32_16x16x32_bf16 v[82:85], v[132:135], v[194:197], v[82:85]
	v_mfma_f32_16x16x32_bf16 v[74:77], v[140:143], v[194:197], v[74:77]
	v_mfma_f32_16x16x32_bf16 v[126:129], v[136:139], v[152:155], v[126:129]
	v_mfma_f32_16x16x32_bf16 v[122:125], v[144:147], v[152:155], v[122:125]
	v_mfma_f32_16x16x32_bf16 v[110:113], v[136:139], v[182:185], v[110:113]
	v_mfma_f32_16x16x32_bf16 v[106:109], v[144:147], v[182:185], v[106:109]
	v_mfma_f32_16x16x32_bf16 v[98:101], v[136:139], v[190:193], v[98:101]
	v_mfma_f32_16x16x32_bf16 v[90:93], v[144:147], v[190:193], v[90:93]
	v_mfma_f32_16x16x32_bf16 v[82:85], v[136:139], v[198:201], v[82:85]
	v_mfma_f32_16x16x32_bf16 v[74:77], v[144:147], v[198:201], v[74:77]
	s_barrier
	s_add_i32 s5, 0, 0x1c000
	v_add_u32_e32 v156, s5, v237
	s_add_i32 s4, s4, s3
	ds_read_b128 v[202:205], v156
	ds_read_b128 v[206:209], v156 offset:1024
	ds_read_b128 v[210:213], v156 offset:2048
	ds_read_b128 v[214:217], v156 offset:3072
	s_add_i32 m0, s4, 0xffffff80
	s_nop 0
	global_load_lds_dwordx4 v[218:219], off offset:128
	s_add_i32 m0, s4, 0x1f80
	s_nop 0
	global_load_lds_dwordx4 v[224:225], off offset:128
	s_barrier
	s_waitcnt lgkmcnt(0)
	s_waitcnt lgkmcnt(0)
	v_mfma_f32_16x16x32_bf16 v[118:121], v[202:205], v[148:151], v[118:121]
	v_mfma_f32_16x16x32_bf16 v[114:117], v[210:213], v[148:151], v[114:117]
	v_mfma_f32_16x16x32_bf16 v[102:105], v[202:205], v[178:181], v[102:105]
	v_mfma_f32_16x16x32_bf16 v[94:97], v[210:213], v[178:181], v[94:97]
	v_mfma_f32_16x16x32_bf16 v[86:89], v[202:205], v[186:189], v[86:89]
	v_mfma_f32_16x16x32_bf16 v[78:81], v[210:213], v[186:189], v[78:81]
	v_mfma_f32_16x16x32_bf16 v[70:73], v[202:205], v[194:197], v[70:73]
	v_mfma_f32_16x16x32_bf16 v[66:69], v[210:213], v[194:197], v[66:69]
	v_mfma_f32_16x16x32_bf16 v[118:121], v[206:209], v[152:155], v[118:121]
	v_mfma_f32_16x16x32_bf16 v[114:117], v[214:217], v[152:155], v[114:117]
	v_mfma_f32_16x16x32_bf16 v[102:105], v[206:209], v[182:185], v[102:105]
	v_mfma_f32_16x16x32_bf16 v[94:97], v[214:217], v[182:185], v[94:97]
	v_mfma_f32_16x16x32_bf16 v[86:89], v[206:209], v[190:193], v[86:89]
	v_mfma_f32_16x16x32_bf16 v[78:81], v[214:217], v[190:193], v[78:81]
	v_mfma_f32_16x16x32_bf16 v[70:73], v[206:209], v[198:201], v[70:73]
	v_mfma_f32_16x16x32_bf16 v[66:69], v[214:217], v[198:201], v[66:69]
	s_add_i32 m0, s12, 0xffffff80
	s_barrier
	ds_read_b128 v[148:151], v243 offset:49152
	ds_read_b128 v[152:155], v243 offset:50176
	ds_read_b128 v[178:181], v243 offset:51200
	ds_read_b128 v[182:185], v243 offset:52224
	ds_read_b128 v[186:189], v243 offset:53248
	ds_read_b128 v[190:193], v243 offset:54272
	ds_read_b128 v[194:197], v243 offset:55296
	ds_read_b128 v[198:201], v243 offset:56320
	global_load_lds_dwordx4 v[230:231], off offset:128
	s_add_i32 m0, s28, 0xffffff80
	s_nop 0
	global_load_lds_dwordx4 v[232:233], off offset:128
	s_barrier
	s_waitcnt lgkmcnt(0)
	s_waitcnt lgkmcnt(0)
	v_mfma_f32_16x16x32_bf16 v[62:65], v[132:135], v[148:151], v[62:65]
	v_mfma_f32_16x16x32_bf16 v[58:61], v[140:143], v[148:151], v[58:61]
	v_mfma_f32_16x16x32_bf16 v[46:49], v[132:135], v[178:181], v[46:49]
	v_mfma_f32_16x16x32_bf16 v[42:45], v[140:143], v[178:181], v[42:45]
	v_mfma_f32_16x16x32_bf16 v[34:37], v[132:135], v[186:189], v[34:37]
	v_mfma_f32_16x16x32_bf16 v[26:29], v[140:143], v[186:189], v[26:29]
	v_mfma_f32_16x16x32_bf16 v[18:21], v[132:135], v[194:197], v[18:21]
	v_mfma_f32_16x16x32_bf16 v[10:13], v[140:143], v[194:197], v[10:13]
	v_mfma_f32_16x16x32_bf16 v[62:65], v[136:139], v[152:155], v[62:65]
	v_mfma_f32_16x16x32_bf16 v[58:61], v[144:147], v[152:155], v[58:61]
	v_mfma_f32_16x16x32_bf16 v[46:49], v[136:139], v[182:185], v[46:49]
	v_mfma_f32_16x16x32_bf16 v[42:45], v[144:147], v[182:185], v[42:45]
	v_mfma_f32_16x16x32_bf16 v[34:37], v[136:139], v[190:193], v[34:37]
	v_mfma_f32_16x16x32_bf16 v[26:29], v[144:147], v[190:193], v[26:29]
	v_mfma_f32_16x16x32_bf16 v[18:21], v[136:139], v[198:201], v[18:21]
	v_mfma_f32_16x16x32_bf16 v[10:13], v[144:147], v[198:201], v[10:13]
	s_barrier
	s_add_i32 s4, s5, s3
	s_add_i32 m0, s4, 0xffffff80
	s_nop 0
	global_load_lds_dwordx4 v[244:245], off offset:128
	s_add_i32 m0, s4, 0x1f80
	s_nop 0
	global_load_lds_dwordx4 v[246:247], off offset:128
	s_waitcnt vmcnt(6)
	s_barrier
	v_mfma_f32_16x16x32_bf16 v[54:57], v[202:205], v[148:151], v[54:57]
	v_mfma_f32_16x16x32_bf16 v[50:53], v[210:213], v[148:151], v[50:53]
	v_mfma_f32_16x16x32_bf16 v[38:41], v[202:205], v[178:181], v[38:41]
	v_mfma_f32_16x16x32_bf16 v[30:33], v[210:213], v[178:181], v[30:33]
	v_mfma_f32_16x16x32_bf16 v[22:25], v[202:205], v[186:189], v[22:25]
	v_mfma_f32_16x16x32_bf16 v[14:17], v[210:213], v[186:189], v[14:17]
	v_mfma_f32_16x16x32_bf16 v[6:9], v[202:205], v[194:197], v[6:9]
	v_mfma_f32_16x16x32_bf16 v[2:5], v[210:213], v[194:197], v[2:5]
	v_mfma_f32_16x16x32_bf16 v[54:57], v[206:209], v[152:155], v[54:57]
	v_mfma_f32_16x16x32_bf16 v[50:53], v[214:217], v[152:155], v[50:53]
	v_mfma_f32_16x16x32_bf16 v[38:41], v[206:209], v[182:185], v[38:41]
	v_mfma_f32_16x16x32_bf16 v[30:33], v[214:217], v[182:185], v[30:33]
	v_mfma_f32_16x16x32_bf16 v[22:25], v[206:209], v[190:193], v[22:25]
	v_mfma_f32_16x16x32_bf16 v[14:17], v[214:217], v[190:193], v[14:17]
	v_mfma_f32_16x16x32_bf16 v[6:9], v[206:209], v[198:201], v[6:9]
	v_mfma_f32_16x16x32_bf16 v[2:5], v[214:217], v[198:201], v[2:5]
	s_add_u32 s6, s6, 0x100
	s_addc_u32 s7, s7, 0
	v_lshl_add_u64 v[130:131], v[130:131], 0, s[86:87]
	s_cmp_ge_u32 s42, s13
	s_mov_b32 s4, s42
	s_barrier
	s_cbranch_scc0 .LBB0_649
	s_lshl_b32 s6, s23, 8
	v_lshl_or_b32 v178, s22, 8, v238
	v_add_u32_e32 v130, s6, v1
	v_ashrrev_i32_e32 v179, 31, v178
	v_lshlrev_b64 v[186:187], 1, v[178:179]
	v_ashrrev_i32_e32 v131, 31, v130
	v_lshl_add_u64 v[190:191], s[18:19], 0, v[186:187]
	v_lshlrev_b64 v[188:189], 11, v[130:131]
	v_lshl_add_u64 v[132:133], v[190:191], 0, v[188:189]
	global_load_dwordx4 v[192:195], v[132:133], off
	global_load_dwordx4 v[154:157], v[132:133], off offset:256
	v_or_b32_e32 v132, 16, v130
	v_ashrrev_i32_e32 v133, 31, v132
	v_lshlrev_b64 v[184:185], 11, v[132:133]
	v_lshl_add_u64 v[132:133], v[190:191], 0, v[184:185]
	global_load_dwordx4 v[150:153], v[132:133], off
	global_load_dwordx4 v[146:149], v[132:133], off offset:256
	v_or_b32_e32 v132, 32, v130
	v_ashrrev_i32_e32 v133, 31, v132
	v_lshlrev_b64 v[182:183], 11, v[132:133]
	v_or_b32_e32 v130, 48, v130
	v_lshl_add_u64 v[132:133], v[190:191], 0, v[182:183]
	v_ashrrev_i32_e32 v131, 31, v130
	global_load_dwordx4 v[142:145], v[132:133], off
	global_load_dwordx4 v[138:141], v[132:133], off offset:256
	v_lshlrev_b64 v[180:181], 11, v[130:131]
	v_lshl_add_u64 v[130:131], v[190:191], 0, v[180:181]
	global_load_dwordx4 v[134:137], v[130:131], off
	s_nop 0
	global_load_dwordx4 v[130:133], v[130:131], off offset:256
	v_mov_b32_e32 v169, v168
	s_mov_b64 s[4:5], 0x40000
	v_cmp_lt_i32_e32 vcc, v227, v222
	s_waitcnt vmcnt(0)
	v_lshlrev_b32_e32 v196, 16, v192
	v_and_b32_e32 v197, 0xffff0000, v192
	v_lshlrev_b32_e32 v192, 16, v193
	v_and_b32_e32 v193, 0xffff0000, v193
	v_lshlrev_b32_e32 v198, 16, v194
	v_and_b32_e32 v199, 0xffff0000, v194
	v_lshlrev_b32_e32 v194, 16, v195
	v_and_b32_e32 v195, 0xffff0000, v195
	v_pk_fma_f32 v[128:129], v[168:169], v[128:129], v[192:193]
	v_pk_fma_f32 v[126:127], v[170:171], v[126:127], v[196:197]
	v_pk_fma_f32 v[192:193], v[168:169], v[124:125], v[194:195]
	v_pk_fma_f32 v[124:125], v[170:171], v[122:123], v[198:199]
	v_mul_f32_e32 v122, v127, v127
	v_mul_f32_e32 v123, v129, v129
	v_fmac_f32_e32 v122, v126, v126
	v_fmac_f32_e32 v123, v128, v128
	v_add_f32_e32 v122, v122, v123
	v_mul_f32_e32 v123, v125, v125
	v_mul_f32_e32 v194, v193, v193
	v_fmac_f32_e32 v123, v124, v124
	v_fmac_f32_e32 v194, v192, v192
	v_add_f32_e32 v123, v123, v194
	v_add_f32_e32 v194, v122, v123
	v_cvt_pk_bf16_f32 v122, v126, v127
	v_cvt_pk_bf16_f32 v123, v128, v129
	v_lshlrev_b32_e32 v126, 16, v154
	v_and_b32_e32 v127, 0xffff0000, v154
	v_lshlrev_b32_e32 v128, 16, v155
	v_and_b32_e32 v129, 0xffff0000, v155
	v_lshlrev_b32_e32 v154, 16, v156
	v_and_b32_e32 v155, 0xffff0000, v156
	v_lshlrev_b32_e32 v156, 16, v157
	v_and_b32_e32 v157, 0xffff0000, v157
	v_pk_fma_f32 v[120:121], v[168:169], v[120:121], v[128:129]
	v_pk_fma_f32 v[118:119], v[170:171], v[118:119], v[126:127]
	v_pk_fma_f32 v[126:127], v[168:169], v[116:117], v[156:157]
	v_pk_fma_f32 v[116:117], v[170:171], v[114:115], v[154:155]
	v_mul_f32_e32 v114, v119, v119
	v_mul_f32_e32 v115, v121, v121
	v_fmac_f32_e32 v114, v118, v118
	v_fmac_f32_e32 v115, v120, v120
	v_add_f32_e32 v114, v114, v115
	v_mul_f32_e32 v115, v117, v117
	v_mul_f32_e32 v128, v127, v127
	v_fmac_f32_e32 v115, v116, v116
	v_fmac_f32_e32 v128, v126, v126
	v_add_f32_e32 v115, v115, v128
	v_add_f32_e32 v114, v114, v115
	v_cvt_pk_bf16_f32 v124, v124, v125
	v_cvt_pk_bf16_f32 v125, v192, v193
	v_add_f32_e32 v244, v194, v114
	v_cvt_pk_bf16_f32 v114, v118, v119
	v_cvt_pk_bf16_f32 v115, v120, v121
	v_lshlrev_b32_e32 v118, 16, v150
	v_and_b32_e32 v119, 0xffff0000, v150
	v_lshlrev_b32_e32 v120, 16, v151
	v_and_b32_e32 v121, 0xffff0000, v151
	v_pk_fma_f32 v[154:155], v[168:169], v[112:113], v[120:121]
	v_pk_fma_f32 v[156:157], v[170:171], v[110:111], v[118:119]
	v_lshlrev_b32_e32 v110, 16, v146
	v_and_b32_e32 v111, 0xffff0000, v146
	v_lshlrev_b32_e32 v112, 16, v147
	v_and_b32_e32 v113, 0xffff0000, v147
	v_lshlrev_b32_e32 v118, 16, v148
	v_and_b32_e32 v119, 0xffff0000, v148
	v_lshlrev_b32_e32 v120, 16, v149
	v_and_b32_e32 v121, 0xffff0000, v149
	v_pk_fma_f32 v[146:147], v[168:169], v[104:105], v[112:113]
	v_pk_fma_f32 v[192:193], v[170:171], v[102:103], v[110:111]
	v_pk_fma_f32 v[148:149], v[168:169], v[96:97], v[120:121]
	v_pk_fma_f32 v[198:199], v[170:171], v[94:95], v[118:119]
	v_lshlrev_b32_e32 v94, 16, v142
	v_and_b32_e32 v95, 0xffff0000, v142
	v_lshlrev_b32_e32 v96, 16, v143
	v_and_b32_e32 v97, 0xffff0000, v143
	v_lshlrev_b32_e32 v110, 16, v144
	v_and_b32_e32 v111, 0xffff0000, v144
	v_lshlrev_b32_e32 v112, 16, v145
	v_and_b32_e32 v113, 0xffff0000, v145
	v_pk_fma_f32 v[142:143], v[168:169], v[100:101], v[96:97]
	v_pk_fma_f32 v[194:195], v[170:171], v[98:99], v[94:95]
	v_pk_fma_f32 v[144:145], v[168:169], v[92:93], v[112:113]
	v_pk_fma_f32 v[196:197], v[170:171], v[90:91], v[110:111]
	v_lshlrev_b32_e32 v90, 16, v138
	v_and_b32_e32 v91, 0xffff0000, v138
	v_lshlrev_b32_e32 v92, 16, v139
	v_and_b32_e32 v93, 0xffff0000, v139
	v_lshlrev_b32_e32 v98, 16, v140
	v_and_b32_e32 v99, 0xffff0000, v140
	v_lshlrev_b32_e32 v100, 16, v141
	v_and_b32_e32 v101, 0xffff0000, v141
	v_pk_fma_f32 v[200:201], v[168:169], v[88:89], v[92:93]
	v_pk_fma_f32 v[208:209], v[170:171], v[86:87], v[90:91]
	v_pk_fma_f32 v[204:205], v[168:169], v[80:81], v[100:101]
	v_pk_fma_f32 v[210:211], v[170:171], v[78:79], v[98:99]
	v_lshlrev_b32_e32 v78, 16, v134
	v_and_b32_e32 v79, 0xffff0000, v134
	v_lshlrev_b32_e32 v80, 16, v135
	v_and_b32_e32 v81, 0xffff0000, v135
	v_lshlrev_b32_e32 v86, 16, v136
	v_and_b32_e32 v87, 0xffff0000, v136
	v_lshlrev_b32_e32 v88, 16, v137
	v_and_b32_e32 v89, 0xffff0000, v137
	v_cvt_pk_bf16_f32 v116, v116, v117
	v_cvt_pk_bf16_f32 v117, v126, v127
	v_lshlrev_b32_e32 v126, 16, v152
	v_and_b32_e32 v127, 0xffff0000, v152
	v_lshlrev_b32_e32 v128, 16, v153
	v_and_b32_e32 v129, 0xffff0000, v153
	v_pk_fma_f32 v[138:139], v[168:169], v[84:85], v[80:81]
	v_pk_fma_f32 v[202:203], v[170:171], v[82:83], v[78:79]
	v_pk_fma_f32 v[140:141], v[168:169], v[76:77], v[88:89]
	v_pk_fma_f32 v[206:207], v[170:171], v[74:75], v[86:87]
	v_lshlrev_b32_e32 v74, 16, v130
	v_and_b32_e32 v75, 0xffff0000, v130
	v_lshlrev_b32_e32 v76, 16, v131
	v_and_b32_e32 v77, 0xffff0000, v131
	v_lshlrev_b32_e32 v78, 16, v132
	v_and_b32_e32 v79, 0xffff0000, v132
	v_lshlrev_b32_e32 v80, 16, v133
	v_and_b32_e32 v81, 0xffff0000, v133
	v_lshl_add_u64 v[136:137], v[188:189], 0, s[4:5]
	s_mov_b64 s[4:5], 0x48000
	v_pk_fma_f32 v[150:151], v[168:169], v[108:109], v[128:129]
	v_pk_fma_f32 v[152:153], v[170:171], v[106:107], v[126:127]
	v_cvt_pk_bf16_f32 v106, v156, v157
	v_cvt_pk_bf16_f32 v107, v154, v155
	v_pk_fma_f32 v[212:213], v[168:169], v[72:73], v[76:77]
	v_cvt_pk_bf16_f32 v108, v152, v153
	v_cvt_pk_bf16_f32 v109, v150, v151
	v_cvt_pk_bf16_f32 v102, v192, v193
	v_cvt_pk_bf16_f32 v103, v146, v147
	v_cvt_pk_bf16_f32 v104, v198, v199
	v_cvt_pk_bf16_f32 v105, v148, v149
	v_cvt_pk_bf16_f32 v94, v194, v195
	v_cvt_pk_bf16_f32 v95, v142, v143
	v_cvt_pk_bf16_f32 v96, v196, v197
	v_cvt_pk_bf16_f32 v97, v144, v145
	v_cvt_pk_bf16_f32 v118, v208, v209
	v_cvt_pk_bf16_f32 v119, v200, v201
	v_cvt_pk_bf16_f32 v120, v210, v211
	v_cvt_pk_bf16_f32 v121, v204, v205
	v_cvt_pk_bf16_f32 v98, v202, v203
	v_cvt_pk_bf16_f32 v99, v138, v139
	v_cvt_pk_bf16_f32 v100, v206, v207
	v_cvt_pk_bf16_f32 v101, v140, v141
	v_pk_fma_f32 v[216:217], v[170:171], v[70:71], v[74:75]
	v_pk_fma_f32 v[214:215], v[168:169], v[68:69], v[80:81]
	v_pk_fma_f32 v[218:219], v[170:171], v[66:67], v[78:79]
	v_cvt_pk_bf16_f32 v126, v216, v217
	v_cvt_pk_bf16_f32 v127, v212, v213
	v_lshl_add_u64 v[66:67], v[190:191], 0, v[136:137]
	v_cvt_pk_bf16_f32 v128, v218, v219
	v_cvt_pk_bf16_f32 v129, v214, v215
	v_lshl_add_u64 v[134:135], v[188:189], 0, s[4:5]
	s_mov_b64 s[4:5], 0x50000
	global_load_dwordx4 v[110:113], v[66:67], off
	global_load_dwordx4 v[90:93], v[66:67], off offset:256
	v_lshl_add_u64 v[66:67], v[190:191], 0, v[134:135]
	v_lshl_add_u64 v[132:133], v[188:189], 0, s[4:5]
	s_mov_b64 s[4:5], 0x58000
	global_load_dwordx4 v[86:89], v[66:67], off
	global_load_dwordx4 v[82:85], v[66:67], off offset:256
	v_lshl_add_u64 v[66:67], v[190:191], 0, v[132:133]
	v_lshl_add_u64 v[130:131], v[188:189], 0, s[4:5]
	global_load_dwordx4 v[78:81], v[66:67], off
	global_load_dwordx4 v[74:77], v[66:67], off offset:256
	v_lshl_add_u64 v[66:67], v[190:191], 0, v[130:131]
	global_load_dwordx4 v[70:73], v[66:67], off
	s_nop 0
	global_load_dwordx4 v[66:69], v[66:67], off offset:256
	v_cndmask_b32_e32 v169, v221, v227, vcc
	v_lshl_add_u64 v[188:189], s[18:19], 0, v[188:189]
	v_lshlrev_b32_e32 v190, 2, v169
	v_lshl_add_u64 v[186:187], v[188:189], 0, v[186:187]
	global_store_dwordx4 v[186:187], v[122:125], off
	global_store_dwordx4 v[186:187], v[114:117], off offset:256
	ds_bpermute_b32 v114, v190, v244
	v_cmp_lt_i32_e32 vcc, v228, v222
	s_waitcnt lgkmcnt(0)
	v_add_f32_e32 v114, v244, v114
	v_cndmask_b32_e32 v169, v221, v228, vcc
	v_lshlrev_b32_e32 v191, 2, v169
	ds_bpermute_b32 v115, v191, v114
	s_and_saveexec_b64 s[4:5], s[38:39]
	s_cbranch_execz .LBB0_652
	s_waitcnt lgkmcnt(0)
	v_add_f32_e32 v114, v114, v115
	v_add_u32_e32 v115, s90, v239
	ds_write_b32 v115, v114

.LBB0_679:
	s_lshl_b64 s[6:7], s[38:39], 2
	v_readlane_b32 s22, v250, 19
	v_readlane_b32 s23, v250, 20
	s_add_u32 s6, s22, s6
	v_mov_b32_e32 v147, v0
	s_addc_u32 s7, s23, s7
	s_add_i32 m0, s10, 0x17f80
	v_lshl_add_u64 v[20:21], v[2:3], 0, v[146:147]
	v_mov_b32_e32 v151, v0
	s_waitcnt vmcnt(4)
	s_barrier
	global_load_lds_dwordx4 v[4:5], off offset:128
	s_add_i32 m0, s10, 0x19f80
	s_add_i32 s54, s10, 0x8000
	v_lshl_add_u64 v[22:23], v[2:3], 0, v[150:151]
	global_load_lds_dwordx4 v[6:7], off offset:128
	s_add_i32 m0, s54, 0xffffff80
	s_add_i32 s3, s10, 0xa000
	global_load_lds_dwordx4 v[20:21], off offset:128
	s_add_i32 m0, s3, 0xffffff80
	v_and_b32_e32 v6, 15, v12
	global_load_lds_dwordx4 v[22:23], off offset:128
	s_add_i32 m0, s10, 0x1bf80
	global_load_lds_dwordx4 v[8:9], off offset:128
	s_add_i32 m0, s10, 0x1df80
	v_and_b32_e32 v7, 48, v12
	global_load_lds_dwordx4 v[10:11], off offset:128
	v_lshl_or_b32 v1, s0, 6, v6
	v_lshl_or_b32 v6, v6, 6, v7
	v_lshlrev_b32_e32 v7, 2, v12
	s_lshl_b32 s0, s0, 13
	v_and_b32_e32 v7, 32, v7
	v_bitop3_b32 v8, v6, s0, v7 bitop3:0xde
	s_lshl_b32 s0, s1, 5
	s_lshl_b32 s1, s1, 11
	v_writelane_b32 v255, s6, 25
	s_and_b32 s0, s0, 0x60
	s_add_i32 s35, s1, 0
	v_writelane_b32 v255, s7, 26
	s_lshl_b32 s6, s0, 7
	s_add_i32 s35, s35, 0x22100
	s_add_i32 s44, s13, -2
	s_ashr_i32 s65, s37, 31
	s_ashr_i32 s96, s14, 31
	s_cmp_lg_u64 s[28:29], 0
	s_cselect_b64 s[42:43], -1, 0
	s_lshl_b32 s45, s16, 3
	v_bitop3_b32 v176, s6, v6, v7 bitop3:0xf6
	v_cvt_f32_u32_e32 v6, s45
	v_and_b32_e32 v4, 63, v12
	v_bfe_u32 v5, v12, 4, 2
	v_lshlrev_b32_e32 v7, 2, v4
	v_rcp_iflag_f32_e32 v6, v6
	v_lshl_or_b32 v177, v5, 3, s0
	v_lshlrev_b32_e32 v4, 2, v5
	v_mov_b32_e32 v5, v0
	v_lshl_add_u64 v[154:155], s[28:29], 0, v[4:5]
	v_mul_f32_e32 v4, 0x4f7ffffe, v6
	v_cvt_u32_f32_e32 v4, v4
	s_lshr_b32 s0, s24, 3
	v_writelane_b32 v255, s0, 27
	s_sub_i32 s0, 0, s45
	v_readfirstlane_b32 s1, v4
	v_add_u32_e32 v4, v15, v13
	s_mul_i32 s0, s0, s1
	v_add_lshl_u32 v4, v4, v14, 1
	s_waitcnt vmcnt(6)
	s_mul_hi_u32 s0, s1, s0
	v_lshl_add_u64 v[156:157], s[94:95], 0, v[4:5]
	v_add_u32_e32 v4, v18, v16
	s_add_i32 s0, s1, s0
	v_add_lshl_u32 v4, v4, v17, 1
	s_mov_b32 s25, s95
	s_mov_b32 s12, 0
	v_writelane_b32 v255, s0, 28
	v_lshl_add_u64 v[160:161], s[94:95], 0, v[4:5]
	v_add_u32_e32 v178, 0, v8
	v_add_u32_e32 v179, s35, v7
	s_mov_b64 s[90:91], s[42:43]
	s_barrier
	s_branch .LBB0_682

.LBB0_691:
	s_add_i32 s6, s0, 2
	s_add_i32 s7, 0, 0x10000
	s_cmp_eq_u32 s44, s0
	v_lshl_add_u64 v[100:101], v[98:99], 0, s[84:85]
	s_cselect_b64 vcc, -1, 0
	v_add_u32_e32 v104, s7, v176
	v_cndmask_b32_e32 v175, v101, v165, vcc
	v_cndmask_b32_e32 v174, v100, v164, vcc
	ds_read_b128 v[100:103], v104
	ds_read_b128 v[138:141], v104 offset:1024
	ds_read_b128 v[142:145], v104 offset:2048
	ds_read_b128 v[166:169], v104 offset:3072
	s_cselect_b32 s0, s22, s4
	s_cselect_b32 s1, s23, s5
	v_lshl_add_u64 v[104:105], v[98:99], 0, v[156:157]
	s_add_i32 m0, s10, 0xc000
	ds_read_b128 v[170:173], v178
	ds_read_b128 v[180:183], v178 offset:1024
	ds_read_b128 v[184:187], v178 offset:2048
	ds_read_b128 v[188:191], v178 offset:3072
	ds_read_b128 v[192:195], v178 offset:4096
	ds_read_b128 v[196:199], v178 offset:5120
	ds_read_b128 v[200:203], v178 offset:6144
	ds_read_b128 v[204:207], v178 offset:7168
	global_load_lds_dwordx4 v[104:105], off
	v_lshl_add_u64 v[104:105], v[98:99], 0, v[160:161]
	s_add_i32 m0, s10, 0xe000
	s_nop 0
	global_load_lds_dwordx4 v[104:105], off
	s_waitcnt lgkmcnt(8)
	s_barrier
	s_waitcnt lgkmcnt(0)
	s_waitcnt lgkmcnt(0)
	v_mfma_f32_16x16x32_bf16 v[134:137], v[100:103], v[170:173], v[134:137]
	v_mfma_f32_16x16x32_bf16 v[130:133], v[142:145], v[170:173], v[130:133]
	v_mfma_f32_16x16x32_bf16 v[126:129], v[100:103], v[184:187], v[126:129]
	v_mfma_f32_16x16x32_bf16 v[122:125], v[142:145], v[184:187], v[122:125]
	v_mfma_f32_16x16x32_bf16 v[118:121], v[100:103], v[192:195], v[118:121]
	v_mfma_f32_16x16x32_bf16 v[114:117], v[142:145], v[192:195], v[114:117]
	v_mfma_f32_16x16x32_bf16 v[110:113], v[100:103], v[200:203], v[110:113]
	v_mfma_f32_16x16x32_bf16 v[104:107], v[142:145], v[200:203], v[106:109]
	v_mfma_f32_16x16x32_bf16 v[134:137], v[138:141], v[180:183], v[134:137]
	v_mfma_f32_16x16x32_bf16 v[130:133], v[166:169], v[180:183], v[130:133]
	v_mfma_f32_16x16x32_bf16 v[126:129], v[138:141], v[188:191], v[126:129]
	v_mfma_f32_16x16x32_bf16 v[122:125], v[166:169], v[188:191], v[122:125]
	v_mfma_f32_16x16x32_bf16 v[118:121], v[138:141], v[196:199], v[118:121]
	v_mfma_f32_16x16x32_bf16 v[114:117], v[166:169], v[196:199], v[114:117]
	v_mfma_f32_16x16x32_bf16 v[110:113], v[138:141], v[204:207], v[110:113]
	v_mfma_f32_16x16x32_bf16 v[104:107], v[166:169], v[204:207], v[104:107]
	s_barrier
	s_add_i32 s36, 0, 0x14000
	s_add_i32 s7, s7, s9
	v_add_u32_e32 v108, s36, v176
	v_lshl_add_u64 v[242:243], s[0:1], 0, v[148:149]
	s_mov_b32 m0, s7
	ds_read_b128 v[208:211], v108
	ds_read_b128 v[212:215], v108 offset:1024
	ds_read_b128 v[216:219], v108 offset:2048
	ds_read_b128 v[238:241], v108 offset:3072
	global_load_lds_dwordx4 v[242:243], off
	v_lshl_add_u64 v[244:245], s[0:1], 0, v[152:153]
	s_add_i32 m0, s7, 0x2000
	s_nop 0
	global_load_lds_dwordx4 v[244:245], off
	s_barrier
	s_waitcnt lgkmcnt(0)
	s_waitcnt lgkmcnt(0)
	v_mfma_f32_16x16x32_bf16 v[62:65], v[208:211], v[170:173], v[62:65]
	v_mfma_f32_16x16x32_bf16 v[58:61], v[216:219], v[170:173], v[58:61]
	v_mfma_f32_16x16x32_bf16 v[54:57], v[208:211], v[184:187], v[54:57]
	v_mfma_f32_16x16x32_bf16 v[50:53], v[216:219], v[184:187], v[50:53]
	v_mfma_f32_16x16x32_bf16 v[46:49], v[208:211], v[192:195], v[46:49]
	v_mfma_f32_16x16x32_bf16 v[42:45], v[216:219], v[192:195], v[42:45]
	v_mfma_f32_16x16x32_bf16 v[38:41], v[208:211], v[200:203], v[38:41]
	v_mfma_f32_16x16x32_bf16 v[34:37], v[216:219], v[200:203], v[34:37]
	v_mfma_f32_16x16x32_bf16 v[62:65], v[212:215], v[180:183], v[62:65]
	v_mfma_f32_16x16x32_bf16 v[58:61], v[238:241], v[180:183], v[58:61]
	v_mfma_f32_16x16x32_bf16 v[54:57], v[212:215], v[188:191], v[54:57]
	v_mfma_f32_16x16x32_bf16 v[50:53], v[238:241], v[188:191], v[50:53]
	v_mfma_f32_16x16x32_bf16 v[46:49], v[212:215], v[196:199], v[46:49]
	v_mfma_f32_16x16x32_bf16 v[42:45], v[238:241], v[196:199], v[42:45]
	v_mfma_f32_16x16x32_bf16 v[38:41], v[212:215], v[204:207], v[38:41]
	v_mfma_f32_16x16x32_bf16 v[34:37], v[238:241], v[204:207], v[34:37]
	s_mov_b32 m0, s10
	v_lshl_add_u64 v[246:247], v[174:175], 0, v[146:147]
	s_barrier
	ds_read_b128 v[170:173], v178 offset:16384
	ds_read_b128 v[180:183], v178 offset:17408
	ds_read_b128 v[184:187], v178 offset:18432
	ds_read_b128 v[188:191], v178 offset:19456
	ds_read_b128 v[192:195], v178 offset:20480
	ds_read_b128 v[196:199], v178 offset:21504
	ds_read_b128 v[200:203], v178 offset:22528
	ds_read_b128 v[204:207], v178 offset:23552
	global_load_lds_dwordx4 v[246:247], off
	v_lshl_add_u64 v[248:249], v[174:175], 0, v[150:151]
	s_mov_b32 m0, s11
	s_nop 0
	global_load_lds_dwordx4 v[248:249], off
	s_barrier
	s_waitcnt lgkmcnt(0)
	s_waitcnt lgkmcnt(0)
	v_mfma_f32_16x16x32_bf16 v[94:97], v[100:103], v[170:173], v[94:97]
	v_mfma_f32_16x16x32_bf16 v[90:93], v[142:145], v[170:173], v[90:93]
	v_mfma_f32_16x16x32_bf16 v[86:89], v[100:103], v[184:187], v[86:89]
	v_mfma_f32_16x16x32_bf16 v[82:85], v[142:145], v[184:187], v[82:85]
	v_mfma_f32_16x16x32_bf16 v[78:81], v[100:103], v[192:195], v[78:81]
	v_mfma_f32_16x16x32_bf16 v[74:77], v[142:145], v[192:195], v[74:77]
	v_mfma_f32_16x16x32_bf16 v[70:73], v[100:103], v[200:203], v[70:73]
	v_mfma_f32_16x16x32_bf16 v[66:69], v[142:145], v[200:203], v[66:69]
	v_mfma_f32_16x16x32_bf16 v[94:97], v[138:141], v[180:183], v[94:97]
	v_mfma_f32_16x16x32_bf16 v[90:93], v[166:169], v[180:183], v[90:93]
	v_mfma_f32_16x16x32_bf16 v[86:89], v[138:141], v[188:191], v[86:89]
	v_mfma_f32_16x16x32_bf16 v[82:85], v[166:169], v[188:191], v[82:85]
	v_mfma_f32_16x16x32_bf16 v[78:81], v[138:141], v[196:199], v[78:81]
	v_mfma_f32_16x16x32_bf16 v[74:77], v[166:169], v[196:199], v[74:77]
	v_mfma_f32_16x16x32_bf16 v[70:73], v[138:141], v[204:207], v[70:73]
	v_mfma_f32_16x16x32_bf16 v[66:69], v[166:169], v[204:207], v[66:69]
	s_barrier
	s_add_u32 s0, s0, s94
	s_addc_u32 s1, s1, 0
	s_add_i32 s7, s36, s9
	v_lshl_add_u64 v[230:231], s[0:1], 0, v[148:149]
	s_mov_b32 m0, s7
	v_lshl_add_u64 v[224:225], s[0:1], 0, v[152:153]
	global_load_lds_dwordx4 v[230:231], off
	s_add_i32 m0, s7, 0x2000
	s_nop 0
	global_load_lds_dwordx4 v[224:225], off
	s_waitcnt vmcnt(6)
	s_barrier
	v_mfma_f32_16x16x32_bf16 v[30:33], v[208:211], v[170:173], v[30:33]
	v_mfma_f32_16x16x32_bf16 v[26:29], v[216:219], v[170:173], v[26:29]
	v_mfma_f32_16x16x32_bf16 v[22:25], v[208:211], v[184:187], v[22:25]
	v_mfma_f32_16x16x32_bf16 v[18:21], v[216:219], v[184:187], v[18:21]
	v_mfma_f32_16x16x32_bf16 v[14:17], v[208:211], v[192:195], v[14:17]
	v_mfma_f32_16x16x32_bf16 v[10:13], v[216:219], v[192:195], v[10:13]
	v_mfma_f32_16x16x32_bf16 v[6:9], v[208:211], v[200:203], v[6:9]
	v_mfma_f32_16x16x32_bf16 v[2:5], v[216:219], v[200:203], v[2:5]
	v_mfma_f32_16x16x32_bf16 v[30:33], v[212:215], v[180:183], v[30:33]
	v_mfma_f32_16x16x32_bf16 v[26:29], v[238:241], v[180:183], v[26:29]
	v_mfma_f32_16x16x32_bf16 v[22:25], v[212:215], v[188:191], v[22:25]
	v_mfma_f32_16x16x32_bf16 v[18:21], v[238:241], v[188:191], v[18:21]
	v_mfma_f32_16x16x32_bf16 v[14:17], v[212:215], v[196:199], v[14:17]
	v_mfma_f32_16x16x32_bf16 v[10:13], v[238:241], v[196:199], v[10:13]
	v_mfma_f32_16x16x32_bf16 v[6:9], v[212:215], v[204:207], v[6:9]
	v_mfma_f32_16x16x32_bf16 v[2:5], v[238:241], v[204:207], v[2:5]
	s_add_i32 s0, 0, 0x18000
	v_add_u32_e32 v108, s0, v176
	s_barrier
	ds_read_b128 v[100:103], v108
	ds_read_b128 v[138:141], v108 offset:1024
	ds_read_b128 v[142:145], v108 offset:2048
	ds_read_b128 v[166:169], v108 offset:3072
	v_lshl_add_u64 v[108:109], v[174:175], 0, s[94:95]
	s_mov_b32 m0, s8
	v_lshl_add_u64 v[174:175], v[108:109], 0, v[146:147]
	ds_read_b128 v[170:173], v178 offset:32768
	ds_read_b128 v[180:183], v178 offset:33792
	ds_read_b128 v[184:187], v178 offset:34816
	ds_read_b128 v[188:191], v178 offset:35840
	ds_read_b128 v[192:195], v178 offset:36864
	ds_read_b128 v[196:199], v178 offset:37888
	ds_read_b128 v[200:203], v178 offset:38912
	ds_read_b128 v[204:207], v178 offset:39936
	global_load_lds_dwordx4 v[174:175], off
	v_lshl_add_u64 v[108:109], v[108:109], 0, v[150:151]
	s_mov_b32 m0, s2
	s_nop 0
	global_load_lds_dwordx4 v[108:109], off
	s_waitcnt lgkmcnt(8)
	s_barrier
	s_waitcnt lgkmcnt(0)
	s_waitcnt lgkmcnt(0)
	v_mfma_f32_16x16x32_bf16 v[134:137], v[100:103], v[170:173], v[134:137]
	v_mfma_f32_16x16x32_bf16 v[130:133], v[142:145], v[170:173], v[130:133]
	v_mfma_f32_16x16x32_bf16 v[126:129], v[100:103], v[184:187], v[126:129]
	v_mfma_f32_16x16x32_bf16 v[122:125], v[142:145], v[184:187], v[122:125]
	v_mfma_f32_16x16x32_bf16 v[118:121], v[100:103], v[192:195], v[118:121]
	v_mfma_f32_16x16x32_bf16 v[114:117], v[142:145], v[192:195], v[114:117]
	v_mfma_f32_16x16x32_bf16 v[108:111], v[100:103], v[200:203], v[110:113]
	v_mfma_f32_16x16x32_bf16 v[104:107], v[142:145], v[200:203], v[104:107]
	v_mfma_f32_16x16x32_bf16 v[134:137], v[138:141], v[180:183], v[134:137]
	v_mfma_f32_16x16x32_bf16 v[130:133], v[166:169], v[180:183], v[130:133]
	v_mfma_f32_16x16x32_bf16 v[126:129], v[138:141], v[188:191], v[126:129]
	v_mfma_f32_16x16x32_bf16 v[122:125], v[166:169], v[188:191], v[122:125]
	v_mfma_f32_16x16x32_bf16 v[118:121], v[138:141], v[196:199], v[118:121]
	v_mfma_f32_16x16x32_bf16 v[114:117], v[166:169], v[196:199], v[114:117]
	v_mfma_f32_16x16x32_bf16 v[110:113], v[138:141], v[204:207], v[108:111]
	v_mfma_f32_16x16x32_bf16 v[106:109], v[166:169], v[204:207], v[104:107]
	s_barrier
	s_add_i32 s1, 0, 0x1c000
	v_add_u32_e32 v104, s1, v176
	s_add_i32 s0, s0, s9
	ds_read_b128 v[208:211], v104
	ds_read_b128 v[212:215], v104 offset:1024
	ds_read_b128 v[216:219], v104 offset:2048
	ds_read_b128 v[238:241], v104 offset:3072
	s_add_i32 m0, s0, 0xffffff80
	s_nop 0
	global_load_lds_dwordx4 v[242:243], off offset:128
	s_add_i32 m0, s0, 0x1f80
	s_nop 0
	global_load_lds_dwordx4 v[244:245], off offset:128
	s_barrier
	s_waitcnt lgkmcnt(0)
	s_waitcnt lgkmcnt(0)
	v_mfma_f32_16x16x32_bf16 v[62:65], v[208:211], v[170:173], v[62:65]
	v_mfma_f32_16x16x32_bf16 v[58:61], v[216:219], v[170:173], v[58:61]
	v_mfma_f32_16x16x32_bf16 v[54:57], v[208:211], v[184:187], v[54:57]
	v_mfma_f32_16x16x32_bf16 v[50:53], v[216:219], v[184:187], v[50:53]
	v_mfma_f32_16x16x32_bf16 v[46:49], v[208:211], v[192:195], v[46:49]
	v_mfma_f32_16x16x32_bf16 v[42:45], v[216:219], v[192:195], v[42:45]
	v_mfma_f32_16x16x32_bf16 v[38:41], v[208:211], v[200:203], v[38:41]
	v_mfma_f32_16x16x32_bf16 v[34:37], v[216:219], v[200:203], v[34:37]
	v_mfma_f32_16x16x32_bf16 v[62:65], v[212:215], v[180:183], v[62:65]
	v_mfma_f32_16x16x32_bf16 v[58:61], v[238:241], v[180:183], v[58:61]
	v_mfma_f32_16x16x32_bf16 v[54:57], v[212:215], v[188:191], v[54:57]
	v_mfma_f32_16x16x32_bf16 v[50:53], v[238:241], v[188:191], v[50:53]
	v_mfma_f32_16x16x32_bf16 v[46:49], v[212:215], v[196:199], v[46:49]
	v_mfma_f32_16x16x32_bf16 v[42:45], v[238:241], v[196:199], v[42:45]
	v_mfma_f32_16x16x32_bf16 v[38:41], v[212:215], v[204:207], v[38:41]
	v_mfma_f32_16x16x32_bf16 v[34:37], v[238:241], v[204:207], v[34:37]
	s_add_i32 m0, s54, 0xffffff80
	s_barrier
	ds_read_b128 v[170:173], v178 offset:49152
	ds_read_b128 v[180:183], v178 offset:50176
	ds_read_b128 v[184:187], v178 offset:51200
	ds_read_b128 v[188:191], v178 offset:52224
	ds_read_b128 v[192:195], v178 offset:53248
	ds_read_b128 v[196:199], v178 offset:54272
	ds_read_b128 v[200:203], v178 offset:55296
	ds_read_b128 v[204:207], v178 offset:56320
	global_load_lds_dwordx4 v[246:247], off offset:128
	s_add_i32 m0, s3, 0xffffff80
	s_nop 0
	global_load_lds_dwordx4 v[248:249], off offset:128
	s_barrier
	s_waitcnt lgkmcnt(0)
	s_waitcnt lgkmcnt(0)
	v_mfma_f32_16x16x32_bf16 v[94:97], v[100:103], v[170:173], v[94:97]
	v_mfma_f32_16x16x32_bf16 v[90:93], v[142:145], v[170:173], v[90:93]
	v_mfma_f32_16x16x32_bf16 v[86:89], v[100:103], v[184:187], v[86:89]
	v_mfma_f32_16x16x32_bf16 v[82:85], v[142:145], v[184:187], v[82:85]
	v_mfma_f32_16x16x32_bf16 v[78:81], v[100:103], v[192:195], v[78:81]
	v_mfma_f32_16x16x32_bf16 v[74:77], v[142:145], v[192:195], v[74:77]
	v_mfma_f32_16x16x32_bf16 v[70:73], v[100:103], v[200:203], v[70:73]
	v_mfma_f32_16x16x32_bf16 v[66:69], v[142:145], v[200:203], v[66:69]
	v_mfma_f32_16x16x32_bf16 v[94:97], v[138:141], v[180:183], v[94:97]
	v_mfma_f32_16x16x32_bf16 v[90:93], v[166:169], v[180:183], v[90:93]
	v_mfma_f32_16x16x32_bf16 v[86:89], v[138:141], v[188:191], v[86:89]
	v_mfma_f32_16x16x32_bf16 v[82:85], v[166:169], v[188:191], v[82:85]
	v_mfma_f32_16x16x32_bf16 v[78:81], v[138:141], v[196:199], v[78:81]
	v_mfma_f32_16x16x32_bf16 v[74:77], v[166:169], v[196:199], v[74:77]
	v_mfma_f32_16x16x32_bf16 v[70:73], v[138:141], v[204:207], v[70:73]
	v_mfma_f32_16x16x32_bf16 v[66:69], v[166:169], v[204:207], v[66:69]
	s_barrier
	s_add_i32 s0, s1, s9
	s_add_i32 m0, s0, 0xffffff80
	s_nop 0
	global_load_lds_dwordx4 v[230:231], off offset:128
	s_add_i32 m0, s0, 0x1f80
	s_nop 0
	global_load_lds_dwordx4 v[224:225], off offset:128
	s_waitcnt vmcnt(6)
	s_barrier
	v_mfma_f32_16x16x32_bf16 v[30:33], v[208:211], v[170:173], v[30:33]
	v_mfma_f32_16x16x32_bf16 v[26:29], v[216:219], v[170:173], v[26:29]
	v_mfma_f32_16x16x32_bf16 v[22:25], v[208:211], v[184:187], v[22:25]
	v_mfma_f32_16x16x32_bf16 v[18:21], v[216:219], v[184:187], v[18:21]
	v_mfma_f32_16x16x32_bf16 v[14:17], v[208:211], v[192:195], v[14:17]
	v_mfma_f32_16x16x32_bf16 v[10:13], v[216:219], v[192:195], v[10:13]
	v_mfma_f32_16x16x32_bf16 v[6:9], v[208:211], v[200:203], v[6:9]
	v_mfma_f32_16x16x32_bf16 v[2:5], v[216:219], v[200:203], v[2:5]
	v_mfma_f32_16x16x32_bf16 v[30:33], v[212:215], v[180:183], v[30:33]
	v_mfma_f32_16x16x32_bf16 v[26:29], v[238:241], v[180:183], v[26:29]
	v_mfma_f32_16x16x32_bf16 v[22:25], v[212:215], v[188:191], v[22:25]
	v_mfma_f32_16x16x32_bf16 v[18:21], v[238:241], v[188:191], v[18:21]
	v_mfma_f32_16x16x32_bf16 v[14:17], v[212:215], v[196:199], v[14:17]
	v_mfma_f32_16x16x32_bf16 v[10:13], v[238:241], v[196:199], v[10:13]
	v_mfma_f32_16x16x32_bf16 v[6:9], v[212:215], v[204:207], v[6:9]
	v_mfma_f32_16x16x32_bf16 v[2:5], v[238:241], v[204:207], v[2:5]
	s_add_u32 s4, s4, 0x100
	s_addc_u32 s5, s5, 0
	v_lshl_add_u64 v[98:99], v[98:99], 0, s[86:87]
	s_cmp_ge_u32 s6, s13
	s_mov_b32 s0, s6
	s_barrier
	s_cbranch_scc0 .LBB0_691
	s_and_b64 vcc, exec, s[42:43]
	s_cbranch_vccz .LBB0_694
	ds_read2st64_b32 v[98:99], v179 offset0:6 offset1:7
	ds_read2st64_b32 v[102:103], v179 offset0:4 offset1:5
	ds_read2st64_b32 v[104:105], v179 offset0:2 offset1:3
	ds_read2st64_b32 v[100:101], v179 offset1:1
	v_cmp_lt_i32_e32 vcc, v227, v222
	s_mov_b32 s0, 0x358637bd
	s_mov_b32 s4, 0x3a800000
	v_cndmask_b32_e32 v138, v221, v227, vcc
	v_cmp_lt_i32_e32 vcc, v228, v222
	v_lshlrev_b32_e32 v142, 2, v138
	s_waitcnt lgkmcnt(0)
	ds_bpermute_b32 v139, v142, v101
	v_cndmask_b32_e32 v138, v221, v228, vcc
	v_lshlrev_b32_e32 v143, 2, v138
	ds_bpermute_b32 v138, v142, v100
	s_mov_b32 s6, 0x45800000
	s_waitcnt lgkmcnt(0)
	v_pk_add_f32 v[100:101], v[100:101], v[138:139]
	ds_bpermute_b32 v138, v143, v100
	ds_bpermute_b32 v139, v143, v101
	s_waitcnt lgkmcnt(0)
	v_pk_add_f32 v[138:139], v[100:101], v[138:139]
	v_mov_b64_e32 v[100:101], s[0:1]
	v_pk_fma_f32 v[138:139], v[138:139], s[4:5], v[100:101] op_sel_hi:[1,0,0]
	s_nop 0
	v_mul_f32_e32 v140, 0x4b800000, v138
	v_cmp_gt_f32_e64 s[0:1], s88, v138
	v_cmp_gt_f32_e32 vcc, s88, v139
	s_nop 0
	v_cndmask_b32_e64 v138, v138, v140, s[0:1]
	v_mul_f32_e32 v140, 0x4b800000, v139
	v_cndmask_b32_e32 v139, v139, v140, vcc
	v_rsq_f32_e32 v138, v138
	v_rsq_f32_e32 v139, v139
	s_nop 0
	v_pk_mul_f32 v[140:141], v[138:139], s[6:7] op_sel_hi:[1,0]
	s_nop 0
	v_cndmask_b32_e64 v174, v138, v140, s[0:1]
	v_cndmask_b32_e32 v175, v139, v141, vcc
	ds_bpermute_b32 v138, v142, v104
	ds_bpermute_b32 v139, v142, v105
	s_waitcnt lgkmcnt(0)
	v_pk_add_f32 v[104:105], v[104:105], v[138:139]
	ds_bpermute_b32 v138, v143, v104
	ds_bpermute_b32 v139, v143, v105
	s_waitcnt lgkmcnt(0)
	v_pk_add_f32 v[104:105], v[104:105], v[138:139]
	s_nop 0
	v_pk_fma_f32 v[104:105], v[104:105], s[4:5], v[100:101] op_sel_hi:[1,0,0]
	s_nop 0
	v_mul_f32_e32 v138, 0x4b800000, v104
	v_cmp_gt_f32_e64 s[0:1], s88, v104
	v_cmp_gt_f32_e32 vcc, s88, v105
	s_nop 0
	v_cndmask_b32_e64 v104, v104, v138, s[0:1]
	v_mul_f32_e32 v138, 0x4b800000, v105
	v_cndmask_b32_e32 v105, v105, v138, vcc
	v_rsq_f32_e32 v104, v104
	v_rsq_f32_e32 v105, v105
	s_nop 0
	v_pk_mul_f32 v[138:139], v[104:105], s[6:7] op_sel_hi:[1,0]
	s_nop 0
	v_cndmask_b32_e64 v172, v104, v138, s[0:1]
	v_cndmask_b32_e32 v173, v105, v139, vcc
	ds_bpermute_b32 v104, v142, v102
	ds_bpermute_b32 v105, v142, v103
	s_waitcnt lgkmcnt(0)
	v_pk_add_f32 v[102:103], v[102:103], v[104:105]
	ds_bpermute_b32 v104, v143, v102
	ds_bpermute_b32 v105, v143, v103
	s_waitcnt lgkmcnt(0)
	v_pk_add_f32 v[102:103], v[102:103], v[104:105]
	s_nop 0
	v_pk_fma_f32 v[102:103], v[102:103], s[4:5], v[100:101] op_sel_hi:[1,0,0]
	s_nop 0
	v_mul_f32_e32 v104, 0x4b800000, v102
	v_cmp_gt_f32_e64 s[0:1], s88, v102
	v_cmp_gt_f32_e32 vcc, s88, v103
	s_nop 0
	v_cndmask_b32_e64 v102, v102, v104, s[0:1]
	v_mul_f32_e32 v104, 0x4b800000, v103
	v_cndmask_b32_e32 v103, v103, v104, vcc
	v_rsq_f32_e32 v102, v102
	v_rsq_f32_e32 v103, v103
	s_nop 0
	v_pk_mul_f32 v[104:105], v[102:103], s[6:7] op_sel_hi:[1,0]
	s_nop 0
	v_cndmask_b32_e64 v170, v102, v104, s[0:1]
	v_cndmask_b32_e32 v171, v103, v105, vcc
	ds_bpermute_b32 v102, v142, v98
	ds_bpermute_b32 v103, v142, v99
	s_waitcnt lgkmcnt(0)
	v_pk_add_f32 v[98:99], v[98:99], v[102:103]
	ds_bpermute_b32 v102, v143, v98
	ds_bpermute_b32 v103, v143, v99
	s_waitcnt lgkmcnt(0)
	v_pk_add_f32 v[98:99], v[98:99], v[102:103]
	s_nop 0
	v_pk_fma_f32 v[98:99], v[98:99], s[4:5], v[100:101] op_sel_hi:[1,0,0]
	s_nop 0
	v_mul_f32_e32 v100, 0x4b800000, v98
	v_cmp_gt_f32_e64 s[0:1], s88, v98
	v_cmp_gt_f32_e32 vcc, s88, v99
	s_nop 0
	v_cndmask_b32_e64 v98, v98, v100, s[0:1]
	v_mul_f32_e32 v100, 0x4b800000, v99
	v_cndmask_b32_e32 v99, v99, v100, vcc
	v_rsq_f32_e32 v98, v98
	v_rsq_f32_e32 v99, v99
	s_nop 0
	v_pk_mul_f32 v[100:101], v[98:99], s[6:7] op_sel_hi:[1,0]
	s_nop 0
	v_cndmask_b32_e64 v168, v98, v100, s[0:1]
	v_cndmask_b32_e32 v169, v99, v101, vcc
	s_branch .LBB0_695

.LBB0_814:
	v_mov_b32_e32 v137, v0
	s_add_i32 m0, s28, 0x17f80
	v_lshl_add_u64 v[20:21], v[2:3], 0, v[136:137]
	v_mov_b32_e32 v133, v0
	s_waitcnt vmcnt(4)
	s_barrier
	global_load_lds_dwordx4 v[4:5], off offset:128
	s_add_i32 m0, s28, 0x19f80
	s_add_i32 s36, s28, 0x8000
	v_lshl_add_u64 v[22:23], v[2:3], 0, v[132:133]
	global_load_lds_dwordx4 v[6:7], off offset:128
	s_add_i32 m0, s36, 0xffffff80
	s_add_i32 s42, s28, 0xa000
	global_load_lds_dwordx4 v[20:21], off offset:128
	s_add_i32 m0, s42, 0xffffff80
	v_bfe_u32 v7, v12, 4, 2
	global_load_lds_dwordx4 v[22:23], off offset:128
	s_add_i32 m0, s28, 0x1bf80
	global_load_lds_dwordx4 v[8:9], off offset:128
	s_add_i32 m0, s28, 0x1df80
	v_and_b32_e32 v6, 63, v12
	global_load_lds_dwordx4 v[10:11], off offset:128
	v_and_b32_e32 v4, 15, v12
	v_and_b32_e32 v5, 48, v12
	v_lshl_or_b32 v1, s1, 6, v4
	v_lshl_or_b32 v4, v4, 6, v5
	v_lshlrev_b32_e32 v5, 2, v12
	s_lshl_b32 s1, s1, 13
	v_and_b32_e32 v5, 32, v5
	v_bitop3_b32 v8, v4, s1, v5 bitop3:0xde
	s_lshl_b32 s1, s0, 5
	s_and_b32 s1, s1, 0x60
	s_lshl_b32 s6, s1, 7
	v_bitop3_b32 v153, s6, v4, v5 bitop3:0xf6
	v_readlane_b32 s6, v250, 12
	v_lshlrev_b32_e32 v4, 2, v7
	v_mov_b32_e32 v5, v0
	v_readlane_b32 s7, v250, 13
	s_lshl_b32 s0, s0, 11
	s_waitcnt vmcnt(6)
	s_add_i32 s43, s0, 0
	v_lshl_add_u64 v[138:139], s[6:7], 0, v[4:5]
	v_add_u32_e32 v4, v18, v16
	v_add_lshl_u32 v4, v4, v17, 1
	v_lshl_add_u64 v[140:141], s[94:95], 0, v[4:5]
	v_add_u32_e32 v4, v15, v13
	s_add_i32 s43, s43, 0x22100
	v_lshlrev_b32_e32 v6, 2, v6
	v_add_lshl_u32 v4, v4, v14, 1
	s_add_i32 s44, s13, -2
	s_ashr_i32 s45, s37, 31
	s_mov_b32 s25, s95
	v_lshl_or_b32 v155, v7, 3, s1
	v_lshl_add_u64 v[142:143], s[94:95], 0, v[4:5]
	s_mov_b32 s54, 0
	v_add_u32_e32 v157, 0, v8
	v_add_u32_e32 v161, s43, v6
	s_movk_i32 s89, 0x1600
	s_barrier

.LBB0_824:
	s_add_i32 s7, 0, 0x10000
	v_add_u32_e32 v145, s7, v153
	ds_read_b128 v[162:165], v145
	ds_read_b128 v[166:169], v145 offset:1024
	ds_read_b128 v[170:173], v145 offset:2048
	ds_read_b128 v[174:177], v145 offset:3072
	s_add_i32 s6, s0, 2
	s_cmp_eq_u32 s44, s0
	v_lshl_add_u64 v[150:151], v[148:149], 0, s[84:85]
	s_cselect_b64 vcc, -1, 0
	s_cselect_b32 s0, s22, s4
	v_cndmask_b32_e32 v151, v151, v147, vcc
	v_cndmask_b32_e32 v150, v150, v146, vcc
	s_cselect_b32 s1, s23, s5
	v_lshl_add_u64 v[210:211], v[148:149], 0, v[140:141]
	s_add_i32 m0, s28, 0xc000
	ds_read_b128 v[178:181], v157
	ds_read_b128 v[182:185], v157 offset:1024
	ds_read_b128 v[186:189], v157 offset:2048
	ds_read_b128 v[190:193], v157 offset:3072
	ds_read_b128 v[194:197], v157 offset:4096
	ds_read_b128 v[198:201], v157 offset:5120
	ds_read_b128 v[202:205], v157 offset:6144
	ds_read_b128 v[206:209], v157 offset:7168
	global_load_lds_dwordx4 v[210:211], off
	v_lshl_add_u64 v[210:211], v[148:149], 0, v[142:143]
	s_add_i32 m0, s28, 0xe000
	s_nop 0
	global_load_lds_dwordx4 v[210:211], off
	s_waitcnt lgkmcnt(8)
	s_barrier
	s_waitcnt lgkmcnt(0)
	s_waitcnt lgkmcnt(0)
	v_mfma_f32_16x16x32_bf16 v[126:129], v[162:165], v[178:181], v[126:129]
	v_mfma_f32_16x16x32_bf16 v[118:121], v[170:173], v[178:181], v[118:121]
	v_mfma_f32_16x16x32_bf16 v[110:113], v[162:165], v[186:189], v[110:113]
	v_mfma_f32_16x16x32_bf16 v[102:105], v[170:173], v[186:189], v[102:105]
	v_mfma_f32_16x16x32_bf16 v[94:97], v[162:165], v[194:197], v[94:97]
	v_mfma_f32_16x16x32_bf16 v[86:89], v[170:173], v[194:197], v[86:89]
	v_mfma_f32_16x16x32_bf16 v[78:81], v[162:165], v[202:205], v[78:81]
	v_mfma_f32_16x16x32_bf16 v[70:73], v[170:173], v[202:205], v[70:73]
	v_mfma_f32_16x16x32_bf16 v[126:129], v[166:169], v[182:185], v[126:129]
	v_mfma_f32_16x16x32_bf16 v[118:121], v[174:177], v[182:185], v[118:121]
	v_mfma_f32_16x16x32_bf16 v[110:113], v[166:169], v[190:193], v[110:113]
	v_mfma_f32_16x16x32_bf16 v[102:105], v[174:177], v[190:193], v[102:105]
	v_mfma_f32_16x16x32_bf16 v[94:97], v[166:169], v[198:201], v[94:97]
	v_mfma_f32_16x16x32_bf16 v[86:89], v[174:177], v[198:201], v[86:89]
	v_mfma_f32_16x16x32_bf16 v[78:81], v[166:169], v[206:209], v[78:81]
	v_mfma_f32_16x16x32_bf16 v[70:73], v[174:177], v[206:209], v[70:73]
	s_barrier
	s_add_i32 s40, 0, 0x14000
	s_add_i32 s7, s7, s3
	v_add_u32_e32 v145, s40, v153
	v_lshl_add_u64 v[218:219], s[0:1], 0, v[134:135]
	s_mov_b32 m0, s7
	ds_read_b128 v[210:213], v145
	ds_read_b128 v[214:217], v145 offset:1024
	ds_read_b128 v[238:241], v145 offset:2048
	ds_read_b128 v[242:245], v145 offset:3072
	global_load_lds_dwordx4 v[218:219], off
	v_lshl_add_u64 v[224:225], s[0:1], 0, v[130:131]
	s_add_i32 m0, s7, 0x2000
	s_nop 0
	global_load_lds_dwordx4 v[224:225], off
	s_barrier
	s_waitcnt lgkmcnt(0)
	s_waitcnt lgkmcnt(0)
	v_mfma_f32_16x16x32_bf16 v[122:125], v[210:213], v[178:181], v[122:125]
	v_mfma_f32_16x16x32_bf16 v[114:117], v[238:241], v[178:181], v[114:117]
	v_mfma_f32_16x16x32_bf16 v[106:109], v[210:213], v[186:189], v[106:109]
	v_mfma_f32_16x16x32_bf16 v[98:101], v[238:241], v[186:189], v[98:101]
	v_mfma_f32_16x16x32_bf16 v[90:93], v[210:213], v[194:197], v[90:93]
	v_mfma_f32_16x16x32_bf16 v[82:85], v[238:241], v[194:197], v[82:85]
	v_mfma_f32_16x16x32_bf16 v[74:77], v[210:213], v[202:205], v[74:77]
	v_mfma_f32_16x16x32_bf16 v[66:69], v[238:241], v[202:205], v[66:69]
	v_mfma_f32_16x16x32_bf16 v[122:125], v[214:217], v[182:185], v[122:125]
	v_mfma_f32_16x16x32_bf16 v[114:117], v[242:245], v[182:185], v[114:117]
	v_mfma_f32_16x16x32_bf16 v[106:109], v[214:217], v[190:193], v[106:109]
	v_mfma_f32_16x16x32_bf16 v[98:101], v[242:245], v[190:193], v[98:101]
	v_mfma_f32_16x16x32_bf16 v[90:93], v[214:217], v[198:201], v[90:93]
	v_mfma_f32_16x16x32_bf16 v[82:85], v[242:245], v[198:201], v[82:85]
	v_mfma_f32_16x16x32_bf16 v[74:77], v[214:217], v[206:209], v[74:77]
	v_mfma_f32_16x16x32_bf16 v[66:69], v[242:245], v[206:209], v[66:69]
	s_mov_b32 m0, s28
	v_lshl_add_u64 v[230:231], v[150:151], 0, v[136:137]
	s_barrier
	ds_read_b128 v[178:181], v157 offset:16384
	ds_read_b128 v[182:185], v157 offset:17408
	ds_read_b128 v[186:189], v157 offset:18432
	ds_read_b128 v[190:193], v157 offset:19456
	ds_read_b128 v[194:197], v157 offset:20480
	ds_read_b128 v[198:201], v157 offset:21504
	ds_read_b128 v[202:205], v157 offset:22528
	ds_read_b128 v[206:209], v157 offset:23552
	global_load_lds_dwordx4 v[230:231], off
	v_lshl_add_u64 v[246:247], v[150:151], 0, v[132:133]
	s_mov_b32 m0, s29
	s_nop 0
	global_load_lds_dwordx4 v[246:247], off
	s_barrier
	s_waitcnt lgkmcnt(0)
	s_waitcnt lgkmcnt(0)
	v_mfma_f32_16x16x32_bf16 v[58:61], v[162:165], v[178:181], v[58:61]
	v_mfma_f32_16x16x32_bf16 v[50:53], v[170:173], v[178:181], v[50:53]
	v_mfma_f32_16x16x32_bf16 v[42:45], v[162:165], v[186:189], v[42:45]
	v_mfma_f32_16x16x32_bf16 v[34:37], v[170:173], v[186:189], v[34:37]
	v_mfma_f32_16x16x32_bf16 v[26:29], v[162:165], v[194:197], v[26:29]
	v_mfma_f32_16x16x32_bf16 v[18:21], v[170:173], v[194:197], v[18:21]
	v_mfma_f32_16x16x32_bf16 v[6:9], v[162:165], v[202:205], v[6:9]
	v_mfma_f32_16x16x32_bf16 v[2:5], v[170:173], v[202:205], v[2:5]
	v_mfma_f32_16x16x32_bf16 v[58:61], v[166:169], v[182:185], v[58:61]
	v_mfma_f32_16x16x32_bf16 v[50:53], v[174:177], v[182:185], v[50:53]
	v_mfma_f32_16x16x32_bf16 v[42:45], v[166:169], v[190:193], v[42:45]
	v_mfma_f32_16x16x32_bf16 v[34:37], v[174:177], v[190:193], v[34:37]
	v_mfma_f32_16x16x32_bf16 v[26:29], v[166:169], v[198:201], v[26:29]
	v_mfma_f32_16x16x32_bf16 v[18:21], v[174:177], v[198:201], v[18:21]
	v_mfma_f32_16x16x32_bf16 v[6:9], v[166:169], v[206:209], v[6:9]
	v_mfma_f32_16x16x32_bf16 v[2:5], v[174:177], v[206:209], v[2:5]
	s_barrier
	s_add_u32 s0, s0, s94
	s_addc_u32 s1, s1, 0
	s_add_i32 s7, s40, s3
	v_lshl_add_u64 v[248:249], s[0:1], 0, v[134:135]
	s_mov_b32 m0, s7
	v_lshl_add_u64 v[232:233], s[0:1], 0, v[130:131]
	global_load_lds_dwordx4 v[248:249], off
	s_add_i32 m0, s7, 0x2000
	s_nop 0
	global_load_lds_dwordx4 v[232:233], off
	s_waitcnt vmcnt(6)
	s_barrier
	v_mfma_f32_16x16x32_bf16 v[62:65], v[210:213], v[178:181], v[62:65]
	v_mfma_f32_16x16x32_bf16 v[54:57], v[238:241], v[178:181], v[54:57]
	v_mfma_f32_16x16x32_bf16 v[46:49], v[210:213], v[186:189], v[46:49]
	v_mfma_f32_16x16x32_bf16 v[38:41], v[238:241], v[186:189], v[38:41]
	v_mfma_f32_16x16x32_bf16 v[30:33], v[210:213], v[194:197], v[30:33]
	v_mfma_f32_16x16x32_bf16 v[22:25], v[238:241], v[194:197], v[22:25]
	v_mfma_f32_16x16x32_bf16 v[14:17], v[210:213], v[202:205], v[14:17]
	v_mfma_f32_16x16x32_bf16 v[10:13], v[238:241], v[202:205], v[10:13]
	v_mfma_f32_16x16x32_bf16 v[62:65], v[214:217], v[182:185], v[62:65]
	v_mfma_f32_16x16x32_bf16 v[54:57], v[242:245], v[182:185], v[54:57]
	v_mfma_f32_16x16x32_bf16 v[46:49], v[214:217], v[190:193], v[46:49]
	v_mfma_f32_16x16x32_bf16 v[38:41], v[242:245], v[190:193], v[38:41]
	v_mfma_f32_16x16x32_bf16 v[30:33], v[214:217], v[198:201], v[30:33]
	v_mfma_f32_16x16x32_bf16 v[22:25], v[242:245], v[198:201], v[22:25]
	v_mfma_f32_16x16x32_bf16 v[14:17], v[214:217], v[206:209], v[14:17]
	v_mfma_f32_16x16x32_bf16 v[10:13], v[242:245], v[206:209], v[10:13]
	s_add_i32 s0, 0, 0x18000
	v_add_u32_e32 v145, s0, v153
	s_barrier
	ds_read_b128 v[162:165], v145
	ds_read_b128 v[166:169], v145 offset:1024
	ds_read_b128 v[170:173], v145 offset:2048
	ds_read_b128 v[174:177], v145 offset:3072
	v_lshl_add_u64 v[150:151], v[150:151], 0, s[94:95]
	s_mov_b32 m0, s34
	v_lshl_add_u64 v[210:211], v[150:151], 0, v[136:137]
	ds_read_b128 v[178:181], v157 offset:32768
	ds_read_b128 v[182:185], v157 offset:33792
	ds_read_b128 v[186:189], v157 offset:34816
	ds_read_b128 v[190:193], v157 offset:35840
	ds_read_b128 v[194:197], v157 offset:36864
	ds_read_b128 v[198:201], v157 offset:37888
	ds_read_b128 v[202:205], v157 offset:38912
	ds_read_b128 v[206:209], v157 offset:39936
	global_load_lds_dwordx4 v[210:211], off
	v_lshl_add_u64 v[150:151], v[150:151], 0, v[132:133]
	s_mov_b32 m0, s35
	s_nop 0
	global_load_lds_dwordx4 v[150:151], off
	s_waitcnt lgkmcnt(8)
	s_barrier
	s_waitcnt lgkmcnt(0)
	s_waitcnt lgkmcnt(0)
	v_mfma_f32_16x16x32_bf16 v[126:129], v[162:165], v[178:181], v[126:129]
	v_mfma_f32_16x16x32_bf16 v[118:121], v[170:173], v[178:181], v[118:121]
	v_mfma_f32_16x16x32_bf16 v[110:113], v[162:165], v[186:189], v[110:113]
	v_mfma_f32_16x16x32_bf16 v[102:105], v[170:173], v[186:189], v[102:105]
	v_mfma_f32_16x16x32_bf16 v[94:97], v[162:165], v[194:197], v[94:97]
	v_mfma_f32_16x16x32_bf16 v[86:89], v[170:173], v[194:197], v[86:89]
	v_mfma_f32_16x16x32_bf16 v[78:81], v[162:165], v[202:205], v[78:81]
	v_mfma_f32_16x16x32_bf16 v[70:73], v[170:173], v[202:205], v[70:73]
	v_mfma_f32_16x16x32_bf16 v[126:129], v[166:169], v[182:185], v[126:129]
	v_mfma_f32_16x16x32_bf16 v[118:121], v[174:177], v[182:185], v[118:121]
	v_mfma_f32_16x16x32_bf16 v[110:113], v[166:169], v[190:193], v[110:113]
	v_mfma_f32_16x16x32_bf16 v[102:105], v[174:177], v[190:193], v[102:105]
	v_mfma_f32_16x16x32_bf16 v[94:97], v[166:169], v[198:201], v[94:97]
	v_mfma_f32_16x16x32_bf16 v[86:89], v[174:177], v[198:201], v[86:89]
	v_mfma_f32_16x16x32_bf16 v[78:81], v[166:169], v[206:209], v[78:81]
	v_mfma_f32_16x16x32_bf16 v[70:73], v[174:177], v[206:209], v[70:73]
	s_barrier
	s_add_i32 s1, 0, 0x1c000
	s_add_i32 s0, s0, s3
	v_add_u32_e32 v145, s1, v153
	s_add_i32 m0, s0, 0xffffff80
	ds_read_b128 v[210:213], v145
	ds_read_b128 v[214:217], v145 offset:1024
	ds_read_b128 v[238:241], v145 offset:2048
	ds_read_b128 v[242:245], v145 offset:3072
	global_load_lds_dwordx4 v[218:219], off offset:128
	s_add_i32 m0, s0, 0x1f80
	s_nop 0
	global_load_lds_dwordx4 v[224:225], off offset:128
	s_barrier
	s_waitcnt lgkmcnt(0)
	s_waitcnt lgkmcnt(0)
	v_mfma_f32_16x16x32_bf16 v[122:125], v[210:213], v[178:181], v[122:125]
	v_mfma_f32_16x16x32_bf16 v[114:117], v[238:241], v[178:181], v[114:117]
	v_mfma_f32_16x16x32_bf16 v[106:109], v[210:213], v[186:189], v[106:109]
	v_mfma_f32_16x16x32_bf16 v[98:101], v[238:241], v[186:189], v[98:101]
	v_mfma_f32_16x16x32_bf16 v[90:93], v[210:213], v[194:197], v[90:93]
	v_mfma_f32_16x16x32_bf16 v[82:85], v[238:241], v[194:197], v[82:85]
	v_mfma_f32_16x16x32_bf16 v[74:77], v[210:213], v[202:205], v[74:77]
	v_mfma_f32_16x16x32_bf16 v[66:69], v[238:241], v[202:205], v[66:69]
	v_mfma_f32_16x16x32_bf16 v[122:125], v[214:217], v[182:185], v[122:125]
	v_mfma_f32_16x16x32_bf16 v[114:117], v[242:245], v[182:185], v[114:117]
	v_mfma_f32_16x16x32_bf16 v[106:109], v[214:217], v[190:193], v[106:109]
	v_mfma_f32_16x16x32_bf16 v[98:101], v[242:245], v[190:193], v[98:101]
	v_mfma_f32_16x16x32_bf16 v[90:93], v[214:217], v[198:201], v[90:93]
	v_mfma_f32_16x16x32_bf16 v[82:85], v[242:245], v[198:201], v[82:85]
	v_mfma_f32_16x16x32_bf16 v[74:77], v[214:217], v[206:209], v[74:77]
	v_mfma_f32_16x16x32_bf16 v[66:69], v[242:245], v[206:209], v[66:69]
	s_add_i32 m0, s36, 0xffffff80
	s_barrier
	ds_read_b128 v[178:181], v157 offset:49152
	ds_read_b128 v[182:185], v157 offset:50176
	ds_read_b128 v[186:189], v157 offset:51200
	ds_read_b128 v[190:193], v157 offset:52224
	ds_read_b128 v[194:197], v157 offset:53248
	ds_read_b128 v[198:201], v157 offset:54272
	ds_read_b128 v[202:205], v157 offset:55296
	ds_read_b128 v[206:209], v157 offset:56320
	global_load_lds_dwordx4 v[230:231], off offset:128
	s_add_i32 m0, s42, 0xffffff80
	s_nop 0
	global_load_lds_dwordx4 v[246:247], off offset:128
	s_barrier
	s_waitcnt lgkmcnt(0)
	s_waitcnt lgkmcnt(0)
	v_mfma_f32_16x16x32_bf16 v[58:61], v[162:165], v[178:181], v[58:61]
	v_mfma_f32_16x16x32_bf16 v[50:53], v[170:173], v[178:181], v[50:53]
	v_mfma_f32_16x16x32_bf16 v[42:45], v[162:165], v[186:189], v[42:45]
	v_mfma_f32_16x16x32_bf16 v[34:37], v[170:173], v[186:189], v[34:37]
	v_mfma_f32_16x16x32_bf16 v[26:29], v[162:165], v[194:197], v[26:29]
	v_mfma_f32_16x16x32_bf16 v[18:21], v[170:173], v[194:197], v[18:21]
	v_mfma_f32_16x16x32_bf16 v[6:9], v[162:165], v[202:205], v[6:9]
	v_mfma_f32_16x16x32_bf16 v[2:5], v[170:173], v[202:205], v[2:5]
	v_mfma_f32_16x16x32_bf16 v[58:61], v[166:169], v[182:185], v[58:61]
	v_mfma_f32_16x16x32_bf16 v[50:53], v[174:177], v[182:185], v[50:53]
	v_mfma_f32_16x16x32_bf16 v[42:45], v[166:169], v[190:193], v[42:45]
	v_mfma_f32_16x16x32_bf16 v[34:37], v[174:177], v[190:193], v[34:37]
	v_mfma_f32_16x16x32_bf16 v[26:29], v[166:169], v[198:201], v[26:29]
	v_mfma_f32_16x16x32_bf16 v[18:21], v[174:177], v[198:201], v[18:21]
	v_mfma_f32_16x16x32_bf16 v[6:9], v[166:169], v[206:209], v[6:9]
	v_mfma_f32_16x16x32_bf16 v[2:5], v[174:177], v[206:209], v[2:5]
	s_barrier
	s_add_i32 s0, s1, s3
	s_add_i32 m0, s0, 0xffffff80
	s_nop 0
	global_load_lds_dwordx4 v[248:249], off offset:128
	s_add_i32 m0, s0, 0x1f80
	s_nop 0
	global_load_lds_dwordx4 v[232:233], off offset:128
	s_waitcnt vmcnt(6)
	s_barrier
	v_mfma_f32_16x16x32_bf16 v[62:65], v[210:213], v[178:181], v[62:65]
	v_mfma_f32_16x16x32_bf16 v[54:57], v[238:241], v[178:181], v[54:57]
	v_mfma_f32_16x16x32_bf16 v[46:49], v[210:213], v[186:189], v[46:49]
	v_mfma_f32_16x16x32_bf16 v[38:41], v[238:241], v[186:189], v[38:41]
	v_mfma_f32_16x16x32_bf16 v[30:33], v[210:213], v[194:197], v[30:33]
	v_mfma_f32_16x16x32_bf16 v[22:25], v[238:241], v[194:197], v[22:25]
	v_mfma_f32_16x16x32_bf16 v[14:17], v[210:213], v[202:205], v[14:17]
	v_mfma_f32_16x16x32_bf16 v[10:13], v[238:241], v[202:205], v[10:13]
	v_mfma_f32_16x16x32_bf16 v[62:65], v[214:217], v[182:185], v[62:65]
	v_mfma_f32_16x16x32_bf16 v[54:57], v[242:245], v[182:185], v[54:57]
	v_mfma_f32_16x16x32_bf16 v[46:49], v[214:217], v[190:193], v[46:49]
	v_mfma_f32_16x16x32_bf16 v[38:41], v[242:245], v[190:193], v[38:41]
	v_mfma_f32_16x16x32_bf16 v[30:33], v[214:217], v[198:201], v[30:33]
	v_mfma_f32_16x16x32_bf16 v[22:25], v[242:245], v[198:201], v[22:25]
	v_mfma_f32_16x16x32_bf16 v[14:17], v[214:217], v[206:209], v[14:17]
	v_mfma_f32_16x16x32_bf16 v[10:13], v[242:245], v[206:209], v[10:13]
	s_add_u32 s4, s4, 0x100
	s_addc_u32 s5, s5, 0
	v_lshl_add_u64 v[148:149], v[148:149], 0, s[86:87]
	s_cmp_ge_u32 s6, s13
	s_mov_b32 s0, s6
	s_barrier
	s_cbranch_scc0 .LBB0_824
	v_cmp_lt_i32_e32 vcc, v227, v222
	ds_read2st64_b32 v[150:151], v161 offset1:1
	ds_read2st64_b32 v[168:169], v161 offset0:2 offset1:3
	ds_read2st64_b32 v[170:171], v161 offset0:4 offset1:5
	ds_read2st64_b32 v[148:149], v161 offset0:6 offset1:7
	v_cndmask_b32_e32 v145, v221, v227, vcc
	v_cmp_lt_i32_e32 vcc, v228, v222
	s_mov_b32 s0, 0x358637bd
	v_lshlrev_b32_e32 v145, 2, v145
	s_mov_b32 s4, 0x3a800000
	v_lshl_or_b32 v164, s17, 7, v155
	v_cndmask_b32_e32 v224, v221, v228, vcc
	v_mov_b32_e32 v180, s0
	v_lshlrev_b32_e32 v224, 2, v224
	s_mov_b32 s17, s90
	s_mov_b32 s40, s91
	s_waitcnt lgkmcnt(0)
	ds_bpermute_b32 v172, v145, v150
	ds_bpermute_b32 v173, v145, v151
	ds_bpermute_b32 v174, v145, v168
	ds_bpermute_b32 v175, v145, v169
	ds_bpermute_b32 v176, v145, v170
	ds_bpermute_b32 v177, v145, v171
	ds_bpermute_b32 v178, v145, v148
	ds_bpermute_b32 v179, v145, v149
	v_ashrrev_i32_e32 v165, 31, v164
	v_mov_b64_e32 v[212:213], s[20:21]
	v_lshlrev_b64 v[216:217], 1, v[164:165]
	v_mad_i64_i32 v[212:213], vcc, v144, s89, v[212:213]
	s_waitcnt lgkmcnt(0)
	v_pk_add_f32 v[150:151], v[150:151], v[172:173]
	v_pk_add_f32 v[168:169], v[168:169], v[174:175]
	v_pk_add_f32 v[170:171], v[170:171], v[176:177]
	v_pk_add_f32 v[148:149], v[148:149], v[178:179]
	s_waitcnt lgkmcnt(0)
	ds_bpermute_b32 v172, v224, v150
	ds_bpermute_b32 v173, v224, v151
	ds_bpermute_b32 v174, v224, v168
	ds_bpermute_b32 v175, v224, v169
	ds_bpermute_b32 v176, v224, v170
	ds_bpermute_b32 v177, v224, v171
	ds_bpermute_b32 v178, v224, v148
	ds_bpermute_b32 v179, v224, v149
	v_mov_b64_e32 v[218:219], 0
	v_lshl_add_u64 v[212:213], v[212:213], 0, v[216:217]
	s_waitcnt lgkmcnt(0)
	v_pk_add_f32 v[150:151], v[150:151], v[172:173]
	v_pk_add_f32 v[168:169], v[168:169], v[174:175]
	v_pk_add_f32 v[170:171], v[170:171], v[176:177]
	v_pk_add_f32 v[148:149], v[148:149], v[178:179]
	v_pk_fma_f32 v[150:151], v[150:151], s[4:5], v[180:181] op_sel_hi:[1,0,0]
	v_pk_fma_f32 v[168:169], v[168:169], s[4:5], v[180:181] op_sel_hi:[1,0,0]
	v_pk_fma_f32 v[170:171], v[170:171], s[4:5], v[180:181] op_sel_hi:[1,0,0]
	v_pk_fma_f32 v[148:149], v[148:149], s[4:5], v[180:181] op_sel_hi:[1,0,0]
	s_mov_b32 s0, 0xbfb8aa3b
	v_rsq_f32_e32 v150, v150
	v_rsq_f32_e32 v151, v151
	v_rsq_f32_e32 v168, v168
	v_rsq_f32_e32 v169, v169
	v_rsq_f32_e32 v170, v170
	v_rsq_f32_e32 v171, v171
	v_rsq_f32_e32 v148, v148
	v_rsq_f32_e32 v149, v149
	v_pk_mul_f32 v[126:127], v[126:127], v[150:151] op_sel_hi:[1,0]
	v_pk_mul_f32 v[128:129], v[128:129], v[150:151] op_sel_hi:[1,0]
	v_pk_mul_f32 v[118:119], v[118:119], v[150:151] op_sel_hi:[1,0]
	v_pk_mul_f32 v[120:121], v[120:121], v[150:151] op_sel_hi:[1,0]
	v_pk_mul_f32 v[172:173], v[126:127], s[0:1] op_sel_hi:[1,0]
	v_pk_mul_f32 v[174:175], v[128:129], s[0:1] op_sel_hi:[1,0]
	v_pk_mul_f32 v[176:177], v[118:119], s[0:1] op_sel_hi:[1,0]
	v_pk_mul_f32 v[178:179], v[120:121], s[0:1] op_sel_hi:[1,0]
	v_pk_mul_f32 v[122:123], v[122:123], v[150:151] op_sel_hi:[1,0]
	v_pk_mul_f32 v[124:125], v[124:125], v[150:151] op_sel_hi:[1,0]
	v_pk_mul_f32 v[114:115], v[114:115], v[150:151] op_sel_hi:[1,0]
	v_pk_mul_f32 v[116:117], v[116:117], v[150:151] op_sel_hi:[1,0]
	v_exp_f32_e32 v172, v172
	v_pk_mul_f32 v[110:111], v[110:111], v[150:151] op_sel:[0,1] op_sel_hi:[1,1]
	v_pk_mul_f32 v[112:113], v[112:113], v[150:151] op_sel:[0,1] op_sel_hi:[1,1]
	v_exp_f32_e32 v173, v173
	v_pk_mul_f32 v[102:103], v[102:103], v[150:151] op_sel:[0,1] op_sel_hi:[1,1]
	v_exp_f32_e32 v174, v174
	v_pk_mul_f32 v[104:105], v[104:105], v[150:151] op_sel:[0,1] op_sel_hi:[1,1]
	v_pk_mul_f32 v[180:181], v[110:111], s[0:1] op_sel_hi:[1,0]
	v_exp_f32_e32 v175, v175
	v_pk_mul_f32 v[182:183], v[112:113], s[0:1] op_sel_hi:[1,0]
	v_exp_f32_e32 v176, v176
	v_pk_mul_f32 v[184:185], v[102:103], s[0:1] op_sel_hi:[1,0]
	v_pk_mul_f32 v[186:187], v[104:105], s[0:1] op_sel_hi:[1,0]
	v_exp_f32_e32 v177, v177
	v_pk_mul_f32 v[106:107], v[106:107], v[150:151] op_sel:[0,1] op_sel_hi:[1,1]
	v_exp_f32_e32 v178, v178
	v_pk_mul_f32 v[108:109], v[108:109], v[150:151] op_sel:[0,1] op_sel_hi:[1,1]
	v_pk_mul_f32 v[98:99], v[98:99], v[150:151] op_sel:[0,1] op_sel_hi:[1,1]
	v_exp_f32_e32 v179, v179
	v_pk_mul_f32 v[100:101], v[100:101], v[150:151] op_sel:[0,1] op_sel_hi:[1,1]
	v_exp_f32_e32 v180, v180
	v_pk_mul_f32 v[94:95], v[94:95], v[168:169] op_sel_hi:[1,0]
	v_pk_mul_f32 v[96:97], v[96:97], v[168:169] op_sel_hi:[1,0]
	v_exp_f32_e32 v181, v181
	v_pk_mul_f32 v[86:87], v[86:87], v[168:169] op_sel_hi:[1,0]
	v_pk_mul_f32 v[88:89], v[88:89], v[168:169] op_sel_hi:[1,0]
	v_exp_f32_e32 v182, v182
	v_pk_mul_f32 v[188:189], v[94:95], s[0:1] op_sel_hi:[1,0]
	v_pk_mul_f32 v[190:191], v[96:97], s[0:1] op_sel_hi:[1,0]
	v_exp_f32_e32 v183, v183
	v_pk_mul_f32 v[192:193], v[86:87], s[0:1] op_sel_hi:[1,0]
	v_pk_mul_f32 v[194:195], v[88:89], s[0:1] op_sel_hi:[1,0]
	v_exp_f32_e32 v184, v184
	v_pk_mul_f32 v[90:91], v[90:91], v[168:169] op_sel_hi:[1,0]
	v_pk_mul_f32 v[92:93], v[92:93], v[168:169] op_sel_hi:[1,0]
	v_exp_f32_e32 v185, v185
	v_pk_mul_f32 v[82:83], v[82:83], v[168:169] op_sel_hi:[1,0]
	v_pk_mul_f32 v[84:85], v[84:85], v[168:169] op_sel_hi:[1,0]
	v_exp_f32_e32 v186, v186
	v_pk_add_f32 v[172:173], v[172:173], 1.0 op_sel_hi:[1,0]
	v_pk_add_f32 v[174:175], v[174:175], 1.0 op_sel_hi:[1,0]
	v_exp_f32_e32 v187, v187
	v_pk_add_f32 v[176:177], v[176:177], 1.0 op_sel_hi:[1,0]
	v_pk_add_f32 v[178:179], v[178:179], 1.0 op_sel_hi:[1,0]
	v_exp_f32_e32 v188, v188
	v_pk_mul_f32 v[78:79], v[78:79], v[168:169] op_sel:[0,1] op_sel_hi:[1,1]
	v_rcp_f32_e32 v172, v172
	v_pk_mul_f32 v[80:81], v[80:81], v[168:169] op_sel:[0,1] op_sel_hi:[1,1]
	v_exp_f32_e32 v189, v189
	v_pk_mul_f32 v[70:71], v[70:71], v[168:169] op_sel:[0,1] op_sel_hi:[1,1]
	v_rcp_f32_e32 v173, v173
	v_pk_mul_f32 v[72:73], v[72:73], v[168:169] op_sel:[0,1] op_sel_hi:[1,1]
	v_exp_f32_e32 v190, v190
	v_pk_mul_f32 v[196:197], v[78:79], s[0:1] op_sel_hi:[1,0]
	v_rcp_f32_e32 v174, v174
	v_pk_mul_f32 v[198:199], v[80:81], s[0:1] op_sel_hi:[1,0]
	v_exp_f32_e32 v191, v191
	v_pk_mul_f32 v[200:201], v[70:71], s[0:1] op_sel_hi:[1,0]
	v_rcp_f32_e32 v175, v175
	v_pk_mul_f32 v[202:203], v[72:73], s[0:1] op_sel_hi:[1,0]
	v_exp_f32_e32 v192, v192
	v_pk_mul_f32 v[74:75], v[74:75], v[168:169] op_sel:[0,1] op_sel_hi:[1,1]
	v_rcp_f32_e32 v176, v176
	v_pk_mul_f32 v[76:77], v[76:77], v[168:169] op_sel:[0,1] op_sel_hi:[1,1]
	v_exp_f32_e32 v193, v193
	v_pk_mul_f32 v[66:67], v[66:67], v[168:169] op_sel:[0,1] op_sel_hi:[1,1]
	v_rcp_f32_e32 v177, v177
	v_pk_mul_f32 v[68:69], v[68:69], v[168:169] op_sel:[0,1] op_sel_hi:[1,1]
	v_exp_f32_e32 v194, v194
	v_pk_add_f32 v[180:181], v[180:181], 1.0 op_sel_hi:[1,0]
	v_rcp_f32_e32 v178, v178
	v_pk_add_f32 v[182:183], v[182:183], 1.0 op_sel_hi:[1,0]
	v_exp_f32_e32 v195, v195
	v_pk_add_f32 v[184:185], v[184:185], 1.0 op_sel_hi:[1,0]
	v_rcp_f32_e32 v179, v179
	v_pk_add_f32 v[186:187], v[186:187], 1.0 op_sel_hi:[1,0]
	v_exp_f32_e32 v196, v196
	v_pk_mul_f32 v[58:59], v[58:59], v[170:171] op_sel_hi:[1,0]
	v_pk_mul_f32 v[60:61], v[60:61], v[170:171] op_sel_hi:[1,0]
	v_rcp_f32_e32 v180, v180
	v_pk_mul_f32 v[50:51], v[50:51], v[170:171] op_sel_hi:[1,0]
	v_pk_mul_f32 v[52:53], v[52:53], v[170:171] op_sel_hi:[1,0]
	v_exp_f32_e32 v197, v197
	v_pk_mul_f32 v[204:205], v[58:59], s[0:1] op_sel_hi:[1,0]
	v_pk_mul_f32 v[206:207], v[60:61], s[0:1] op_sel_hi:[1,0]
	v_rcp_f32_e32 v181, v181
	v_pk_mul_f32 v[208:209], v[50:51], s[0:1] op_sel_hi:[1,0]
	v_pk_mul_f32 v[210:211], v[52:53], s[0:1] op_sel_hi:[1,0]
	v_exp_f32_e32 v198, v198
	v_pk_mul_f32 v[62:63], v[62:63], v[170:171] op_sel_hi:[1,0]
	v_pk_mul_f32 v[64:65], v[64:65], v[170:171] op_sel_hi:[1,0]
	v_rcp_f32_e32 v182, v182
	v_pk_mul_f32 v[54:55], v[54:55], v[170:171] op_sel_hi:[1,0]
	v_exp_f32_e32 v199, v199
	v_pk_mul_f32 v[56:57], v[56:57], v[170:171] op_sel_hi:[1,0]
	v_pk_add_f32 v[188:189], v[188:189], 1.0 op_sel_hi:[1,0]
	v_rcp_f32_e32 v183, v183
	v_pk_add_f32 v[190:191], v[190:191], 1.0 op_sel_hi:[1,0]
	v_pk_add_f32 v[192:193], v[192:193], 1.0 op_sel_hi:[1,0]
	v_exp_f32_e32 v200, v200
	v_pk_add_f32 v[194:195], v[194:195], 1.0 op_sel_hi:[1,0]
	v_pk_mul_f32 v[126:127], v[126:127], v[172:173]
	v_rcp_f32_e32 v184, v184
	v_pk_mul_f32 v[128:129], v[128:129], v[174:175]
	v_pk_mul_f32 v[118:119], v[118:119], v[176:177]
	v_exp_f32_e32 v201, v201
	v_pk_mul_f32 v[120:121], v[120:121], v[178:179]
	v_rcp_f32_e32 v185, v185
	v_pk_mul_f32 v[122:123], v[122:123], v[126:127]
	v_pk_mul_f32 v[124:125], v[124:125], v[128:129]
	v_exp_f32_e32 v202, v202
	v_pk_mul_f32 v[114:115], v[114:115], v[118:119]
	v_pk_mul_f32 v[116:117], v[116:117], v[120:121]
	v_rcp_f32_e32 v186, v186
	v_cvt_pk_bf16_f32 v122, v122, v123
	v_cvt_pk_bf16_f32 v123, v124, v125
	v_exp_f32_e32 v203, v203
	v_cvt_pk_bf16_f32 v124, v114, v115
	v_cvt_pk_bf16_f32 v125, v116, v117
	v_rcp_f32_e32 v187, v187
	global_store_dwordx4 v[212:213], v[122:125], off
	v_exp_f32_e32 v204, v204
	v_pk_mul_f32 v[42:43], v[42:43], v[170:171] op_sel:[0,1] op_sel_hi:[1,1]
	v_pk_mul_f32 v[44:45], v[44:45], v[170:171] op_sel:[0,1] op_sel_hi:[1,1]
	v_rcp_f32_e32 v188, v188
	v_pk_mul_f32 v[34:35], v[34:35], v[170:171] op_sel:[0,1] op_sel_hi:[1,1]
	v_pk_mul_f32 v[36:37], v[36:37], v[170:171] op_sel:[0,1] op_sel_hi:[1,1]
	v_exp_f32_e32 v205, v205
	v_pk_mul_f32 v[172:173], v[42:43], s[0:1] op_sel_hi:[1,0]
	v_pk_mul_f32 v[174:175], v[44:45], s[0:1] op_sel_hi:[1,0]
	v_rcp_f32_e32 v189, v189
	v_pk_mul_f32 v[176:177], v[34:35], s[0:1] op_sel_hi:[1,0]
	v_pk_mul_f32 v[178:179], v[36:37], s[0:1] op_sel_hi:[1,0]
	v_exp_f32_e32 v206, v206
	v_pk_mul_f32 v[46:47], v[46:47], v[170:171] op_sel:[0,1] op_sel_hi:[1,1]
	v_pk_mul_f32 v[48:49], v[48:49], v[170:171] op_sel:[0,1] op_sel_hi:[1,1]
	v_rcp_f32_e32 v190, v190
	v_pk_mul_f32 v[38:39], v[38:39], v[170:171] op_sel:[0,1] op_sel_hi:[1,1]
	v_pk_mul_f32 v[40:41], v[40:41], v[170:171] op_sel:[0,1] op_sel_hi:[1,1]
	v_exp_f32_e32 v207, v207
	v_pk_add_f32 v[196:197], v[196:197], 1.0 op_sel_hi:[1,0]
	v_pk_add_f32 v[198:199], v[198:199], 1.0 op_sel_hi:[1,0]
	v_rcp_f32_e32 v191, v191
	v_pk_add_f32 v[200:201], v[200:201], 1.0 op_sel_hi:[1,0]
	v_pk_add_f32 v[202:203], v[202:203], 1.0 op_sel_hi:[1,0]
	v_exp_f32_e32 v208, v208
	v_pk_mul_f32 v[110:111], v[110:111], v[180:181]
	v_pk_mul_f32 v[112:113], v[112:113], v[182:183]
	v_rcp_f32_e32 v192, v192
	v_pk_mul_f32 v[102:103], v[102:103], v[184:185]
	v_pk_mul_f32 v[104:105], v[104:105], v[186:187]
	v_exp_f32_e32 v209, v209
	s_mov_b32 s4, 0x16000
	s_mov_b32 s5, 0
	v_rcp_f32_e32 v193, v193
	v_pk_mul_f32 v[106:107], v[106:107], v[110:111]
	v_pk_mul_f32 v[108:109], v[108:109], v[112:113]
	v_exp_f32_e32 v210, v210
	v_lshl_add_u64 v[214:215], v[212:213], 0, s[4:5]
	v_pk_mul_f32 v[98:99], v[98:99], v[102:103]
	v_rcp_f32_e32 v194, v194
	v_pk_mul_f32 v[100:101], v[100:101], v[104:105]
	v_cvt_pk_bf16_f32 v106, v106, v107
	v_exp_f32_e32 v211, v211
	v_cvt_pk_bf16_f32 v107, v108, v109
	v_cvt_pk_bf16_f32 v108, v98, v99
	v_rcp_f32_e32 v195, v195
	v_cvt_pk_bf16_f32 v109, v100, v101
	global_store_dwordx4 v[214:215], v[106:109], off
	v_exp_f32_e32 v172, v172
	v_pk_mul_f32 v[26:27], v[26:27], v[148:149] op_sel_hi:[1,0]
	v_pk_mul_f32 v[28:29], v[28:29], v[148:149] op_sel_hi:[1,0]
	v_rcp_f32_e32 v196, v196
	v_pk_mul_f32 v[18:19], v[18:19], v[148:149] op_sel_hi:[1,0]
	v_pk_mul_f32 v[20:21], v[20:21], v[148:149] op_sel_hi:[1,0]
	v_exp_f32_e32 v173, v173
	v_pk_mul_f32 v[180:181], v[26:27], s[0:1] op_sel_hi:[1,0]
	v_pk_mul_f32 v[182:183], v[28:29], s[0:1] op_sel_hi:[1,0]
	v_rcp_f32_e32 v197, v197
	v_pk_mul_f32 v[184:185], v[18:19], s[0:1] op_sel_hi:[1,0]
	v_pk_mul_f32 v[186:187], v[20:21], s[0:1] op_sel_hi:[1,0]
	v_exp_f32_e32 v174, v174
	v_pk_mul_f32 v[30:31], v[30:31], v[148:149] op_sel_hi:[1,0]
	v_pk_mul_f32 v[32:33], v[32:33], v[148:149] op_sel_hi:[1,0]
	v_rcp_f32_e32 v198, v198
	v_pk_mul_f32 v[22:23], v[22:23], v[148:149] op_sel_hi:[1,0]
	v_pk_mul_f32 v[24:25], v[24:25], v[148:149] op_sel_hi:[1,0]
	v_exp_f32_e32 v175, v175
	v_pk_add_f32 v[204:205], v[204:205], 1.0 op_sel_hi:[1,0]
	v_pk_add_f32 v[206:207], v[206:207], 1.0 op_sel_hi:[1,0]
	v_rcp_f32_e32 v199, v199
	v_pk_add_f32 v[208:209], v[208:209], 1.0 op_sel_hi:[1,0]
	v_pk_add_f32 v[210:211], v[210:211], 1.0 op_sel_hi:[1,0]
	v_exp_f32_e32 v176, v176
	v_pk_mul_f32 v[94:95], v[94:95], v[188:189]
	v_pk_mul_f32 v[96:97], v[96:97], v[190:191]
	v_rcp_f32_e32 v200, v200
	v_pk_mul_f32 v[86:87], v[86:87], v[192:193]
	v_pk_mul_f32 v[88:89], v[88:89], v[194:195]
	v_exp_f32_e32 v177, v177
	s_mov_b32 s4, 0x16000
	s_mov_b32 s5, 0
	v_rcp_f32_e32 v201, v201
	v_pk_mul_f32 v[90:91], v[90:91], v[94:95]
	v_pk_mul_f32 v[92:93], v[92:93], v[96:97]
	v_exp_f32_e32 v178, v178
	v_lshl_add_u64 v[212:213], v[214:215], 0, s[4:5]
	v_pk_mul_f32 v[82:83], v[82:83], v[86:87]
	v_rcp_f32_e32 v202, v202
	v_pk_mul_f32 v[84:85], v[84:85], v[88:89]
	v_cvt_pk_bf16_f32 v90, v90, v91
	v_exp_f32_e32 v179, v179
	v_cvt_pk_bf16_f32 v91, v92, v93
	v_cvt_pk_bf16_f32 v92, v82, v83
	v_rcp_f32_e32 v203, v203
	v_cvt_pk_bf16_f32 v93, v84, v85
	global_store_dwordx4 v[212:213], v[90:93], off
	v_exp_f32_e32 v180, v180
	v_pk_mul_f32 v[6:7], v[6:7], v[148:149] op_sel:[0,1] op_sel_hi:[1,1]
	v_pk_mul_f32 v[8:9], v[8:9], v[148:149] op_sel:[0,1] op_sel_hi:[1,1]
	v_rcp_f32_e32 v204, v204
	v_pk_mul_f32 v[2:3], v[2:3], v[148:149] op_sel:[0,1] op_sel_hi:[1,1]
	v_pk_mul_f32 v[4:5], v[4:5], v[148:149] op_sel:[0,1] op_sel_hi:[1,1]
	v_exp_f32_e32 v181, v181
	v_pk_mul_f32 v[188:189], v[6:7], s[0:1] op_sel_hi:[1,0]
	v_pk_mul_f32 v[190:191], v[8:9], s[0:1] op_sel_hi:[1,0]
	v_rcp_f32_e32 v205, v205
	v_pk_mul_f32 v[192:193], v[2:3], s[0:1] op_sel_hi:[1,0]
	v_pk_mul_f32 v[194:195], v[4:5], s[0:1] op_sel_hi:[1,0]
	v_exp_f32_e32 v182, v182
	v_pk_mul_f32 v[14:15], v[14:15], v[148:149] op_sel:[0,1] op_sel_hi:[1,1]
	v_pk_mul_f32 v[16:17], v[16:17], v[148:149] op_sel:[0,1] op_sel_hi:[1,1]
	v_rcp_f32_e32 v206, v206
	v_pk_mul_f32 v[10:11], v[10:11], v[148:149] op_sel:[0,1] op_sel_hi:[1,1]
	v_pk_mul_f32 v[12:13], v[12:13], v[148:149] op_sel:[0,1] op_sel_hi:[1,1]
	v_exp_f32_e32 v183, v183
	v_pk_add_f32 v[172:173], v[172:173], 1.0 op_sel_hi:[1,0]
	v_pk_add_f32 v[174:175], v[174:175], 1.0 op_sel_hi:[1,0]
	v_rcp_f32_e32 v207, v207
	v_pk_add_f32 v[176:177], v[176:177], 1.0 op_sel_hi:[1,0]
	v_pk_add_f32 v[178:179], v[178:179], 1.0 op_sel_hi:[1,0]
	v_exp_f32_e32 v184, v184
	v_pk_mul_f32 v[78:79], v[78:79], v[196:197]
	v_pk_mul_f32 v[80:81], v[80:81], v[198:199]
	v_rcp_f32_e32 v208, v208
	v_pk_mul_f32 v[70:71], v[70:71], v[200:201]
	v_pk_mul_f32 v[72:73], v[72:73], v[202:203]
	v_exp_f32_e32 v185, v185
	s_mov_b32 s4, 0x16000
	s_mov_b32 s5, 0
	v_rcp_f32_e32 v209, v209
	v_pk_mul_f32 v[74:75], v[74:75], v[78:79]
	v_pk_mul_f32 v[76:77], v[76:77], v[80:81]
	v_exp_f32_e32 v186, v186
	v_lshl_add_u64 v[214:215], v[212:213], 0, s[4:5]
	v_pk_mul_f32 v[66:67], v[66:67], v[70:71]
	v_rcp_f32_e32 v210, v210
	v_pk_mul_f32 v[68:69], v[68:69], v[72:73]
	v_cvt_pk_bf16_f32 v74, v74, v75
	v_exp_f32_e32 v187, v187
	v_cvt_pk_bf16_f32 v75, v76, v77
	v_cvt_pk_bf16_f32 v76, v66, v67
	v_rcp_f32_e32 v211, v211
	v_cvt_pk_bf16_f32 v77, v68, v69
	global_store_dwordx4 v[214:215], v[74:77], off
	v_exp_f32_e32 v188, v188
	v_pk_add_f32 v[180:181], v[180:181], 1.0 op_sel_hi:[1,0]
	v_pk_add_f32 v[182:183], v[182:183], 1.0 op_sel_hi:[1,0]
	v_rcp_f32_e32 v172, v172
	v_pk_add_f32 v[184:185], v[184:185], 1.0 op_sel_hi:[1,0]
	v_exp_f32_e32 v189, v189
	v_pk_add_f32 v[186:187], v[186:187], 1.0 op_sel_hi:[1,0]
	v_rcp_f32_e32 v173, v173
	v_pk_mul_f32 v[58:59], v[58:59], v[204:205]
	v_exp_f32_e32 v190, v190
	v_pk_mul_f32 v[60:61], v[60:61], v[206:207]
	v_pk_mul_f32 v[50:51], v[50:51], v[208:209]
	v_rcp_f32_e32 v174, v174
	v_pk_mul_f32 v[52:53], v[52:53], v[210:211]
	v_exp_f32_e32 v191, v191
	s_mov_b32 s4, 0x6e000
	v_rcp_f32_e32 v175, v175
	s_mov_b32 s5, 0
	v_exp_f32_e32 v192, v192
	v_pk_mul_f32 v[62:63], v[62:63], v[58:59]
	v_pk_mul_f32 v[64:65], v[64:65], v[60:61]
	v_rcp_f32_e32 v176, v176
	v_lshl_add_u64 v[212:213], v[214:215], 0, s[4:5]
	v_exp_f32_e32 v193, v193
	v_pk_mul_f32 v[54:55], v[54:55], v[50:51]
	v_rcp_f32_e32 v177, v177
	v_pk_mul_f32 v[56:57], v[56:57], v[52:53]
	v_exp_f32_e32 v194, v194
	v_cvt_pk_bf16_f32 v62, v62, v63
	v_cvt_pk_bf16_f32 v63, v64, v65
	v_rcp_f32_e32 v178, v178
	v_cvt_pk_bf16_f32 v64, v54, v55
	v_exp_f32_e32 v195, v195
	v_cvt_pk_bf16_f32 v65, v56, v57
	v_rcp_f32_e32 v179, v179
	global_store_dwordx4 v[212:213], v[62:65], off
	v_rcp_f32_e32 v180, v180
	v_pk_add_f32 v[188:189], v[188:189], 1.0 op_sel_hi:[1,0]
	v_pk_add_f32 v[190:191], v[190:191], 1.0 op_sel_hi:[1,0]
	v_pk_add_f32 v[192:193], v[192:193], 1.0 op_sel_hi:[1,0]
	v_rcp_f32_e32 v181, v181
	v_pk_add_f32 v[194:195], v[194:195], 1.0 op_sel_hi:[1,0]
	v_pk_mul_f32 v[42:43], v[42:43], v[172:173]
	v_rcp_f32_e32 v182, v182
	v_pk_mul_f32 v[44:45], v[44:45], v[174:175]
	v_pk_mul_f32 v[34:35], v[34:35], v[176:177]
	v_pk_mul_f32 v[36:37], v[36:37], v[178:179]
	v_rcp_f32_e32 v183, v183
	s_mov_b32 s4, 0x16000
	s_mov_b32 s5, 0
	v_rcp_f32_e32 v184, v184
	v_pk_mul_f32 v[46:47], v[46:47], v[42:43]
	v_pk_mul_f32 v[48:49], v[48:49], v[44:45]
	v_lshl_add_u64 v[214:215], v[212:213], 0, s[4:5]
	v_rcp_f32_e32 v185, v185
	v_pk_mul_f32 v[38:39], v[38:39], v[34:35]
	v_pk_mul_f32 v[40:41], v[40:41], v[36:37]
	v_rcp_f32_e32 v186, v186
	v_cvt_pk_bf16_f32 v46, v46, v47
	v_cvt_pk_bf16_f32 v47, v48, v49
	v_cvt_pk_bf16_f32 v48, v38, v39
	v_rcp_f32_e32 v187, v187
	v_cvt_pk_bf16_f32 v49, v40, v41
	global_store_dwordx4 v[214:215], v[46:49], off
	v_rcp_f32_e32 v188, v188
	v_pk_mul_f32 v[26:27], v[26:27], v[180:181]
	v_pk_mul_f32 v[28:29], v[28:29], v[182:183]
	v_rcp_f32_e32 v189, v189
	v_pk_mul_f32 v[18:19], v[18:19], v[184:185]
	v_pk_mul_f32 v[20:21], v[20:21], v[186:187]
	v_rcp_f32_e32 v190, v190
	s_mov_b32 s4, 0x16000
	s_mov_b32 s5, 0
	v_rcp_f32_e32 v191, v191
	v_pk_mul_f32 v[30:31], v[30:31], v[26:27]
	v_pk_mul_f32 v[32:33], v[32:33], v[28:29]
	v_rcp_f32_e32 v192, v192
	v_lshl_add_u64 v[212:213], v[214:215], 0, s[4:5]
	v_pk_mul_f32 v[22:23], v[22:23], v[18:19]
	v_rcp_f32_e32 v193, v193
	v_pk_mul_f32 v[24:25], v[24:25], v[20:21]
	v_cvt_pk_bf16_f32 v30, v30, v31
	v_rcp_f32_e32 v194, v194
	v_cvt_pk_bf16_f32 v31, v32, v33
	v_cvt_pk_bf16_f32 v32, v22, v23
	v_rcp_f32_e32 v195, v195
	v_cvt_pk_bf16_f32 v33, v24, v25
	global_store_dwordx4 v[212:213], v[30:33], off
	v_pk_mul_f32 v[6:7], v[6:7], v[188:189]
	v_pk_mul_f32 v[8:9], v[8:9], v[190:191]
	v_pk_mul_f32 v[2:3], v[2:3], v[192:193]
	v_pk_mul_f32 v[4:5], v[4:5], v[194:195]
	s_mov_b32 s4, 0x16000
	s_mov_b32 s5, 0
	v_pk_mul_f32 v[14:15], v[14:15], v[6:7]
	v_pk_mul_f32 v[16:17], v[16:17], v[8:9]
	v_lshl_add_u64 v[214:215], v[212:213], 0, s[4:5]
	v_pk_mul_f32 v[10:11], v[10:11], v[2:3]
	v_pk_mul_f32 v[12:13], v[12:13], v[4:5]
	v_cvt_pk_bf16_f32 v14, v14, v15
	v_cvt_pk_bf16_f32 v15, v16, v17
	v_cvt_pk_bf16_f32 v16, v10, v11
	v_cvt_pk_bf16_f32 v17, v12, v13
	global_store_dwordx4 v[214:215], v[14:17], off
	v_mov_b64_e32 v[2:3], v[146:147]
	s_mov_b64 s[4:5], s[22:23]
	s_and_b64 vcc, exec, s[38:39]
	s_cbranch_vccz .LBB0_815
	s_waitcnt vmcnt(0)
	s_cmpk_gt_u32 s2, 0xff
	v_readlane_b32 s89, v253, 39
	s_cbranch_scc1 .LBB0_14
	s_barrier
	s_branch .LBB0_14
